# GEMM K-loops: one LDS-DMA load of each 6-load SP2 segment deferred to the following SP1 segment (balances load segments; vmcnt 8->7)
# speedup vs baseline: 1.0156x; 1.0013x over previous
; #define PG8_STAGE(bufoff, gbase, voff) do { _Pragma("unroll") for (int _i = 0; _i < 2; ++_i) \
;         __builtin_amdgcn_global_load_lds((const unsigned*)((const char*)(gbase) + (voff)[_i]), (PG8_LAS unsigned*)(lds + (bufoff) + ldsw + _i * 8192), 16, 0, 0); } while (0)
; #define PG8_LDA(dst, b, h) do { _Pragma("unroll") for (int m = 0; m < 4; ++m) _Pragma("unroll") for (int k = 0; k < 2; ++k) dst[m][k] = *(const PG8_LAS bf16x8*)(lds + PG8_SA(b, h) + aoff + m * 2048 + k * 1024); } while (0)
; #define PG8_LDB(dst, b, h) do { _Pragma("unroll") for (int n = 0; n < 2; ++n) _Pragma("unroll") for (int k = 0; k < 2; ++k) dst[n][k] = *(const PG8_LAS bf16x8*)(lds + PG8_SB(b, h) + boff + n * 2048 + k * 1024); } while (0)
; #define PG8_WAIT_V(n) asm volatile("s_waitcnt vmcnt(" #n ")" ::: "memory")
; #define PG8_WAIT_L(n) asm volatile("s_waitcnt lgkmcnt(" #n ")" ::: "memory")
; #define PG8_BAR __builtin_amdgcn_s_barrier()
; #define PG8_SCHED __builtin_amdgcn_sched_barrier(0)
; #define PG8_MMA2(ai) PG8_MMA(ai, 0, At, B0)
;     ...
;         for (int t = 0; t < nt; t += 2) {
;             const bool last = (t == nt - 2);
;             const char* a1 = cA + (size_t)(t + 1) * kstep;
;             const char* a2 = last ? nA : cA + (size_t)(t + 2) * kstep; const char* b2 = last ? nB : cB + (size_t)(t + 2) * kstep;
;             const char* a3 = a2 + kstep; const char* b3 = b2 + kstep;
;             if (last && has_next) S.a_ready(nxt);
;             if constexpr (SP2) {
;             PG8_LDB(B0, 0, 0); PG8_LDB(B1, 0, 1); PG8_SCHED; PG8_LDA(At, 0, 0); PG8_STAGE(PG8_SA(1, 1), a1 + hstep, voffA);
;             PG8_WAIT_V(8); PG8_WAIT_L(0); PG8_BAR; PG8_MMA2(0); PG8_BAR; PG8_SCHED;
;             PG8_LDA(At, 0, 1); PG8_STAGE(PG8_SB(0, 0), b2, voffB); PG8_STAGE(PG8_SB(0, 1), b2 + hstep, voffB); PG8_STAGE(PG8_SA(0, 0), a2, voffA);
;             PG8_WAIT_V(8); PG8_WAIT_L(0); PG8_BAR; PG8_MMA2(1); PG8_BAR; PG8_SCHED;
;             PG8_LDB(B0, 1, 0); PG8_LDB(B1, 1, 1); PG8_SCHED; PG8_LDA(At, 1, 0); PG8_STAGE(PG8_SA(0, 1), a2 + hstep, voffA);
;             PG8_WAIT_V(8); PG8_WAIT_L(0); PG8_BAR; PG8_MMA2(0); PG8_BAR; PG8_SCHED;
;             PG8_LDA(At, 1, 1); PG8_STAGE(PG8_SB(1, 0), b3, voffB); PG8_STAGE(PG8_SB(1, 1), b3 + hstep, voffB); PG8_STAGE(PG8_SA(1, 0), a3, voffA);
;             PG8_WAIT_V(8); PG8_WAIT_L(0); PG8_BAR; PG8_MMA2(1); PG8_BAR; PG8_SCHED;
.LBB0_232:
	s_cmp_eq_u32 s62, -2
	s_cbranch_scc1 .Ldf_skipA_0
	s_mov_b32 m0, s51
	s_nop 0
	global_load_lds_dwordx4 v[144:145], off
.Ldf_skipA_0:
	ds_read_b128 v[152:155], v149
	ds_read_b128 v[156:159], v149 offset:1024
	ds_read_b128 v[160:163], v149 offset:2048
	ds_read_b128 v[164:167], v149 offset:3072
	ds_read_b128 v[168:171], v150
	ds_read_b128 v[172:175], v150 offset:1024
	ds_read_b128 v[176:179], v150 offset:2048
	ds_read_b128 v[180:183], v150 offset:3072
	s_add_u32 s16, s36, 0xfffc0080
	s_addc_u32 s17, s37, -1
	s_cmp_eq_u32 s62, 12
	s_cselect_b32 s41, s19, s17
	s_cselect_b32 s40, s58, s16
	s_cselect_b32 s39, s15, s61
	s_cselect_b32 s38, s59, s60
	v_lshl_add_u64 v[144:145], s[36:37], 0, v[138:139]
	s_add_i32 m0, s27, 0xc000
	ds_read_b128 v[184:187], v151
	ds_read_b128 v[188:191], v151 offset:1024
	ds_read_b128 v[192:195], v151 offset:2048
	ds_read_b128 v[196:199], v151 offset:3072
	ds_read_b128 v[200:203], v151 offset:4096
	ds_read_b128 v[208:211], v151 offset:5120
	ds_read_b128 v[214:217], v151 offset:6144
	ds_read_b128 v[218:221], v151 offset:7168
	global_load_lds_dwordx4 v[144:145], off
	v_lshl_add_u64 v[144:145], s[36:37], 0, v[136:137]
	s_add_i32 m0, s27, 0xe000
	s_nop 0
	global_load_lds_dwordx4 v[144:145], off
	s_waitcnt vmcnt(8)
	s_waitcnt lgkmcnt(0)
	s_barrier
	s_setprio 1
	s_waitcnt lgkmcnt(0)
	v_mfma_f32_16x16x32_bf16 v[124:127], v[152:155], v[184:187], v[124:127]
	v_mfma_f32_16x16x32_bf16 v[120:123], v[160:163], v[184:187], v[120:123]
	v_mfma_f32_16x16x32_bf16 v[108:111], v[152:155], v[192:195], v[108:111]
	v_mfma_f32_16x16x32_bf16 v[104:107], v[160:163], v[192:195], v[104:107]
	v_mfma_f32_16x16x32_bf16 v[92:95], v[152:155], v[200:203], v[92:95]
	v_mfma_f32_16x16x32_bf16 v[88:91], v[160:163], v[200:203], v[88:91]
	v_mfma_f32_16x16x32_bf16 v[76:79], v[152:155], v[214:217], v[76:79]
	v_mfma_f32_16x16x32_bf16 v[72:75], v[160:163], v[214:217], v[72:75]
	v_mfma_f32_16x16x32_bf16 v[124:127], v[156:159], v[188:191], v[124:127]
	v_mfma_f32_16x16x32_bf16 v[120:123], v[164:167], v[188:191], v[120:123]
	v_mfma_f32_16x16x32_bf16 v[108:111], v[156:159], v[196:199], v[108:111]
	v_mfma_f32_16x16x32_bf16 v[104:107], v[164:167], v[196:199], v[104:107]
	v_mfma_f32_16x16x32_bf16 v[92:95], v[156:159], v[208:211], v[92:95]
	v_mfma_f32_16x16x32_bf16 v[88:91], v[164:167], v[208:211], v[88:91]
	v_mfma_f32_16x16x32_bf16 v[76:79], v[156:159], v[218:221], v[76:79]
	v_mfma_f32_16x16x32_bf16 v[72:75], v[164:167], v[218:221], v[72:75]
	s_setprio 0
	s_setprio 1
	v_mfma_f32_16x16x32_bf16 v[116:119], v[168:171], v[184:187], v[116:119]
	v_mfma_f32_16x16x32_bf16 v[112:115], v[176:179], v[184:187], v[112:115]
	v_mfma_f32_16x16x32_bf16 v[100:103], v[168:171], v[192:195], v[100:103]
	v_mfma_f32_16x16x32_bf16 v[96:99], v[176:179], v[192:195], v[96:99]
	v_mfma_f32_16x16x32_bf16 v[84:87], v[168:171], v[200:203], v[84:87]
	v_mfma_f32_16x16x32_bf16 v[80:83], v[176:179], v[200:203], v[80:83]
	v_mfma_f32_16x16x32_bf16 v[68:71], v[168:171], v[214:217], v[68:71]
	v_mfma_f32_16x16x32_bf16 v[64:67], v[176:179], v[214:217], v[64:67]
	v_mfma_f32_16x16x32_bf16 v[116:119], v[172:175], v[188:191], v[116:119]
	v_mfma_f32_16x16x32_bf16 v[112:115], v[180:183], v[188:191], v[112:115]
	v_mfma_f32_16x16x32_bf16 v[100:103], v[172:175], v[196:199], v[100:103]
	v_mfma_f32_16x16x32_bf16 v[96:99], v[180:183], v[196:199], v[96:99]
	v_mfma_f32_16x16x32_bf16 v[84:87], v[172:175], v[208:211], v[84:87]
	v_mfma_f32_16x16x32_bf16 v[80:83], v[180:183], v[208:211], v[80:83]
	v_mfma_f32_16x16x32_bf16 v[68:71], v[172:175], v[218:221], v[68:71]
	v_mfma_f32_16x16x32_bf16 v[64:67], v[180:183], v[218:221], v[64:67]
	s_setprio 0
	s_barrier
	s_add_i32 s16, s54, s45
	v_lshl_add_u64 v[144:145], s[38:39], 0, v[130:131]
	s_mov_b32 m0, s16
	ds_read_b128 v[184:187], v151 offset:16384
	ds_read_b128 v[188:191], v151 offset:17408
	ds_read_b128 v[192:195], v151 offset:18432
	ds_read_b128 v[196:199], v151 offset:19456
	ds_read_b128 v[200:203], v151 offset:20480
	ds_read_b128 v[208:211], v151 offset:21504
	ds_read_b128 v[214:217], v151 offset:22528
	ds_read_b128 v[218:221], v151 offset:23552
	global_load_lds_dwordx4 v[144:145], off
	s_add_i32 m0, s16, 0x2000
	s_add_u32 s34, s38, 0x40000
	v_lshl_add_u64 v[204:205], s[38:39], 0, v[134:135]
	s_addc_u32 s35, s39, 0
	s_add_i32 s16, s55, s45
	global_load_lds_dwordx4 v[204:205], off
	v_lshl_add_u64 v[222:223], s[34:35], 0, v[130:131]
	s_mov_b32 m0, s16
	v_lshl_add_u64 v[224:225], s[40:41], 0, v[132:133]
	global_load_lds_dwordx4 v[222:223], off
	v_lshl_add_u64 v[222:223], s[34:35], 0, v[134:135]
	s_add_i32 m0, s16, 0x2000
	s_nop 0
	global_load_lds_dwordx4 v[222:223], off
	v_lshl_add_u64 v[222:223], s[40:41], 0, v[128:129]
	s_mov_b32 m0, s27
	s_nop 0
	global_load_lds_dwordx4 v[222:223], off
	s_nop 0
	s_waitcnt vmcnt(7)
	s_waitcnt lgkmcnt(0)
	s_barrier
; #define PG8_STAGE(bufoff, gbase, voff) do { _Pragma("unroll") for (int _i = 0; _i < 2; ++_i) \
;         __builtin_amdgcn_global_load_lds((const unsigned*)((const char*)(gbase) + (voff)[_i]), (PG8_LAS unsigned*)(lds + (bufoff) + ldsw + _i * 8192), 16, 0, 0); } while (0)
; #define PG8_LDA(dst, b, h) do { _Pragma("unroll") for (int m = 0; m < 4; ++m) _Pragma("unroll") for (int k = 0; k < 2; ++k) dst[m][k] = *(const PG8_LAS bf16x8*)(lds + PG8_SA(b, h) + aoff + m * 2048 + k * 1024); } while (0)
; #define PG8_LDB(dst, b, h) do { _Pragma("unroll") for (int n = 0; n < 2; ++n) _Pragma("unroll") for (int k = 0; k < 2; ++k) dst[n][k] = *(const PG8_LAS bf16x8*)(lds + PG8_SB(b, h) + boff + n * 2048 + k * 1024); } while (0)
; #define PG8_WAIT_V(n) asm volatile("s_waitcnt vmcnt(" #n ")" ::: "memory")
; #define PG8_WAIT_L(n) asm volatile("s_waitcnt lgkmcnt(" #n ")" ::: "memory")
; #define PG8_BAR __builtin_amdgcn_s_barrier()
; #define PG8_SCHED __builtin_amdgcn_sched_barrier(0)
; #define PG8_MMA2(ai) PG8_MMA(ai, 0, At, B0)
; #define PG8_MMA2(ai) PG8_MMA(ai, 1, At, B1)
; #define PG8_MMA2(ai) do { PG8_MMA(ai, 0, At, B0); PG8_MMA(ai, 1, At, B1); } while (0)
;     ...
;             PG8_WAIT_V(8); PG8_WAIT_L(0); PG8_BAR; PG8_MMA2(1); PG8_BAR; PG8_SCHED;
;             PG8_LDB(B0, 1, 0); PG8_LDB(B1, 1, 1); PG8_SCHED; PG8_LDA(At, 1, 0); PG8_STAGE(PG8_SA(0, 1), a2 + hstep, voffA);
;             PG8_WAIT_V(8); PG8_WAIT_L(0); PG8_BAR; PG8_MMA2(0); PG8_BAR; PG8_SCHED;
	s_setprio 1
	s_waitcnt lgkmcnt(0)
	v_mfma_f32_16x16x32_bf16 v[60:63], v[152:155], v[184:187], v[60:63]
	v_mfma_f32_16x16x32_bf16 v[56:59], v[160:163], v[184:187], v[56:59]
	v_mfma_f32_16x16x32_bf16 v[44:47], v[152:155], v[192:195], v[44:47]
	v_mfma_f32_16x16x32_bf16 v[40:43], v[160:163], v[192:195], v[40:43]
	v_mfma_f32_16x16x32_bf16 v[28:31], v[152:155], v[200:203], v[28:31]
	v_mfma_f32_16x16x32_bf16 v[24:27], v[160:163], v[200:203], v[24:27]
	v_mfma_f32_16x16x32_bf16 v[12:15], v[152:155], v[214:217], v[12:15]
	v_mfma_f32_16x16x32_bf16 v[8:11], v[160:163], v[214:217], v[8:11]
	v_mfma_f32_16x16x32_bf16 v[60:63], v[156:159], v[188:191], v[60:63]
	v_mfma_f32_16x16x32_bf16 v[56:59], v[164:167], v[188:191], v[56:59]
	v_mfma_f32_16x16x32_bf16 v[44:47], v[156:159], v[196:199], v[44:47]
	v_mfma_f32_16x16x32_bf16 v[40:43], v[164:167], v[196:199], v[40:43]
	v_mfma_f32_16x16x32_bf16 v[28:31], v[156:159], v[208:211], v[28:31]
	v_mfma_f32_16x16x32_bf16 v[24:27], v[164:167], v[208:211], v[24:27]
	v_mfma_f32_16x16x32_bf16 v[12:15], v[156:159], v[218:221], v[12:15]
	v_mfma_f32_16x16x32_bf16 v[8:11], v[164:167], v[218:221], v[8:11]
	s_setprio 0
	s_setprio 1
	v_mfma_f32_16x16x32_bf16 v[52:55], v[168:171], v[184:187], v[52:55]
	v_mfma_f32_16x16x32_bf16 v[48:51], v[176:179], v[184:187], v[48:51]
	v_mfma_f32_16x16x32_bf16 v[36:39], v[168:171], v[192:195], v[36:39]
	v_mfma_f32_16x16x32_bf16 v[32:35], v[176:179], v[192:195], v[32:35]
	v_mfma_f32_16x16x32_bf16 v[20:23], v[168:171], v[200:203], v[20:23]
	v_mfma_f32_16x16x32_bf16 v[16:19], v[176:179], v[200:203], v[16:19]
	v_mfma_f32_16x16x32_bf16 v[4:7], v[168:171], v[214:217], v[4:7]
	v_mfma_f32_16x16x32_bf16 v[0:3], v[176:179], v[214:217], v[0:3]
	v_mfma_f32_16x16x32_bf16 v[52:55], v[172:175], v[188:191], v[52:55]
	v_mfma_f32_16x16x32_bf16 v[48:51], v[180:183], v[188:191], v[48:51]
	v_mfma_f32_16x16x32_bf16 v[36:39], v[172:175], v[196:199], v[36:39]
	v_mfma_f32_16x16x32_bf16 v[32:35], v[180:183], v[196:199], v[32:35]
	v_mfma_f32_16x16x32_bf16 v[20:23], v[172:175], v[208:211], v[20:23]
	v_mfma_f32_16x16x32_bf16 v[16:19], v[180:183], v[208:211], v[16:19]
	v_mfma_f32_16x16x32_bf16 v[4:7], v[172:175], v[218:221], v[4:7]
	v_mfma_f32_16x16x32_bf16 v[0:3], v[180:183], v[218:221], v[0:3]
	s_setprio 0
	s_barrier
	s_add_i32 s16, 0, 0x18000
	s_add_i32 s17, 0, 0x1c000
	v_add_u32_e32 v164, s16, v147
	v_add_u32_e32 v180, s17, v147
	ds_read_b128 v[152:155], v164
	ds_read_b128 v[156:159], v164 offset:1024
	ds_read_b128 v[160:163], v164 offset:2048
	ds_read_b128 v[164:167], v164 offset:3072
	ds_read_b128 v[168:171], v180
	ds_read_b128 v[172:175], v180 offset:1024
	ds_read_b128 v[176:179], v180 offset:2048
	ds_read_b128 v[180:183], v180 offset:3072
	s_add_u32 s34, s40, 0x40000
	s_addc_u32 s35, s41, 0
	s_mov_b32 m0, s46
	s_nop 0
	global_load_lds_dwordx4 v[224:225], off
	s_mov_b32 m0, s47
	v_lshl_add_u64 v[226:227], s[34:35], 0, v[128:129]
	ds_read_b128 v[184:187], v151 offset:32768
	ds_read_b128 v[188:191], v151 offset:33792
	ds_read_b128 v[192:195], v151 offset:34816
	ds_read_b128 v[196:199], v151 offset:35840
	ds_read_b128 v[200:203], v151 offset:36864
	ds_read_b128 v[208:211], v151 offset:37888
	ds_read_b128 v[214:217], v151 offset:38912
	ds_read_b128 v[218:221], v151 offset:39936
	global_load_lds_dwordx4 v[226:227], off
	v_lshl_add_u64 v[226:227], s[34:35], 0, v[132:133]
	s_mov_b32 m0, s48
	s_nop 0
	global_load_lds_dwordx4 v[226:227], off
	s_waitcnt vmcnt(8)
	s_waitcnt lgkmcnt(0)
	s_barrier
	s_setprio 1
	s_waitcnt lgkmcnt(0)
	v_mfma_f32_16x16x32_bf16 v[124:127], v[152:155], v[184:187], v[124:127]
	v_mfma_f32_16x16x32_bf16 v[120:123], v[160:163], v[184:187], v[120:123]
	v_mfma_f32_16x16x32_bf16 v[108:111], v[152:155], v[192:195], v[108:111]
	v_mfma_f32_16x16x32_bf16 v[104:107], v[160:163], v[192:195], v[104:107]
	v_mfma_f32_16x16x32_bf16 v[92:95], v[152:155], v[200:203], v[92:95]
	v_mfma_f32_16x16x32_bf16 v[88:91], v[160:163], v[200:203], v[88:91]
	v_mfma_f32_16x16x32_bf16 v[76:79], v[152:155], v[214:217], v[76:79]
	v_mfma_f32_16x16x32_bf16 v[72:75], v[160:163], v[214:217], v[72:75]
	v_mfma_f32_16x16x32_bf16 v[124:127], v[156:159], v[188:191], v[124:127]
	v_mfma_f32_16x16x32_bf16 v[120:123], v[164:167], v[188:191], v[120:123]
	v_mfma_f32_16x16x32_bf16 v[108:111], v[156:159], v[196:199], v[108:111]
	v_mfma_f32_16x16x32_bf16 v[104:107], v[164:167], v[196:199], v[104:107]
	v_mfma_f32_16x16x32_bf16 v[92:95], v[156:159], v[208:211], v[92:95]
	v_mfma_f32_16x16x32_bf16 v[88:91], v[164:167], v[208:211], v[88:91]
	v_mfma_f32_16x16x32_bf16 v[76:79], v[156:159], v[218:221], v[76:79]
	v_mfma_f32_16x16x32_bf16 v[72:75], v[164:167], v[218:221], v[72:75]
	s_setprio 0
	s_setprio 1
	v_mfma_f32_16x16x32_bf16 v[116:119], v[168:171], v[184:187], v[116:119]
	v_mfma_f32_16x16x32_bf16 v[112:115], v[176:179], v[184:187], v[112:115]
	v_mfma_f32_16x16x32_bf16 v[100:103], v[168:171], v[192:195], v[100:103]
	v_mfma_f32_16x16x32_bf16 v[96:99], v[176:179], v[192:195], v[96:99]
	v_mfma_f32_16x16x32_bf16 v[84:87], v[168:171], v[200:203], v[84:87]
	v_mfma_f32_16x16x32_bf16 v[80:83], v[176:179], v[200:203], v[80:83]
	v_mfma_f32_16x16x32_bf16 v[68:71], v[168:171], v[214:217], v[68:71]
	v_mfma_f32_16x16x32_bf16 v[64:67], v[176:179], v[214:217], v[64:67]
	v_mfma_f32_16x16x32_bf16 v[116:119], v[172:175], v[188:191], v[116:119]
	v_mfma_f32_16x16x32_bf16 v[112:115], v[180:183], v[188:191], v[112:115]
	v_mfma_f32_16x16x32_bf16 v[100:103], v[172:175], v[196:199], v[100:103]
	v_mfma_f32_16x16x32_bf16 v[96:99], v[180:183], v[196:199], v[96:99]
	v_mfma_f32_16x16x32_bf16 v[84:87], v[172:175], v[208:211], v[84:87]
	v_mfma_f32_16x16x32_bf16 v[80:83], v[180:183], v[208:211], v[80:83]
	v_mfma_f32_16x16x32_bf16 v[68:71], v[172:175], v[218:221], v[68:71]
	v_mfma_f32_16x16x32_bf16 v[64:67], v[180:183], v[218:221], v[64:67]
	s_setprio 0
	s_barrier
; #define PG8_STAGE(bufoff, gbase, voff) do { _Pragma("unroll") for (int _i = 0; _i < 2; ++_i) \
;         __builtin_amdgcn_global_load_lds((const unsigned*)((const char*)(gbase) + (voff)[_i]), (PG8_LAS unsigned*)(lds + (bufoff) + ldsw + _i * 8192), 16, 0, 0); } while (0)
; #define PG8_LDA(dst, b, h) do { _Pragma("unroll") for (int m = 0; m < 4; ++m) _Pragma("unroll") for (int k = 0; k < 2; ++k) dst[m][k] = *(const PG8_LAS bf16x8*)(lds + PG8_SA(b, h) + aoff + m * 2048 + k * 1024); } while (0)
; #define PG8_WAIT_V(n) asm volatile("s_waitcnt vmcnt(" #n ")" ::: "memory")
; #define PG8_WAIT_L(n) asm volatile("s_waitcnt lgkmcnt(" #n ")" ::: "memory")
; #define PG8_BAR __builtin_amdgcn_s_barrier()
; #define PG8_SCHED __builtin_amdgcn_sched_barrier(0)
; #define PG8_MMA2(ai) PG8_MMA(ai, 0, At, B0)
; #define PG8_MMA2(ai) PG8_MMA(ai, 1, At, B1)
; #define PG8_MMA2(ai) do { PG8_MMA(ai, 0, At, B0); PG8_MMA(ai, 1, At, B1); } while (0)
;     ...
;         for (int t = 0; t < nt; t += 2) {
;             const bool last = (t == nt - 2);
;     ...
;             PG8_LDA(At, 1, 1); PG8_STAGE(PG8_SB(1, 0), b3, voffB); PG8_STAGE(PG8_SB(1, 1), b3 + hstep, voffB); PG8_STAGE(PG8_SA(1, 0), a3, voffA);
;             PG8_WAIT_V(8); PG8_WAIT_L(0); PG8_BAR; PG8_MMA2(1); PG8_BAR; PG8_SCHED;
	s_add_i32 s16, s16, s45
	v_lshl_add_u64 v[144:145], v[144:145], 0, s[10:11]
	s_mov_b32 m0, s16
	ds_read_b128 v[184:187], v151 offset:49152
	ds_read_b128 v[188:191], v151 offset:50176
	ds_read_b128 v[192:195], v151 offset:51200
	ds_read_b128 v[196:199], v151 offset:52224
	ds_read_b128 v[200:203], v151 offset:53248
	ds_read_b128 v[208:211], v151 offset:54272
	ds_read_b128 v[214:217], v151 offset:55296
	ds_read_b128 v[218:221], v151 offset:56320
	global_load_lds_dwordx4 v[144:145], off
	s_add_i32 m0, s16, 0x2000
	s_add_u32 s34, s38, 0x40080
	v_lshl_add_u64 v[144:145], v[204:205], 0, s[10:11]
	s_addc_u32 s35, s39, 0
	s_add_i32 s16, s17, s45
	global_load_lds_dwordx4 v[144:145], off
	v_lshl_add_u64 v[144:145], s[34:35], 0, v[130:131]
	s_mov_b32 m0, s16
	s_nop 0
	global_load_lds_dwordx4 v[144:145], off
	v_lshl_add_u64 v[144:145], s[34:35], 0, v[134:135]
	s_add_i32 m0, s16, 0x2000
	s_nop 0
	global_load_lds_dwordx4 v[144:145], off
	v_lshl_add_u64 v[144:145], v[222:223], 0, s[10:11]
	s_mov_b32 m0, s50
	s_nop 0
	global_load_lds_dwordx4 v[144:145], off
	v_lshl_add_u64 v[144:145], v[224:225], 0, s[10:11]
	s_nop 0
	s_cmp_lg_u32 s62, 12
	s_cbranch_scc1 .Ldf_skipD_0
	s_mov_b32 m0, s51
	s_nop 0
	global_load_lds_dwordx4 v[144:145], off
.Ldf_skipD_0:
	s_waitcnt vmcnt(7)
	s_waitcnt lgkmcnt(0)
	s_barrier
	s_setprio 1
	s_waitcnt lgkmcnt(0)
	v_mfma_f32_16x16x32_bf16 v[60:63], v[152:155], v[184:187], v[60:63]
	v_mfma_f32_16x16x32_bf16 v[56:59], v[160:163], v[184:187], v[56:59]
	v_mfma_f32_16x16x32_bf16 v[44:47], v[152:155], v[192:195], v[44:47]
	v_mfma_f32_16x16x32_bf16 v[40:43], v[160:163], v[192:195], v[40:43]
	v_mfma_f32_16x16x32_bf16 v[28:31], v[152:155], v[200:203], v[28:31]
	v_mfma_f32_16x16x32_bf16 v[24:27], v[160:163], v[200:203], v[24:27]
	v_mfma_f32_16x16x32_bf16 v[12:15], v[152:155], v[214:217], v[12:15]
	v_mfma_f32_16x16x32_bf16 v[8:11], v[160:163], v[214:217], v[8:11]
	v_mfma_f32_16x16x32_bf16 v[60:63], v[156:159], v[188:191], v[60:63]
	v_mfma_f32_16x16x32_bf16 v[56:59], v[164:167], v[188:191], v[56:59]
	v_mfma_f32_16x16x32_bf16 v[44:47], v[156:159], v[196:199], v[44:47]
	v_mfma_f32_16x16x32_bf16 v[40:43], v[164:167], v[196:199], v[40:43]
	v_mfma_f32_16x16x32_bf16 v[28:31], v[156:159], v[208:211], v[28:31]
	v_mfma_f32_16x16x32_bf16 v[24:27], v[164:167], v[208:211], v[24:27]
	v_mfma_f32_16x16x32_bf16 v[12:15], v[156:159], v[218:221], v[12:15]
	v_mfma_f32_16x16x32_bf16 v[8:11], v[164:167], v[218:221], v[8:11]
	s_setprio 0
	s_setprio 1
	v_mfma_f32_16x16x32_bf16 v[52:55], v[168:171], v[184:187], v[52:55]
	v_mfma_f32_16x16x32_bf16 v[48:51], v[176:179], v[184:187], v[48:51]
	v_mfma_f32_16x16x32_bf16 v[36:39], v[168:171], v[192:195], v[36:39]
	v_mfma_f32_16x16x32_bf16 v[32:35], v[176:179], v[192:195], v[32:35]
	v_mfma_f32_16x16x32_bf16 v[20:23], v[168:171], v[200:203], v[20:23]
	v_mfma_f32_16x16x32_bf16 v[16:19], v[176:179], v[200:203], v[16:19]
	v_mfma_f32_16x16x32_bf16 v[4:7], v[168:171], v[214:217], v[4:7]
	v_mfma_f32_16x16x32_bf16 v[0:3], v[176:179], v[214:217], v[0:3]
	v_mfma_f32_16x16x32_bf16 v[52:55], v[172:175], v[188:191], v[52:55]
	v_mfma_f32_16x16x32_bf16 v[48:51], v[180:183], v[188:191], v[48:51]
	v_mfma_f32_16x16x32_bf16 v[36:39], v[172:175], v[196:199], v[36:39]
	v_mfma_f32_16x16x32_bf16 v[32:35], v[180:183], v[196:199], v[32:35]
	v_mfma_f32_16x16x32_bf16 v[20:23], v[172:175], v[208:211], v[20:23]
	v_mfma_f32_16x16x32_bf16 v[16:19], v[180:183], v[208:211], v[16:19]
	v_mfma_f32_16x16x32_bf16 v[4:7], v[172:175], v[218:221], v[4:7]
	v_mfma_f32_16x16x32_bf16 v[0:3], v[180:183], v[218:221], v[0:3]
	s_setprio 0
	s_barrier
	s_add_i32 s62, s62, 2
	s_add_u32 s60, s60, 0x100
	s_addc_u32 s61, s61, 0
	s_add_u32 s36, s36, 0x100
	s_addc_u32 s37, s37, 0
	s_cmp_gt_u32 s62, 13
	s_cbranch_scc0 .LBB0_232
	s_and_b64 vcc, exec, s[12:13]
	s_cbranch_vccz .LBB0_235
	s_barrier

; #define PG8_STAGE(bufoff, gbase, voff) do { _Pragma("unroll") for (int _i = 0; _i < 2; ++_i) \
;         __builtin_amdgcn_global_load_lds((const unsigned*)((const char*)(gbase) + (voff)[_i]), (PG8_LAS unsigned*)(lds + (bufoff) + ldsw + _i * 8192), 16, 0, 0); } while (0)
; #define PG8_LDA(dst, b, h) do { _Pragma("unroll") for (int m = 0; m < 4; ++m) _Pragma("unroll") for (int k = 0; k < 2; ++k) dst[m][k] = *(const PG8_LAS bf16x8*)(lds + PG8_SA(b, h) + aoff + m * 2048 + k * 1024); } while (0)
; #define PG8_LDB(dst, b, h) do { _Pragma("unroll") for (int n = 0; n < 2; ++n) _Pragma("unroll") for (int k = 0; k < 2; ++k) dst[n][k] = *(const PG8_LAS bf16x8*)(lds + PG8_SB(b, h) + boff + n * 2048 + k * 1024); } while (0)
; #define PG8_WAIT_V(n) asm volatile("s_waitcnt vmcnt(" #n ")" ::: "memory")
; #define PG8_WAIT_L(n) asm volatile("s_waitcnt lgkmcnt(" #n ")" ::: "memory")
; #define PG8_BAR __builtin_amdgcn_s_barrier()
; #define PG8_SCHED __builtin_amdgcn_sched_barrier(0)
; #define PG8_MMA2(ai) PG8_MMA(ai, 0, At, B0)
;     ...
;         for (int t = 0; t < nt; t += 2) {
;             const bool last = (t == nt - 2);
;             const char* a1 = cA + (size_t)(t + 1) * kstep;
;             const char* a2 = last ? nA : cA + (size_t)(t + 2) * kstep; const char* b2 = last ? nB : cB + (size_t)(t + 2) * kstep;
;             const char* a3 = a2 + kstep; const char* b3 = b2 + kstep;
;             if (last && has_next) S.a_ready(nxt);
;             if constexpr (SP2) {
;             PG8_LDB(B0, 0, 0); PG8_LDB(B1, 0, 1); PG8_SCHED; PG8_LDA(At, 0, 0); PG8_STAGE(PG8_SA(1, 1), a1 + hstep, voffA);
;             PG8_WAIT_V(8); PG8_WAIT_L(0); PG8_BAR; PG8_MMA2(0); PG8_BAR; PG8_SCHED;
;             PG8_LDA(At, 0, 1); PG8_STAGE(PG8_SB(0, 0), b2, voffB); PG8_STAGE(PG8_SB(0, 1), b2 + hstep, voffB); PG8_STAGE(PG8_SA(0, 0), a2, voffA);
;             PG8_WAIT_V(8); PG8_WAIT_L(0); PG8_BAR; PG8_MMA2(1); PG8_BAR; PG8_SCHED;
;             PG8_LDB(B0, 1, 0); PG8_LDB(B1, 1, 1); PG8_SCHED; PG8_LDA(At, 1, 0); PG8_STAGE(PG8_SA(0, 1), a2 + hstep, voffA);
;             PG8_WAIT_V(8); PG8_WAIT_L(0); PG8_BAR; PG8_MMA2(0); PG8_BAR; PG8_SCHED;
;             PG8_LDA(At, 1, 1); PG8_STAGE(PG8_SB(1, 0), b3, voffB); PG8_STAGE(PG8_SB(1, 1), b3 + hstep, voffB); PG8_STAGE(PG8_SA(1, 0), a3, voffA);
;             PG8_WAIT_V(8); PG8_WAIT_L(0); PG8_BAR; PG8_MMA2(1); PG8_BAR; PG8_SCHED;
.LBB0_312:
	s_cmp_eq_u32 s69, -2
	s_cbranch_scc1 .Ldf_skipA_1
	s_mov_b32 m0, s56
	s_nop 0
	global_load_lds_dwordx4 v[144:145], off
.Ldf_skipA_1:
	ds_read_b128 v[140:143], v149
	ds_read_b128 v[152:155], v149 offset:1024
	ds_read_b128 v[156:159], v149 offset:2048
	ds_read_b128 v[160:163], v149 offset:3072
	ds_read_b128 v[164:167], v150
	ds_read_b128 v[168:171], v150 offset:1024
	ds_read_b128 v[172:175], v150 offset:2048
	ds_read_b128 v[176:179], v150 offset:3072
	s_add_u32 s36, s26, 0x100
	s_addc_u32 s37, s27, 0
	s_cmp_eq_u32 s69, 40
	s_cselect_b32 s41, s7, s37
	s_cselect_b32 s40, s6, s36
	s_cselect_b32 s39, s23, s68
	s_cselect_b32 s38, s22, s67
	v_lshl_add_u64 v[144:145], s[26:27], 0, v[134:135]
	s_add_i32 m0, s46, 0xc000
	ds_read_b128 v[180:183], v151
	ds_read_b128 v[184:187], v151 offset:1024
	ds_read_b128 v[188:191], v151 offset:2048
	ds_read_b128 v[192:195], v151 offset:3072
	ds_read_b128 v[196:199], v151 offset:4096
	ds_read_b128 v[200:203], v151 offset:5120
	ds_read_b128 v[208:211], v151 offset:6144
	ds_read_b128 v[214:217], v151 offset:7168
	global_load_lds_dwordx4 v[144:145], off
	v_lshl_add_u64 v[144:145], s[26:27], 0, v[132:133]
	s_add_i32 m0, s46, 0xe000
	s_nop 0
	global_load_lds_dwordx4 v[144:145], off
	s_waitcnt vmcnt(8)
	s_waitcnt lgkmcnt(0)
	s_barrier
	s_setprio 1
	s_waitcnt lgkmcnt(0)
	v_mfma_f32_16x16x32_bf16 v[124:127], v[140:143], v[180:183], v[124:127]
	v_mfma_f32_16x16x32_bf16 v[120:123], v[156:159], v[180:183], v[120:123]
	v_mfma_f32_16x16x32_bf16 v[112:115], v[140:143], v[188:191], v[112:115]
	v_mfma_f32_16x16x32_bf16 v[104:107], v[156:159], v[188:191], v[104:107]
	v_mfma_f32_16x16x32_bf16 v[96:99], v[140:143], v[196:199], v[96:99]
	v_mfma_f32_16x16x32_bf16 v[88:91], v[156:159], v[196:199], v[88:91]
	v_mfma_f32_16x16x32_bf16 v[80:83], v[140:143], v[208:211], v[80:83]
	v_mfma_f32_16x16x32_bf16 v[72:75], v[156:159], v[208:211], v[72:75]
	v_mfma_f32_16x16x32_bf16 v[124:127], v[152:155], v[184:187], v[124:127]
	v_mfma_f32_16x16x32_bf16 v[120:123], v[160:163], v[184:187], v[120:123]
	v_mfma_f32_16x16x32_bf16 v[112:115], v[152:155], v[192:195], v[112:115]
	v_mfma_f32_16x16x32_bf16 v[104:107], v[160:163], v[192:195], v[104:107]
	v_mfma_f32_16x16x32_bf16 v[96:99], v[152:155], v[200:203], v[96:99]
	v_mfma_f32_16x16x32_bf16 v[88:91], v[160:163], v[200:203], v[88:91]
	v_mfma_f32_16x16x32_bf16 v[80:83], v[152:155], v[214:217], v[80:83]
	v_mfma_f32_16x16x32_bf16 v[72:75], v[160:163], v[214:217], v[72:75]
	s_setprio 0
	s_setprio 1
	v_mfma_f32_16x16x32_bf16 v[116:119], v[164:167], v[180:183], v[116:119]
	v_mfma_f32_16x16x32_bf16 v[108:111], v[172:175], v[180:183], v[108:111]
	v_mfma_f32_16x16x32_bf16 v[100:103], v[164:167], v[188:191], v[100:103]
	v_mfma_f32_16x16x32_bf16 v[92:95], v[172:175], v[188:191], v[92:95]
	v_mfma_f32_16x16x32_bf16 v[84:87], v[164:167], v[196:199], v[84:87]
	v_mfma_f32_16x16x32_bf16 v[76:79], v[172:175], v[196:199], v[76:79]
	v_mfma_f32_16x16x32_bf16 v[68:71], v[164:167], v[208:211], v[68:71]
	v_mfma_f32_16x16x32_bf16 v[64:67], v[172:175], v[208:211], v[64:67]
	v_mfma_f32_16x16x32_bf16 v[116:119], v[168:171], v[184:187], v[116:119]
	v_mfma_f32_16x16x32_bf16 v[108:111], v[176:179], v[184:187], v[108:111]
	v_mfma_f32_16x16x32_bf16 v[100:103], v[168:171], v[192:195], v[100:103]
	v_mfma_f32_16x16x32_bf16 v[92:95], v[176:179], v[192:195], v[92:95]
	v_mfma_f32_16x16x32_bf16 v[84:87], v[168:171], v[200:203], v[84:87]
	v_mfma_f32_16x16x32_bf16 v[76:79], v[176:179], v[200:203], v[76:79]
	v_mfma_f32_16x16x32_bf16 v[68:71], v[168:171], v[214:217], v[68:71]
	v_mfma_f32_16x16x32_bf16 v[64:67], v[176:179], v[214:217], v[64:67]
	s_setprio 0
	s_barrier
	s_add_i32 s16, s60, s45
	v_lshl_add_u64 v[144:145], s[38:39], 0, v[128:129]
	s_mov_b32 m0, s16
	ds_read_b128 v[180:183], v151 offset:16384
	ds_read_b128 v[184:187], v151 offset:17408
	ds_read_b128 v[188:191], v151 offset:18432
	ds_read_b128 v[192:195], v151 offset:19456
	ds_read_b128 v[196:199], v151 offset:20480
	ds_read_b128 v[200:203], v151 offset:21504
	ds_read_b128 v[208:211], v151 offset:22528
	ds_read_b128 v[214:217], v151 offset:23552
	global_load_lds_dwordx4 v[144:145], off
	s_add_i32 m0, s16, 0x2000
	s_add_u32 s26, s38, 0xb0000
	v_lshl_add_u64 v[204:205], s[38:39], 0, v[130:131]
	s_addc_u32 s27, s39, 0
	s_add_i32 s16, s61, s45
	global_load_lds_dwordx4 v[204:205], off
	v_lshl_add_u64 v[218:219], s[26:27], 0, v[128:129]
	s_mov_b32 m0, s16
	v_lshl_add_u64 v[220:221], s[40:41], 0, v[130:131]
	global_load_lds_dwordx4 v[218:219], off
	v_lshl_add_u64 v[218:219], s[26:27], 0, v[130:131]
	s_add_i32 m0, s16, 0x2000
	s_nop 0
	global_load_lds_dwordx4 v[218:219], off
	v_lshl_add_u64 v[218:219], s[40:41], 0, v[128:129]
	s_mov_b32 m0, s46
	s_nop 0
	global_load_lds_dwordx4 v[218:219], off
	s_nop 0
	s_waitcnt vmcnt(7)
	s_waitcnt lgkmcnt(0)
	s_barrier
; #define PG8_STAGE(bufoff, gbase, voff) do { _Pragma("unroll") for (int _i = 0; _i < 2; ++_i) \
;         __builtin_amdgcn_global_load_lds((const unsigned*)((const char*)(gbase) + (voff)[_i]), (PG8_LAS unsigned*)(lds + (bufoff) + ldsw + _i * 8192), 16, 0, 0); } while (0)
; #define PG8_LDA(dst, b, h) do { _Pragma("unroll") for (int m = 0; m < 4; ++m) _Pragma("unroll") for (int k = 0; k < 2; ++k) dst[m][k] = *(const PG8_LAS bf16x8*)(lds + PG8_SA(b, h) + aoff + m * 2048 + k * 1024); } while (0)
; #define PG8_LDB(dst, b, h) do { _Pragma("unroll") for (int n = 0; n < 2; ++n) _Pragma("unroll") for (int k = 0; k < 2; ++k) dst[n][k] = *(const PG8_LAS bf16x8*)(lds + PG8_SB(b, h) + boff + n * 2048 + k * 1024); } while (0)
; #define PG8_WAIT_V(n) asm volatile("s_waitcnt vmcnt(" #n ")" ::: "memory")
; #define PG8_WAIT_L(n) asm volatile("s_waitcnt lgkmcnt(" #n ")" ::: "memory")
; #define PG8_BAR __builtin_amdgcn_s_barrier()
; #define PG8_SCHED __builtin_amdgcn_sched_barrier(0)
; #define PG8_MMA2(ai) PG8_MMA(ai, 0, At, B0)
; #define PG8_MMA2(ai) PG8_MMA(ai, 1, At, B1)
; #define PG8_MMA2(ai) do { PG8_MMA(ai, 0, At, B0); PG8_MMA(ai, 1, At, B1); } while (0)
;     ...
;             PG8_WAIT_V(8); PG8_WAIT_L(0); PG8_BAR; PG8_MMA2(1); PG8_BAR; PG8_SCHED;
;             PG8_LDB(B0, 1, 0); PG8_LDB(B1, 1, 1); PG8_SCHED; PG8_LDA(At, 1, 0); PG8_STAGE(PG8_SA(0, 1), a2 + hstep, voffA);
;             PG8_WAIT_V(8); PG8_WAIT_L(0); PG8_BAR; PG8_MMA2(0); PG8_BAR; PG8_SCHED;
	s_setprio 1
	s_waitcnt lgkmcnt(0)
	v_mfma_f32_16x16x32_bf16 v[60:63], v[140:143], v[180:183], v[60:63]
	v_mfma_f32_16x16x32_bf16 v[56:59], v[156:159], v[180:183], v[56:59]
	v_mfma_f32_16x16x32_bf16 v[48:51], v[140:143], v[188:191], v[48:51]
	v_mfma_f32_16x16x32_bf16 v[40:43], v[156:159], v[188:191], v[40:43]
	v_mfma_f32_16x16x32_bf16 v[32:35], v[140:143], v[196:199], v[32:35]
	v_mfma_f32_16x16x32_bf16 v[24:27], v[156:159], v[196:199], v[24:27]
	v_mfma_f32_16x16x32_bf16 v[16:19], v[140:143], v[208:211], v[16:19]
	v_mfma_f32_16x16x32_bf16 v[8:11], v[156:159], v[208:211], v[8:11]
	v_mfma_f32_16x16x32_bf16 v[60:63], v[152:155], v[184:187], v[60:63]
	v_mfma_f32_16x16x32_bf16 v[56:59], v[160:163], v[184:187], v[56:59]
	v_mfma_f32_16x16x32_bf16 v[48:51], v[152:155], v[192:195], v[48:51]
	v_mfma_f32_16x16x32_bf16 v[40:43], v[160:163], v[192:195], v[40:43]
	v_mfma_f32_16x16x32_bf16 v[32:35], v[152:155], v[200:203], v[32:35]
	v_mfma_f32_16x16x32_bf16 v[24:27], v[160:163], v[200:203], v[24:27]
	v_mfma_f32_16x16x32_bf16 v[16:19], v[152:155], v[214:217], v[16:19]
	v_mfma_f32_16x16x32_bf16 v[8:11], v[160:163], v[214:217], v[8:11]
	s_setprio 0
	s_setprio 1
	v_mfma_f32_16x16x32_bf16 v[52:55], v[164:167], v[180:183], v[52:55]
	v_mfma_f32_16x16x32_bf16 v[44:47], v[172:175], v[180:183], v[44:47]
	v_mfma_f32_16x16x32_bf16 v[36:39], v[164:167], v[188:191], v[36:39]
	v_mfma_f32_16x16x32_bf16 v[28:31], v[172:175], v[188:191], v[28:31]
	v_mfma_f32_16x16x32_bf16 v[20:23], v[164:167], v[196:199], v[20:23]
	v_mfma_f32_16x16x32_bf16 v[12:15], v[172:175], v[196:199], v[12:15]
	v_mfma_f32_16x16x32_bf16 v[4:7], v[164:167], v[208:211], v[4:7]
	v_mfma_f32_16x16x32_bf16 v[0:3], v[172:175], v[208:211], v[0:3]
	v_mfma_f32_16x16x32_bf16 v[52:55], v[168:171], v[184:187], v[52:55]
	v_mfma_f32_16x16x32_bf16 v[44:47], v[176:179], v[184:187], v[44:47]
	v_mfma_f32_16x16x32_bf16 v[36:39], v[168:171], v[192:195], v[36:39]
	v_mfma_f32_16x16x32_bf16 v[28:31], v[176:179], v[192:195], v[28:31]
	v_mfma_f32_16x16x32_bf16 v[20:23], v[168:171], v[200:203], v[20:23]
	v_mfma_f32_16x16x32_bf16 v[12:15], v[176:179], v[200:203], v[12:15]
	v_mfma_f32_16x16x32_bf16 v[4:7], v[168:171], v[214:217], v[4:7]
	v_mfma_f32_16x16x32_bf16 v[0:3], v[176:179], v[214:217], v[0:3]
	s_setprio 0
	s_barrier
	s_add_i32 s16, 0, 0x18000
	s_add_i32 s17, 0, 0x1c000
	v_add_u32_e32 v160, s16, v147
	v_add_u32_e32 v176, s17, v147
	ds_read_b128 v[140:143], v160
	ds_read_b128 v[152:155], v160 offset:1024
	ds_read_b128 v[156:159], v160 offset:2048
	ds_read_b128 v[160:163], v160 offset:3072
	ds_read_b128 v[164:167], v176
	ds_read_b128 v[168:171], v176 offset:1024
	ds_read_b128 v[172:175], v176 offset:2048
	ds_read_b128 v[176:179], v176 offset:3072
	s_add_u32 s26, s40, 0xb0000
	s_addc_u32 s27, s41, 0
	s_mov_b32 m0, s47
	s_nop 0
	global_load_lds_dwordx4 v[220:221], off
	s_mov_b32 m0, s48
	v_lshl_add_u64 v[222:223], s[26:27], 0, v[128:129]
	ds_read_b128 v[180:183], v151 offset:32768
	ds_read_b128 v[184:187], v151 offset:33792
	ds_read_b128 v[188:191], v151 offset:34816
	ds_read_b128 v[192:195], v151 offset:35840
	ds_read_b128 v[196:199], v151 offset:36864
	ds_read_b128 v[200:203], v151 offset:37888
	ds_read_b128 v[208:211], v151 offset:38912
	ds_read_b128 v[214:217], v151 offset:39936
	global_load_lds_dwordx4 v[222:223], off
	v_lshl_add_u64 v[222:223], s[26:27], 0, v[130:131]
	s_mov_b32 m0, s49
	s_nop 0
	global_load_lds_dwordx4 v[222:223], off
	s_waitcnt vmcnt(8)
	s_waitcnt lgkmcnt(0)
	s_barrier
	s_setprio 1
	s_waitcnt lgkmcnt(0)
	v_mfma_f32_16x16x32_bf16 v[124:127], v[140:143], v[180:183], v[124:127]
	v_mfma_f32_16x16x32_bf16 v[120:123], v[156:159], v[180:183], v[120:123]
	v_mfma_f32_16x16x32_bf16 v[112:115], v[140:143], v[188:191], v[112:115]
	v_mfma_f32_16x16x32_bf16 v[104:107], v[156:159], v[188:191], v[104:107]
	v_mfma_f32_16x16x32_bf16 v[96:99], v[140:143], v[196:199], v[96:99]
	v_mfma_f32_16x16x32_bf16 v[88:91], v[156:159], v[196:199], v[88:91]
	v_mfma_f32_16x16x32_bf16 v[80:83], v[140:143], v[208:211], v[80:83]
	v_mfma_f32_16x16x32_bf16 v[72:75], v[156:159], v[208:211], v[72:75]
	v_mfma_f32_16x16x32_bf16 v[124:127], v[152:155], v[184:187], v[124:127]
	v_mfma_f32_16x16x32_bf16 v[120:123], v[160:163], v[184:187], v[120:123]
	v_mfma_f32_16x16x32_bf16 v[112:115], v[152:155], v[192:195], v[112:115]
	v_mfma_f32_16x16x32_bf16 v[104:107], v[160:163], v[192:195], v[104:107]
	v_mfma_f32_16x16x32_bf16 v[96:99], v[152:155], v[200:203], v[96:99]
	v_mfma_f32_16x16x32_bf16 v[88:91], v[160:163], v[200:203], v[88:91]
	v_mfma_f32_16x16x32_bf16 v[80:83], v[152:155], v[214:217], v[80:83]
	v_mfma_f32_16x16x32_bf16 v[72:75], v[160:163], v[214:217], v[72:75]
	s_setprio 0
	s_setprio 1
	v_mfma_f32_16x16x32_bf16 v[116:119], v[164:167], v[180:183], v[116:119]
	v_mfma_f32_16x16x32_bf16 v[108:111], v[172:175], v[180:183], v[108:111]
	v_mfma_f32_16x16x32_bf16 v[100:103], v[164:167], v[188:191], v[100:103]
	v_mfma_f32_16x16x32_bf16 v[92:95], v[172:175], v[188:191], v[92:95]
	v_mfma_f32_16x16x32_bf16 v[84:87], v[164:167], v[196:199], v[84:87]
	v_mfma_f32_16x16x32_bf16 v[76:79], v[172:175], v[196:199], v[76:79]
	v_mfma_f32_16x16x32_bf16 v[68:71], v[164:167], v[208:211], v[68:71]
	v_mfma_f32_16x16x32_bf16 v[64:67], v[172:175], v[208:211], v[64:67]
	v_mfma_f32_16x16x32_bf16 v[116:119], v[168:171], v[184:187], v[116:119]
	v_mfma_f32_16x16x32_bf16 v[108:111], v[176:179], v[184:187], v[108:111]
	v_mfma_f32_16x16x32_bf16 v[100:103], v[168:171], v[192:195], v[100:103]
	v_mfma_f32_16x16x32_bf16 v[92:95], v[176:179], v[192:195], v[92:95]
	v_mfma_f32_16x16x32_bf16 v[84:87], v[168:171], v[200:203], v[84:87]
	v_mfma_f32_16x16x32_bf16 v[76:79], v[176:179], v[200:203], v[76:79]
	v_mfma_f32_16x16x32_bf16 v[68:71], v[168:171], v[214:217], v[68:71]
	v_mfma_f32_16x16x32_bf16 v[64:67], v[176:179], v[214:217], v[64:67]
	s_setprio 0
	s_barrier
; #define PG8_STAGE(bufoff, gbase, voff) do { _Pragma("unroll") for (int _i = 0; _i < 2; ++_i) \
;         __builtin_amdgcn_global_load_lds((const unsigned*)((const char*)(gbase) + (voff)[_i]), (PG8_LAS unsigned*)(lds + (bufoff) + ldsw + _i * 8192), 16, 0, 0); } while (0)
; #define PG8_LDA(dst, b, h) do { _Pragma("unroll") for (int m = 0; m < 4; ++m) _Pragma("unroll") for (int k = 0; k < 2; ++k) dst[m][k] = *(const PG8_LAS bf16x8*)(lds + PG8_SA(b, h) + aoff + m * 2048 + k * 1024); } while (0)
; #define PG8_WAIT_V(n) asm volatile("s_waitcnt vmcnt(" #n ")" ::: "memory")
; #define PG8_WAIT_L(n) asm volatile("s_waitcnt lgkmcnt(" #n ")" ::: "memory")
; #define PG8_BAR __builtin_amdgcn_s_barrier()
; #define PG8_SCHED __builtin_amdgcn_sched_barrier(0)
; #define PG8_MMA2(ai) PG8_MMA(ai, 0, At, B0)
; #define PG8_MMA2(ai) PG8_MMA(ai, 1, At, B1)
; #define PG8_MMA2(ai) do { PG8_MMA(ai, 0, At, B0); PG8_MMA(ai, 1, At, B1); } while (0)
;     ...
;         for (int t = 0; t < nt; t += 2) {
;             const bool last = (t == nt - 2);
;             const char* a1 = cA + (size_t)(t + 1) * kstep;
;             const char* a2 = last ? nA : cA + (size_t)(t + 2) * kstep; const char* b2 = last ? nB : cB + (size_t)(t + 2) * kstep;
;             const char* a3 = a2 + kstep; const char* b3 = b2 + kstep;
;     ...
;             PG8_LDA(At, 1, 1); PG8_STAGE(PG8_SB(1, 0), b3, voffB); PG8_STAGE(PG8_SB(1, 1), b3 + hstep, voffB); PG8_STAGE(PG8_SA(1, 0), a3, voffA);
;             PG8_WAIT_V(8); PG8_WAIT_L(0); PG8_BAR; PG8_MMA2(1); PG8_BAR; PG8_SCHED;
	s_add_i32 s16, s16, s45
	v_lshl_add_u64 v[144:145], v[144:145], 0, s[14:15]
	s_mov_b32 m0, s16
	ds_read_b128 v[180:183], v151 offset:49152
	ds_read_b128 v[184:187], v151 offset:50176
	ds_read_b128 v[188:191], v151 offset:51200
	ds_read_b128 v[192:195], v151 offset:52224
	ds_read_b128 v[196:199], v151 offset:53248
	ds_read_b128 v[200:203], v151 offset:54272
	ds_read_b128 v[208:211], v151 offset:55296
	ds_read_b128 v[214:217], v151 offset:56320
	global_load_lds_dwordx4 v[144:145], off
	s_add_i32 m0, s16, 0x2000
	s_add_u32 s26, s38, 0xb0080
	v_lshl_add_u64 v[144:145], v[204:205], 0, s[14:15]
	s_addc_u32 s27, s39, 0
	s_add_i32 s16, s17, s45
	global_load_lds_dwordx4 v[144:145], off
	v_lshl_add_u64 v[144:145], s[26:27], 0, v[128:129]
	s_mov_b32 m0, s16
	s_nop 0
	global_load_lds_dwordx4 v[144:145], off
	v_lshl_add_u64 v[144:145], s[26:27], 0, v[130:131]
	s_add_i32 m0, s16, 0x2000
	s_nop 0
	global_load_lds_dwordx4 v[144:145], off
	v_lshl_add_u64 v[144:145], v[218:219], 0, s[14:15]
	s_mov_b32 m0, s55
	s_nop 0
	global_load_lds_dwordx4 v[144:145], off
	v_lshl_add_u64 v[144:145], v[220:221], 0, s[14:15]
	s_nop 0
	s_cmp_lg_u32 s69, 40
	s_cbranch_scc1 .Ldf_skipD_1
	s_mov_b32 m0, s56
	s_nop 0
	global_load_lds_dwordx4 v[144:145], off
.Ldf_skipD_1:
	s_waitcnt vmcnt(7)
	s_waitcnt lgkmcnt(0)
	s_barrier
	s_setprio 1
	s_waitcnt lgkmcnt(0)
	v_mfma_f32_16x16x32_bf16 v[60:63], v[140:143], v[180:183], v[60:63]
	v_mfma_f32_16x16x32_bf16 v[56:59], v[156:159], v[180:183], v[56:59]
	v_mfma_f32_16x16x32_bf16 v[48:51], v[140:143], v[188:191], v[48:51]
	v_mfma_f32_16x16x32_bf16 v[40:43], v[156:159], v[188:191], v[40:43]
	v_mfma_f32_16x16x32_bf16 v[32:35], v[140:143], v[196:199], v[32:35]
	v_mfma_f32_16x16x32_bf16 v[24:27], v[156:159], v[196:199], v[24:27]
	v_mfma_f32_16x16x32_bf16 v[16:19], v[140:143], v[208:211], v[16:19]
	v_mfma_f32_16x16x32_bf16 v[8:11], v[156:159], v[208:211], v[8:11]
	v_mfma_f32_16x16x32_bf16 v[60:63], v[152:155], v[184:187], v[60:63]
	v_mfma_f32_16x16x32_bf16 v[56:59], v[160:163], v[184:187], v[56:59]
	v_mfma_f32_16x16x32_bf16 v[48:51], v[152:155], v[192:195], v[48:51]
	v_mfma_f32_16x16x32_bf16 v[40:43], v[160:163], v[192:195], v[40:43]
	v_mfma_f32_16x16x32_bf16 v[32:35], v[152:155], v[200:203], v[32:35]
	v_mfma_f32_16x16x32_bf16 v[24:27], v[160:163], v[200:203], v[24:27]
	v_mfma_f32_16x16x32_bf16 v[16:19], v[152:155], v[214:217], v[16:19]
	v_mfma_f32_16x16x32_bf16 v[8:11], v[160:163], v[214:217], v[8:11]
	s_setprio 0
	s_setprio 1
	v_mfma_f32_16x16x32_bf16 v[52:55], v[164:167], v[180:183], v[52:55]
	v_mfma_f32_16x16x32_bf16 v[44:47], v[172:175], v[180:183], v[44:47]
	v_mfma_f32_16x16x32_bf16 v[36:39], v[164:167], v[188:191], v[36:39]
	v_mfma_f32_16x16x32_bf16 v[28:31], v[172:175], v[188:191], v[28:31]
	v_mfma_f32_16x16x32_bf16 v[20:23], v[164:167], v[196:199], v[20:23]
	v_mfma_f32_16x16x32_bf16 v[12:15], v[172:175], v[196:199], v[12:15]
	v_mfma_f32_16x16x32_bf16 v[4:7], v[164:167], v[208:211], v[4:7]
	v_mfma_f32_16x16x32_bf16 v[0:3], v[172:175], v[208:211], v[0:3]
	v_mfma_f32_16x16x32_bf16 v[52:55], v[168:171], v[184:187], v[52:55]
	v_mfma_f32_16x16x32_bf16 v[44:47], v[176:179], v[184:187], v[44:47]
	v_mfma_f32_16x16x32_bf16 v[36:39], v[168:171], v[192:195], v[36:39]
	v_mfma_f32_16x16x32_bf16 v[28:31], v[176:179], v[192:195], v[28:31]
	v_mfma_f32_16x16x32_bf16 v[20:23], v[168:171], v[200:203], v[20:23]
	v_mfma_f32_16x16x32_bf16 v[12:15], v[176:179], v[200:203], v[12:15]
	v_mfma_f32_16x16x32_bf16 v[4:7], v[168:171], v[214:217], v[4:7]
	v_mfma_f32_16x16x32_bf16 v[0:3], v[176:179], v[214:217], v[0:3]
	s_setprio 0
	s_barrier
	s_add_i32 s69, s69, 2
	s_add_u32 s67, s67, 0x100
	s_addc_u32 s68, s68, 0
	s_cmp_gt_u32 s69, 41
	s_mov_b64 s[26:27], s[36:37]
	s_cbranch_scc0 .LBB0_312
	s_and_b64 vcc, exec, s[20:21]
	s_cbranch_vccz .LBB0_315
	s_barrier

; #define PG8_STAGE(bufoff, gbase, voff) do { _Pragma("unroll") for (int _i = 0; _i < 2; ++_i) \
;         __builtin_amdgcn_global_load_lds((const unsigned*)((const char*)(gbase) + (voff)[_i]), (PG8_LAS unsigned*)(lds + (bufoff) + ldsw + _i * 8192), 16, 0, 0); } while (0)
; #define PG8_LDA(dst, b, h) do { _Pragma("unroll") for (int m = 0; m < 4; ++m) _Pragma("unroll") for (int k = 0; k < 2; ++k) dst[m][k] = *(const PG8_LAS bf16x8*)(lds + PG8_SA(b, h) + aoff + m * 2048 + k * 1024); } while (0)
; #define PG8_LDB(dst, b, h) do { _Pragma("unroll") for (int n = 0; n < 2; ++n) _Pragma("unroll") for (int k = 0; k < 2; ++k) dst[n][k] = *(const PG8_LAS bf16x8*)(lds + PG8_SB(b, h) + boff + n * 2048 + k * 1024); } while (0)
; #define PG8_WAIT_V(n) asm volatile("s_waitcnt vmcnt(" #n ")" ::: "memory")
; #define PG8_WAIT_L(n) asm volatile("s_waitcnt lgkmcnt(" #n ")" ::: "memory")
; #define PG8_BAR __builtin_amdgcn_s_barrier()
; #define PG8_SCHED __builtin_amdgcn_sched_barrier(0)
; #define PG8_MMA2(ai) PG8_MMA(ai, 0, At, B0)
; #define PG8_MMA2(ai) PG8_MMA(ai, 1, At, B1)
; #define PG8_MMA2(ai) do { PG8_MMA(ai, 0, At, B0); PG8_MMA(ai, 1, At, B1); } while (0)
;     ...
;             const bool last = (t == nt - 2);
;             const char* a1 = cA + (size_t)(t + 1) * kstep;
;             const char* a2 = last ? nA : cA + (size_t)(t + 2) * kstep; const char* b2 = last ? nB : cB + (size_t)(t + 2) * kstep;
;             const char* a3 = a2 + kstep; const char* b3 = b2 + kstep;
;             if (last && has_next) S.a_ready(nxt);
;             if constexpr (SP2) {
;             PG8_LDB(B0, 0, 0); PG8_LDB(B1, 0, 1); PG8_SCHED; PG8_LDA(At, 0, 0); PG8_STAGE(PG8_SA(1, 1), a1 + hstep, voffA);
;             PG8_WAIT_V(8); PG8_WAIT_L(0); PG8_BAR; PG8_MMA2(0); PG8_BAR; PG8_SCHED;
;             PG8_LDA(At, 0, 1); PG8_STAGE(PG8_SB(0, 0), b2, voffB); PG8_STAGE(PG8_SB(0, 1), b2 + hstep, voffB); PG8_STAGE(PG8_SA(0, 0), a2, voffA);
;             PG8_WAIT_V(8); PG8_WAIT_L(0); PG8_BAR; PG8_MMA2(1); PG8_BAR; PG8_SCHED;
.LBB0_454:
	s_cmp_eq_u32 s67, -2
	s_cbranch_scc1 .Ldf_skipA_2
	s_mov_b32 m0, s84
	s_nop 0
	global_load_lds_dwordx4 v[172:173], off
.Ldf_skipA_2:
	s_waitcnt lgkmcnt(0)
	ds_read_b128 v[128:131], v182
	ds_read_b128 v[132:135], v182 offset:1024
	ds_read_b128 v[136:139], v182 offset:2048
	ds_read_b128 v[140:143], v182 offset:3072
	ds_read_b128 v[168:171], v183
	ds_read_b128 v[188:191], v183 offset:1024
	ds_read_b128 v[192:195], v183 offset:2048
	ds_read_b128 v[196:199], v183 offset:3072
	s_add_u32 s16, s12, 0xfffc0080
	s_addc_u32 s17, s13, -1
	s_cmp_eq_u32 s67, 12
	s_cselect_b32 s71, s6, s17
	s_cselect_b32 s70, s7, s16
	s_cselect_b32 s69, s15, s61
	s_cselect_b32 s68, s22, s59
	v_lshl_add_u64 v[172:173], s[12:13], 0, v[162:163]
	s_add_i32 m0, s75, 0xc000
	ds_read_b128 v[200:203], v184
	ds_read_b128 v[208:211], v184 offset:1024
	ds_read_b128 v[214:217], v184 offset:2048
	ds_read_b128 v[218:221], v184 offset:3072
	ds_read_b128 v[222:225], v184 offset:4096
	ds_read_b128 v[226:229], v184 offset:5120
	ds_read_b128 v[230:233], v184 offset:6144
	ds_read_b128 v[234:237], v184 offset:7168
	global_load_lds_dwordx4 v[172:173], off
	v_lshl_add_u64 v[172:173], s[12:13], 0, v[160:161]
	s_add_i32 m0, s75, 0xe000
	s_nop 0
	global_load_lds_dwordx4 v[172:173], off
	s_waitcnt vmcnt(8)
	s_waitcnt lgkmcnt(0)
	s_barrier
	s_setprio 1
	s_waitcnt lgkmcnt(0)
	v_mfma_f32_16x16x32_bf16 v[124:127], v[128:131], v[200:203], v[124:127]
	v_mfma_f32_16x16x32_bf16 v[120:123], v[136:139], v[200:203], v[120:123]
	v_mfma_f32_16x16x32_bf16 v[108:111], v[128:131], v[214:217], v[108:111]
	v_mfma_f32_16x16x32_bf16 v[104:107], v[136:139], v[214:217], v[104:107]
	v_mfma_f32_16x16x32_bf16 v[92:95], v[128:131], v[222:225], v[92:95]
	v_mfma_f32_16x16x32_bf16 v[88:91], v[136:139], v[222:225], v[88:91]
	v_mfma_f32_16x16x32_bf16 v[76:79], v[128:131], v[230:233], v[76:79]
	v_mfma_f32_16x16x32_bf16 v[72:75], v[136:139], v[230:233], v[72:75]
	v_mfma_f32_16x16x32_bf16 v[124:127], v[132:135], v[208:211], v[124:127]
	v_mfma_f32_16x16x32_bf16 v[120:123], v[140:143], v[208:211], v[120:123]
	v_mfma_f32_16x16x32_bf16 v[108:111], v[132:135], v[218:221], v[108:111]
	v_mfma_f32_16x16x32_bf16 v[104:107], v[140:143], v[218:221], v[104:107]
	v_mfma_f32_16x16x32_bf16 v[92:95], v[132:135], v[226:229], v[92:95]
	v_mfma_f32_16x16x32_bf16 v[88:91], v[140:143], v[226:229], v[88:91]
	v_mfma_f32_16x16x32_bf16 v[76:79], v[132:135], v[234:237], v[76:79]
	v_mfma_f32_16x16x32_bf16 v[72:75], v[140:143], v[234:237], v[72:75]
	s_setprio 0
	s_setprio 1
	v_mfma_f32_16x16x32_bf16 v[116:119], v[168:171], v[200:203], v[116:119]
	v_mfma_f32_16x16x32_bf16 v[112:115], v[192:195], v[200:203], v[112:115]
	v_mfma_f32_16x16x32_bf16 v[100:103], v[168:171], v[214:217], v[100:103]
	v_mfma_f32_16x16x32_bf16 v[96:99], v[192:195], v[214:217], v[96:99]
	v_mfma_f32_16x16x32_bf16 v[84:87], v[168:171], v[222:225], v[84:87]
	v_mfma_f32_16x16x32_bf16 v[80:83], v[192:195], v[222:225], v[80:83]
	v_mfma_f32_16x16x32_bf16 v[68:71], v[168:171], v[230:233], v[68:71]
	v_mfma_f32_16x16x32_bf16 v[64:67], v[192:195], v[230:233], v[64:67]
	v_mfma_f32_16x16x32_bf16 v[116:119], v[188:191], v[208:211], v[116:119]
	v_mfma_f32_16x16x32_bf16 v[112:115], v[196:199], v[208:211], v[112:115]
	v_mfma_f32_16x16x32_bf16 v[100:103], v[188:191], v[218:221], v[100:103]
	v_mfma_f32_16x16x32_bf16 v[96:99], v[196:199], v[218:221], v[96:99]
	v_mfma_f32_16x16x32_bf16 v[84:87], v[188:191], v[226:229], v[84:87]
	v_mfma_f32_16x16x32_bf16 v[80:83], v[196:199], v[226:229], v[80:83]
	v_mfma_f32_16x16x32_bf16 v[68:71], v[188:191], v[234:237], v[68:71]
	v_mfma_f32_16x16x32_bf16 v[64:67], v[196:199], v[234:237], v[64:67]
	s_setprio 0
	s_barrier
	s_add_i32 s16, s88, s74
	v_lshl_add_u64 v[172:173], s[68:69], 0, v[146:147]
	s_mov_b32 m0, s16
	ds_read_b128 v[200:203], v184 offset:16384
	ds_read_b128 v[208:211], v184 offset:17408
	ds_read_b128 v[214:217], v184 offset:18432
	ds_read_b128 v[218:221], v184 offset:19456
	ds_read_b128 v[222:225], v184 offset:20480
	ds_read_b128 v[226:229], v184 offset:21504
	ds_read_b128 v[230:233], v184 offset:22528
	ds_read_b128 v[234:237], v184 offset:23552
	global_load_lds_dwordx4 v[172:173], off
	s_add_i32 m0, s16, 0x2000
	s_add_u32 s34, s68, 0x40000
	v_lshl_add_u64 v[204:205], s[68:69], 0, v[150:151]
	s_addc_u32 s35, s69, 0
	s_add_i32 s16, s89, s74
	global_load_lds_dwordx4 v[204:205], off
	v_lshl_add_u64 v[238:239], s[34:35], 0, v[146:147]
	s_mov_b32 m0, s16
	v_lshl_add_u64 v[240:241], s[70:71], 0, v[148:149]
	global_load_lds_dwordx4 v[238:239], off
	v_lshl_add_u64 v[238:239], s[34:35], 0, v[150:151]
	s_add_i32 m0, s16, 0x2000
	s_nop 0
	global_load_lds_dwordx4 v[238:239], off
	v_lshl_add_u64 v[238:239], s[70:71], 0, v[144:145]
	s_mov_b32 m0, s75
	s_nop 0
	global_load_lds_dwordx4 v[238:239], off
	s_nop 0
	s_waitcnt vmcnt(7)
	s_waitcnt lgkmcnt(0)
	s_barrier
; #define PG8_STAGE(bufoff, gbase, voff) do { _Pragma("unroll") for (int _i = 0; _i < 2; ++_i) \
;         __builtin_amdgcn_global_load_lds((const unsigned*)((const char*)(gbase) + (voff)[_i]), (PG8_LAS unsigned*)(lds + (bufoff) + ldsw + _i * 8192), 16, 0, 0); } while (0)
; #define PG8_LDA(dst, b, h) do { _Pragma("unroll") for (int m = 0; m < 4; ++m) _Pragma("unroll") for (int k = 0; k < 2; ++k) dst[m][k] = *(const PG8_LAS bf16x8*)(lds + PG8_SA(b, h) + aoff + m * 2048 + k * 1024); } while (0)
; #define PG8_LDB(dst, b, h) do { _Pragma("unroll") for (int n = 0; n < 2; ++n) _Pragma("unroll") for (int k = 0; k < 2; ++k) dst[n][k] = *(const PG8_LAS bf16x8*)(lds + PG8_SB(b, h) + boff + n * 2048 + k * 1024); } while (0)
; #define PG8_WAIT_V(n) asm volatile("s_waitcnt vmcnt(" #n ")" ::: "memory")
; #define PG8_WAIT_L(n) asm volatile("s_waitcnt lgkmcnt(" #n ")" ::: "memory")
; #define PG8_BAR __builtin_amdgcn_s_barrier()
; #define PG8_SCHED __builtin_amdgcn_sched_barrier(0)
; #define PG8_MMA2(ai) PG8_MMA(ai, 0, At, B0)
; #define PG8_MMA2(ai) PG8_MMA(ai, 1, At, B1)
; #define PG8_MMA2(ai) do { PG8_MMA(ai, 0, At, B0); PG8_MMA(ai, 1, At, B1); } while (0)
;     ...
;             PG8_WAIT_V(8); PG8_WAIT_L(0); PG8_BAR; PG8_MMA2(1); PG8_BAR; PG8_SCHED;
;             PG8_LDB(B0, 1, 0); PG8_LDB(B1, 1, 1); PG8_SCHED; PG8_LDA(At, 1, 0); PG8_STAGE(PG8_SA(0, 1), a2 + hstep, voffA);
;             PG8_WAIT_V(8); PG8_WAIT_L(0); PG8_BAR; PG8_MMA2(0); PG8_BAR; PG8_SCHED;
	s_setprio 1
	s_waitcnt lgkmcnt(0)
	v_mfma_f32_16x16x32_bf16 v[60:63], v[128:131], v[200:203], v[60:63]
	v_mfma_f32_16x16x32_bf16 v[56:59], v[136:139], v[200:203], v[56:59]
	v_mfma_f32_16x16x32_bf16 v[44:47], v[128:131], v[214:217], v[44:47]
	v_mfma_f32_16x16x32_bf16 v[40:43], v[136:139], v[214:217], v[40:43]
	v_mfma_f32_16x16x32_bf16 v[28:31], v[128:131], v[222:225], v[28:31]
	v_mfma_f32_16x16x32_bf16 v[24:27], v[136:139], v[222:225], v[24:27]
	v_mfma_f32_16x16x32_bf16 v[12:15], v[128:131], v[230:233], v[12:15]
	v_mfma_f32_16x16x32_bf16 v[8:11], v[136:139], v[230:233], v[8:11]
	v_mfma_f32_16x16x32_bf16 v[60:63], v[132:135], v[208:211], v[60:63]
	v_mfma_f32_16x16x32_bf16 v[56:59], v[140:143], v[208:211], v[56:59]
	v_mfma_f32_16x16x32_bf16 v[44:47], v[132:135], v[218:221], v[44:47]
	v_mfma_f32_16x16x32_bf16 v[40:43], v[140:143], v[218:221], v[40:43]
	v_mfma_f32_16x16x32_bf16 v[28:31], v[132:135], v[226:229], v[28:31]
	v_mfma_f32_16x16x32_bf16 v[24:27], v[140:143], v[226:229], v[24:27]
	v_mfma_f32_16x16x32_bf16 v[12:15], v[132:135], v[234:237], v[12:15]
	v_mfma_f32_16x16x32_bf16 v[8:11], v[140:143], v[234:237], v[8:11]
	s_setprio 0
	s_setprio 1
	v_mfma_f32_16x16x32_bf16 v[52:55], v[168:171], v[200:203], v[52:55]
	v_mfma_f32_16x16x32_bf16 v[48:51], v[192:195], v[200:203], v[48:51]
	v_mfma_f32_16x16x32_bf16 v[36:39], v[168:171], v[214:217], v[36:39]
	v_mfma_f32_16x16x32_bf16 v[32:35], v[192:195], v[214:217], v[32:35]
	v_mfma_f32_16x16x32_bf16 v[20:23], v[168:171], v[222:225], v[20:23]
	v_mfma_f32_16x16x32_bf16 v[16:19], v[192:195], v[222:225], v[16:19]
	v_mfma_f32_16x16x32_bf16 v[4:7], v[168:171], v[230:233], v[4:7]
	v_mfma_f32_16x16x32_bf16 v[0:3], v[192:195], v[230:233], v[0:3]
	v_mfma_f32_16x16x32_bf16 v[52:55], v[188:191], v[208:211], v[52:55]
	v_mfma_f32_16x16x32_bf16 v[48:51], v[196:199], v[208:211], v[48:51]
	v_mfma_f32_16x16x32_bf16 v[36:39], v[188:191], v[218:221], v[36:39]
	v_mfma_f32_16x16x32_bf16 v[32:35], v[196:199], v[218:221], v[32:35]
	v_mfma_f32_16x16x32_bf16 v[20:23], v[188:191], v[226:229], v[20:23]
	v_mfma_f32_16x16x32_bf16 v[16:19], v[196:199], v[226:229], v[16:19]
	v_mfma_f32_16x16x32_bf16 v[4:7], v[188:191], v[234:237], v[4:7]
	v_mfma_f32_16x16x32_bf16 v[0:3], v[196:199], v[234:237], v[0:3]
	s_setprio 0
	s_barrier
	s_add_i32 s16, 0, 0x18000
	s_add_i32 s17, 0, 0x1c000
	v_add_u32_e32 v140, s16, v174
	v_add_u32_e32 v196, s17, v174
	ds_read_b128 v[128:131], v140
	ds_read_b128 v[132:135], v140 offset:1024
	ds_read_b128 v[136:139], v140 offset:2048
	ds_read_b128 v[140:143], v140 offset:3072
	ds_read_b128 v[168:171], v196
	ds_read_b128 v[188:191], v196 offset:1024
	ds_read_b128 v[192:195], v196 offset:2048
	ds_read_b128 v[196:199], v196 offset:3072
	s_add_u32 s34, s70, 0x40000
	s_addc_u32 s35, s71, 0
	s_mov_b32 m0, s76
	s_nop 0
	global_load_lds_dwordx4 v[240:241], off
	s_mov_b32 m0, s77
	v_lshl_add_u64 v[242:243], s[34:35], 0, v[144:145]
	ds_read_b128 v[200:203], v184 offset:32768
	ds_read_b128 v[208:211], v184 offset:33792
	ds_read_b128 v[214:217], v184 offset:34816
	ds_read_b128 v[218:221], v184 offset:35840
	ds_read_b128 v[222:225], v184 offset:36864
	ds_read_b128 v[226:229], v184 offset:37888
	ds_read_b128 v[230:233], v184 offset:38912
	ds_read_b128 v[234:237], v184 offset:39936
	global_load_lds_dwordx4 v[242:243], off
	v_lshl_add_u64 v[242:243], s[34:35], 0, v[148:149]
	s_mov_b32 m0, s78
	s_nop 0
	global_load_lds_dwordx4 v[242:243], off
	s_waitcnt vmcnt(8)
	s_waitcnt lgkmcnt(0)
	s_barrier
	s_setprio 1
	s_waitcnt lgkmcnt(0)
	v_mfma_f32_16x16x32_bf16 v[124:127], v[128:131], v[200:203], v[124:127]
	v_mfma_f32_16x16x32_bf16 v[120:123], v[136:139], v[200:203], v[120:123]
	v_mfma_f32_16x16x32_bf16 v[108:111], v[128:131], v[214:217], v[108:111]
	v_mfma_f32_16x16x32_bf16 v[104:107], v[136:139], v[214:217], v[104:107]
	v_mfma_f32_16x16x32_bf16 v[92:95], v[128:131], v[222:225], v[92:95]
	v_mfma_f32_16x16x32_bf16 v[88:91], v[136:139], v[222:225], v[88:91]
	v_mfma_f32_16x16x32_bf16 v[76:79], v[128:131], v[230:233], v[76:79]
	v_mfma_f32_16x16x32_bf16 v[72:75], v[136:139], v[230:233], v[72:75]
	v_mfma_f32_16x16x32_bf16 v[124:127], v[132:135], v[208:211], v[124:127]
	v_mfma_f32_16x16x32_bf16 v[120:123], v[140:143], v[208:211], v[120:123]
	v_mfma_f32_16x16x32_bf16 v[108:111], v[132:135], v[218:221], v[108:111]
	v_mfma_f32_16x16x32_bf16 v[104:107], v[140:143], v[218:221], v[104:107]
	v_mfma_f32_16x16x32_bf16 v[92:95], v[132:135], v[226:229], v[92:95]
	v_mfma_f32_16x16x32_bf16 v[88:91], v[140:143], v[226:229], v[88:91]
	v_mfma_f32_16x16x32_bf16 v[76:79], v[132:135], v[234:237], v[76:79]
	v_mfma_f32_16x16x32_bf16 v[72:75], v[140:143], v[234:237], v[72:75]
	s_setprio 0
	s_setprio 1
	v_mfma_f32_16x16x32_bf16 v[116:119], v[168:171], v[200:203], v[116:119]
	v_mfma_f32_16x16x32_bf16 v[112:115], v[192:195], v[200:203], v[112:115]
	v_mfma_f32_16x16x32_bf16 v[100:103], v[168:171], v[214:217], v[100:103]
	v_mfma_f32_16x16x32_bf16 v[96:99], v[192:195], v[214:217], v[96:99]
	v_mfma_f32_16x16x32_bf16 v[84:87], v[168:171], v[222:225], v[84:87]
	v_mfma_f32_16x16x32_bf16 v[80:83], v[192:195], v[222:225], v[80:83]
	v_mfma_f32_16x16x32_bf16 v[68:71], v[168:171], v[230:233], v[68:71]
	v_mfma_f32_16x16x32_bf16 v[64:67], v[192:195], v[230:233], v[64:67]
	v_mfma_f32_16x16x32_bf16 v[116:119], v[188:191], v[208:211], v[116:119]
	v_mfma_f32_16x16x32_bf16 v[112:115], v[196:199], v[208:211], v[112:115]
	v_mfma_f32_16x16x32_bf16 v[100:103], v[188:191], v[218:221], v[100:103]
	v_mfma_f32_16x16x32_bf16 v[96:99], v[196:199], v[218:221], v[96:99]
	v_mfma_f32_16x16x32_bf16 v[84:87], v[188:191], v[226:229], v[84:87]
	v_mfma_f32_16x16x32_bf16 v[80:83], v[196:199], v[226:229], v[80:83]
	v_mfma_f32_16x16x32_bf16 v[68:71], v[188:191], v[234:237], v[68:71]
	v_mfma_f32_16x16x32_bf16 v[64:67], v[196:199], v[234:237], v[64:67]
	s_setprio 0
	s_barrier
; #define PG8_STAGE(bufoff, gbase, voff) do { _Pragma("unroll") for (int _i = 0; _i < 2; ++_i) \
;         __builtin_amdgcn_global_load_lds((const unsigned*)((const char*)(gbase) + (voff)[_i]), (PG8_LAS unsigned*)(lds + (bufoff) + ldsw + _i * 8192), 16, 0, 0); } while (0)
; #define PG8_LDA(dst, b, h) do { _Pragma("unroll") for (int m = 0; m < 4; ++m) _Pragma("unroll") for (int k = 0; k < 2; ++k) dst[m][k] = *(const PG8_LAS bf16x8*)(lds + PG8_SA(b, h) + aoff + m * 2048 + k * 1024); } while (0)
; #define PG8_WAIT_V(n) asm volatile("s_waitcnt vmcnt(" #n ")" ::: "memory")
; #define PG8_WAIT_L(n) asm volatile("s_waitcnt lgkmcnt(" #n ")" ::: "memory")
; #define PG8_BAR __builtin_amdgcn_s_barrier()
; #define PG8_SCHED __builtin_amdgcn_sched_barrier(0)
; #define PG8_MMA2(ai) PG8_MMA(ai, 0, At, B0)
; #define PG8_MMA2(ai) PG8_MMA(ai, 1, At, B1)
; #define PG8_MMA2(ai) do { PG8_MMA(ai, 0, At, B0); PG8_MMA(ai, 1, At, B1); } while (0)
;     ...
;         for (int t = 0; t < nt; t += 2) {
;             const bool last = (t == nt - 2);
;             const char* a1 = cA + (size_t)(t + 1) * kstep;
;             const char* a2 = last ? nA : cA + (size_t)(t + 2) * kstep; const char* b2 = last ? nB : cB + (size_t)(t + 2) * kstep;
;             const char* a3 = a2 + kstep; const char* b3 = b2 + kstep;
;     ...
;             PG8_LDA(At, 1, 1); PG8_STAGE(PG8_SB(1, 0), b3, voffB); PG8_STAGE(PG8_SB(1, 1), b3 + hstep, voffB); PG8_STAGE(PG8_SA(1, 0), a3, voffA);
;             PG8_WAIT_V(8); PG8_WAIT_L(0); PG8_BAR; PG8_MMA2(1); PG8_BAR; PG8_SCHED;
	s_add_i32 s16, s16, s74
	v_lshl_add_u64 v[172:173], v[172:173], 0, s[42:43]
	s_mov_b32 m0, s16
	ds_read_b128 v[200:203], v184 offset:49152
	ds_read_b128 v[208:211], v184 offset:50176
	ds_read_b128 v[214:217], v184 offset:51200
	ds_read_b128 v[218:221], v184 offset:52224
	ds_read_b128 v[222:225], v184 offset:53248
	ds_read_b128 v[226:229], v184 offset:54272
	ds_read_b128 v[230:233], v184 offset:55296
	ds_read_b128 v[234:237], v184 offset:56320
	global_load_lds_dwordx4 v[172:173], off
	s_add_i32 m0, s16, 0x2000
	s_add_u32 s34, s68, 0x40080
	v_lshl_add_u64 v[172:173], v[204:205], 0, s[42:43]
	s_addc_u32 s35, s69, 0
	s_add_i32 s16, s17, s74
	global_load_lds_dwordx4 v[172:173], off
	v_lshl_add_u64 v[172:173], s[34:35], 0, v[146:147]
	s_mov_b32 m0, s16
	s_nop 0
	global_load_lds_dwordx4 v[172:173], off
	v_lshl_add_u64 v[172:173], s[34:35], 0, v[150:151]
	s_add_i32 m0, s16, 0x2000
	s_nop 0
	global_load_lds_dwordx4 v[172:173], off
	v_lshl_add_u64 v[172:173], v[238:239], 0, s[42:43]
	s_mov_b32 m0, s83
	s_nop 0
	global_load_lds_dwordx4 v[172:173], off
	v_lshl_add_u64 v[172:173], v[240:241], 0, s[42:43]
	s_nop 0
	s_cmp_lg_u32 s67, 12
	s_cbranch_scc1 .Ldf_skipD_2
	s_mov_b32 m0, s84
	s_nop 0
	global_load_lds_dwordx4 v[172:173], off
.Ldf_skipD_2:
	s_waitcnt vmcnt(7)
	s_waitcnt lgkmcnt(0)
	s_barrier
	s_setprio 1
	s_waitcnt lgkmcnt(0)
	v_mfma_f32_16x16x32_bf16 v[60:63], v[128:131], v[200:203], v[60:63]
	v_mfma_f32_16x16x32_bf16 v[56:59], v[136:139], v[200:203], v[56:59]
	v_mfma_f32_16x16x32_bf16 v[44:47], v[128:131], v[214:217], v[44:47]
	v_mfma_f32_16x16x32_bf16 v[40:43], v[136:139], v[214:217], v[40:43]
	v_mfma_f32_16x16x32_bf16 v[28:31], v[128:131], v[222:225], v[28:31]
	v_mfma_f32_16x16x32_bf16 v[24:27], v[136:139], v[222:225], v[24:27]
	v_mfma_f32_16x16x32_bf16 v[12:15], v[128:131], v[230:233], v[12:15]
	v_mfma_f32_16x16x32_bf16 v[8:11], v[136:139], v[230:233], v[8:11]
	v_mfma_f32_16x16x32_bf16 v[60:63], v[132:135], v[208:211], v[60:63]
	v_mfma_f32_16x16x32_bf16 v[56:59], v[140:143], v[208:211], v[56:59]
	v_mfma_f32_16x16x32_bf16 v[44:47], v[132:135], v[218:221], v[44:47]
	v_mfma_f32_16x16x32_bf16 v[40:43], v[140:143], v[218:221], v[40:43]
	v_mfma_f32_16x16x32_bf16 v[28:31], v[132:135], v[226:229], v[28:31]
	v_mfma_f32_16x16x32_bf16 v[24:27], v[140:143], v[226:229], v[24:27]
	v_mfma_f32_16x16x32_bf16 v[12:15], v[132:135], v[234:237], v[12:15]
	v_mfma_f32_16x16x32_bf16 v[8:11], v[140:143], v[234:237], v[8:11]
	s_setprio 0
	s_setprio 1
	v_mfma_f32_16x16x32_bf16 v[52:55], v[168:171], v[200:203], v[52:55]
	v_mfma_f32_16x16x32_bf16 v[48:51], v[192:195], v[200:203], v[48:51]
	v_mfma_f32_16x16x32_bf16 v[36:39], v[168:171], v[214:217], v[36:39]
	v_mfma_f32_16x16x32_bf16 v[32:35], v[192:195], v[214:217], v[32:35]
	v_mfma_f32_16x16x32_bf16 v[20:23], v[168:171], v[222:225], v[20:23]
	v_mfma_f32_16x16x32_bf16 v[16:19], v[192:195], v[222:225], v[16:19]
	v_mfma_f32_16x16x32_bf16 v[4:7], v[168:171], v[230:233], v[4:7]
	v_mfma_f32_16x16x32_bf16 v[0:3], v[192:195], v[230:233], v[0:3]
	v_mfma_f32_16x16x32_bf16 v[52:55], v[188:191], v[208:211], v[52:55]
	v_mfma_f32_16x16x32_bf16 v[48:51], v[196:199], v[208:211], v[48:51]
	v_mfma_f32_16x16x32_bf16 v[36:39], v[188:191], v[218:221], v[36:39]
	v_mfma_f32_16x16x32_bf16 v[32:35], v[196:199], v[218:221], v[32:35]
	v_mfma_f32_16x16x32_bf16 v[20:23], v[188:191], v[226:229], v[20:23]
	v_mfma_f32_16x16x32_bf16 v[16:19], v[196:199], v[226:229], v[16:19]
	v_mfma_f32_16x16x32_bf16 v[4:7], v[188:191], v[234:237], v[4:7]
	v_mfma_f32_16x16x32_bf16 v[0:3], v[196:199], v[234:237], v[0:3]
	s_setprio 0
	s_barrier
	s_add_i32 s67, s67, 2
	s_add_u32 s59, s59, 0x100
	s_addc_u32 s61, s61, 0
	s_add_u32 s12, s12, 0x100
	s_addc_u32 s13, s13, 0
	s_cmp_gt_u32 s67, 13
	s_cbranch_scc0 .LBB0_454
	s_and_b64 vcc, exec, s[44:45]
	s_cbranch_vccz .LBB0_457
	s_barrier

; #define PG8_STAGE(bufoff, gbase, voff) do { _Pragma("unroll") for (int _i = 0; _i < 2; ++_i) \
;         __builtin_amdgcn_global_load_lds((const unsigned*)((const char*)(gbase) + (voff)[_i]), (PG8_LAS unsigned*)(lds + (bufoff) + ldsw + _i * 8192), 16, 0, 0); } while (0)
; #define PG8_LDA(dst, b, h) do { _Pragma("unroll") for (int m = 0; m < 4; ++m) _Pragma("unroll") for (int k = 0; k < 2; ++k) dst[m][k] = *(const PG8_LAS bf16x8*)(lds + PG8_SA(b, h) + aoff + m * 2048 + k * 1024); } while (0)
; #define PG8_LDB(dst, b, h) do { _Pragma("unroll") for (int n = 0; n < 2; ++n) _Pragma("unroll") for (int k = 0; k < 2; ++k) dst[n][k] = *(const PG8_LAS bf16x8*)(lds + PG8_SB(b, h) + boff + n * 2048 + k * 1024); } while (0)
; #define PG8_WAIT_V(n) asm volatile("s_waitcnt vmcnt(" #n ")" ::: "memory")
; #define PG8_WAIT_L(n) asm volatile("s_waitcnt lgkmcnt(" #n ")" ::: "memory")
; #define PG8_BAR __builtin_amdgcn_s_barrier()
; #define PG8_SCHED __builtin_amdgcn_sched_barrier(0)
; #define PG8_MMA2(ai) PG8_MMA(ai, 0, At, B0)
; #define PG8_MMA2(ai) PG8_MMA(ai, 1, At, B1)
; #define PG8_MMA2(ai) do { PG8_MMA(ai, 0, At, B0); PG8_MMA(ai, 1, At, B1); } while (0)
;     ...
;             const bool last = (t == nt - 2);
;             const char* a1 = cA + (size_t)(t + 1) * kstep;
;             const char* a2 = last ? nA : cA + (size_t)(t + 2) * kstep; const char* b2 = last ? nB : cB + (size_t)(t + 2) * kstep;
;             const char* a3 = a2 + kstep; const char* b3 = b2 + kstep;
;             if (last && has_next) S.a_ready(nxt);
;             if constexpr (SP2) {
;             PG8_LDB(B0, 0, 0); PG8_LDB(B1, 0, 1); PG8_SCHED; PG8_LDA(At, 0, 0); PG8_STAGE(PG8_SA(1, 1), a1 + hstep, voffA);
;             PG8_WAIT_V(8); PG8_WAIT_L(0); PG8_BAR; PG8_MMA2(0); PG8_BAR; PG8_SCHED;
;             PG8_LDA(At, 0, 1); PG8_STAGE(PG8_SB(0, 0), b2, voffB); PG8_STAGE(PG8_SB(0, 1), b2 + hstep, voffB); PG8_STAGE(PG8_SA(0, 0), a2, voffA);
;             PG8_WAIT_V(8); PG8_WAIT_L(0); PG8_BAR; PG8_MMA2(1); PG8_BAR; PG8_SCHED;
.LBB0_1123:
	s_cmp_eq_u32 s71, -2
	s_cbranch_scc1 .Ldf_skipA_3
	s_mov_b32 m0, s64
	s_nop 0
	global_load_lds_dwordx4 v[156:157], off
.Ldf_skipA_3:
	ds_read_b128 v[128:131], v161
	ds_read_b128 v[132:135], v161 offset:1024
	ds_read_b128 v[136:139], v161 offset:2048
	ds_read_b128 v[140:143], v161 offset:3072
	ds_read_b128 v[164:167], v162
	ds_read_b128 v[168:171], v162 offset:1024
	ds_read_b128 v[172:175], v162 offset:2048
	ds_read_b128 v[176:179], v162 offset:3072
	s_add_u32 s44, s42, 0x100
	s_addc_u32 s45, s43, 0
	s_cmp_eq_u32 s71, 12
	s_cselect_b32 s49, s7, s45
	s_cselect_b32 s48, s8, s44
	s_cselect_b32 s47, s9, s70
	s_cselect_b32 s46, s23, s27
	v_lshl_add_u64 v[156:157], s[42:43], 0, v[150:151]
	s_add_i32 m0, s41, 0xc000
	ds_read_b128 v[180:183], v163
	ds_read_b128 v[184:187], v163 offset:1024
	ds_read_b128 v[188:191], v163 offset:2048
	ds_read_b128 v[192:195], v163 offset:3072
	ds_read_b128 v[196:199], v163 offset:4096
	ds_read_b128 v[212:215], v163 offset:5120
	ds_read_b128 v[216:219], v163 offset:6144
	ds_read_b128 v[220:223], v163 offset:7168
	global_load_lds_dwordx4 v[156:157], off
	v_lshl_add_u64 v[156:157], s[42:43], 0, v[148:149]
	s_add_i32 m0, s41, 0xe000
	s_nop 0
	global_load_lds_dwordx4 v[156:157], off
	s_waitcnt vmcnt(8)
	s_waitcnt lgkmcnt(0)
	s_barrier
	s_setprio 1
	s_waitcnt lgkmcnt(0)
	v_mfma_f32_16x16x32_bf16 v[124:127], v[128:131], v[180:183], v[124:127]
	v_mfma_f32_16x16x32_bf16 v[120:123], v[136:139], v[180:183], v[120:123]
	v_mfma_f32_16x16x32_bf16 v[108:111], v[128:131], v[188:191], v[108:111]
	v_mfma_f32_16x16x32_bf16 v[104:107], v[136:139], v[188:191], v[104:107]
	v_mfma_f32_16x16x32_bf16 v[92:95], v[128:131], v[196:199], v[92:95]
	v_mfma_f32_16x16x32_bf16 v[88:91], v[136:139], v[196:199], v[88:91]
	v_mfma_f32_16x16x32_bf16 v[76:79], v[128:131], v[216:219], v[76:79]
	v_mfma_f32_16x16x32_bf16 v[72:75], v[136:139], v[216:219], v[72:75]
	v_mfma_f32_16x16x32_bf16 v[124:127], v[132:135], v[184:187], v[124:127]
	v_mfma_f32_16x16x32_bf16 v[120:123], v[140:143], v[184:187], v[120:123]
	v_mfma_f32_16x16x32_bf16 v[108:111], v[132:135], v[192:195], v[108:111]
	v_mfma_f32_16x16x32_bf16 v[104:107], v[140:143], v[192:195], v[104:107]
	v_mfma_f32_16x16x32_bf16 v[92:95], v[132:135], v[212:215], v[92:95]
	v_mfma_f32_16x16x32_bf16 v[88:91], v[140:143], v[212:215], v[88:91]
	v_mfma_f32_16x16x32_bf16 v[76:79], v[132:135], v[220:223], v[76:79]
	v_mfma_f32_16x16x32_bf16 v[72:75], v[140:143], v[220:223], v[72:75]
	s_setprio 0
	s_setprio 1
	v_mfma_f32_16x16x32_bf16 v[116:119], v[164:167], v[180:183], v[116:119]
	v_mfma_f32_16x16x32_bf16 v[112:115], v[172:175], v[180:183], v[112:115]
	v_mfma_f32_16x16x32_bf16 v[100:103], v[164:167], v[188:191], v[100:103]
	v_mfma_f32_16x16x32_bf16 v[96:99], v[172:175], v[188:191], v[96:99]
	v_mfma_f32_16x16x32_bf16 v[84:87], v[164:167], v[196:199], v[84:87]
	v_mfma_f32_16x16x32_bf16 v[80:83], v[172:175], v[196:199], v[80:83]
	v_mfma_f32_16x16x32_bf16 v[68:71], v[164:167], v[216:219], v[68:71]
	v_mfma_f32_16x16x32_bf16 v[64:67], v[172:175], v[216:219], v[64:67]
	v_mfma_f32_16x16x32_bf16 v[116:119], v[168:171], v[184:187], v[116:119]
	v_mfma_f32_16x16x32_bf16 v[112:115], v[176:179], v[184:187], v[112:115]
	v_mfma_f32_16x16x32_bf16 v[100:103], v[168:171], v[192:195], v[100:103]
	v_mfma_f32_16x16x32_bf16 v[96:99], v[176:179], v[192:195], v[96:99]
	v_mfma_f32_16x16x32_bf16 v[84:87], v[168:171], v[212:215], v[84:87]
	v_mfma_f32_16x16x32_bf16 v[80:83], v[176:179], v[212:215], v[80:83]
	v_mfma_f32_16x16x32_bf16 v[68:71], v[168:171], v[220:223], v[68:71]
	v_mfma_f32_16x16x32_bf16 v[64:67], v[176:179], v[220:223], v[64:67]
	s_setprio 0
	s_barrier
	s_add_i32 s16, s3, s54
	v_lshl_add_u64 v[156:157], s[46:47], 0, v[144:145]
	s_mov_b32 m0, s16
	ds_read_b128 v[180:183], v163 offset:16384
	ds_read_b128 v[184:187], v163 offset:17408
	ds_read_b128 v[188:191], v163 offset:18432
	ds_read_b128 v[192:195], v163 offset:19456
	ds_read_b128 v[196:199], v163 offset:20480
	ds_read_b128 v[212:215], v163 offset:21504
	ds_read_b128 v[216:219], v163 offset:22528
	ds_read_b128 v[220:223], v163 offset:23552
	global_load_lds_dwordx4 v[156:157], off
	s_add_i32 m0, s16, 0x2000
	s_add_u32 s16, s46, 0x40000
	v_lshl_add_u64 v[224:225], s[46:47], 0, v[146:147]
	s_addc_u32 s17, s47, 0
	s_add_i32 s34, s68, s54
	global_load_lds_dwordx4 v[224:225], off
	v_lshl_add_u64 v[226:227], s[16:17], 0, v[144:145]
	s_mov_b32 m0, s34
	v_lshl_add_u64 v[228:229], s[48:49], 0, v[146:147]
	global_load_lds_dwordx4 v[226:227], off
	v_lshl_add_u64 v[226:227], s[16:17], 0, v[146:147]
	s_add_i32 m0, s34, 0x2000
	s_nop 0
	global_load_lds_dwordx4 v[226:227], off
	v_lshl_add_u64 v[226:227], s[48:49], 0, v[144:145]
	s_mov_b32 m0, s41
	s_nop 0
	global_load_lds_dwordx4 v[226:227], off
	s_nop 0
	s_waitcnt vmcnt(7)
	s_waitcnt lgkmcnt(0)
	s_barrier
; #define PG8_STAGE(bufoff, gbase, voff) do { _Pragma("unroll") for (int _i = 0; _i < 2; ++_i) \
;         __builtin_amdgcn_global_load_lds((const unsigned*)((const char*)(gbase) + (voff)[_i]), (PG8_LAS unsigned*)(lds + (bufoff) + ldsw + _i * 8192), 16, 0, 0); } while (0)
; #define PG8_LDA(dst, b, h) do { _Pragma("unroll") for (int m = 0; m < 4; ++m) _Pragma("unroll") for (int k = 0; k < 2; ++k) dst[m][k] = *(const PG8_LAS bf16x8*)(lds + PG8_SA(b, h) + aoff + m * 2048 + k * 1024); } while (0)
; #define PG8_LDB(dst, b, h) do { _Pragma("unroll") for (int n = 0; n < 2; ++n) _Pragma("unroll") for (int k = 0; k < 2; ++k) dst[n][k] = *(const PG8_LAS bf16x8*)(lds + PG8_SB(b, h) + boff + n * 2048 + k * 1024); } while (0)
; #define PG8_WAIT_V(n) asm volatile("s_waitcnt vmcnt(" #n ")" ::: "memory")
; #define PG8_WAIT_L(n) asm volatile("s_waitcnt lgkmcnt(" #n ")" ::: "memory")
; #define PG8_BAR __builtin_amdgcn_s_barrier()
; #define PG8_SCHED __builtin_amdgcn_sched_barrier(0)
; #define PG8_MMA2(ai) PG8_MMA(ai, 0, At, B0)
; #define PG8_MMA2(ai) PG8_MMA(ai, 1, At, B1)
; #define PG8_MMA2(ai) do { PG8_MMA(ai, 0, At, B0); PG8_MMA(ai, 1, At, B1); } while (0)
;     ...
;             PG8_WAIT_V(8); PG8_WAIT_L(0); PG8_BAR; PG8_MMA2(1); PG8_BAR; PG8_SCHED;
;             PG8_LDB(B0, 1, 0); PG8_LDB(B1, 1, 1); PG8_SCHED; PG8_LDA(At, 1, 0); PG8_STAGE(PG8_SA(0, 1), a2 + hstep, voffA);
;             PG8_WAIT_V(8); PG8_WAIT_L(0); PG8_BAR; PG8_MMA2(0); PG8_BAR; PG8_SCHED;
	s_setprio 1
	s_waitcnt lgkmcnt(0)
	v_mfma_f32_16x16x32_bf16 v[60:63], v[128:131], v[180:183], v[60:63]
	v_mfma_f32_16x16x32_bf16 v[56:59], v[136:139], v[180:183], v[56:59]
	v_mfma_f32_16x16x32_bf16 v[44:47], v[128:131], v[188:191], v[44:47]
	v_mfma_f32_16x16x32_bf16 v[40:43], v[136:139], v[188:191], v[40:43]
	v_mfma_f32_16x16x32_bf16 v[28:31], v[128:131], v[196:199], v[28:31]
	v_mfma_f32_16x16x32_bf16 v[24:27], v[136:139], v[196:199], v[24:27]
	v_mfma_f32_16x16x32_bf16 v[12:15], v[128:131], v[216:219], v[12:15]
	v_mfma_f32_16x16x32_bf16 v[8:11], v[136:139], v[216:219], v[8:11]
	v_mfma_f32_16x16x32_bf16 v[60:63], v[132:135], v[184:187], v[60:63]
	v_mfma_f32_16x16x32_bf16 v[56:59], v[140:143], v[184:187], v[56:59]
	v_mfma_f32_16x16x32_bf16 v[44:47], v[132:135], v[192:195], v[44:47]
	v_mfma_f32_16x16x32_bf16 v[40:43], v[140:143], v[192:195], v[40:43]
	v_mfma_f32_16x16x32_bf16 v[28:31], v[132:135], v[212:215], v[28:31]
	v_mfma_f32_16x16x32_bf16 v[24:27], v[140:143], v[212:215], v[24:27]
	v_mfma_f32_16x16x32_bf16 v[12:15], v[132:135], v[220:223], v[12:15]
	v_mfma_f32_16x16x32_bf16 v[8:11], v[140:143], v[220:223], v[8:11]
	s_setprio 0
	s_setprio 1
	v_mfma_f32_16x16x32_bf16 v[52:55], v[164:167], v[180:183], v[52:55]
	v_mfma_f32_16x16x32_bf16 v[48:51], v[172:175], v[180:183], v[48:51]
	v_mfma_f32_16x16x32_bf16 v[36:39], v[164:167], v[188:191], v[36:39]
	v_mfma_f32_16x16x32_bf16 v[32:35], v[172:175], v[188:191], v[32:35]
	v_mfma_f32_16x16x32_bf16 v[20:23], v[164:167], v[196:199], v[20:23]
	v_mfma_f32_16x16x32_bf16 v[16:19], v[172:175], v[196:199], v[16:19]
	v_mfma_f32_16x16x32_bf16 v[4:7], v[164:167], v[216:219], v[4:7]
	v_mfma_f32_16x16x32_bf16 v[0:3], v[172:175], v[216:219], v[0:3]
	v_mfma_f32_16x16x32_bf16 v[52:55], v[168:171], v[184:187], v[52:55]
	v_mfma_f32_16x16x32_bf16 v[48:51], v[176:179], v[184:187], v[48:51]
	v_mfma_f32_16x16x32_bf16 v[36:39], v[168:171], v[192:195], v[36:39]
	v_mfma_f32_16x16x32_bf16 v[32:35], v[176:179], v[192:195], v[32:35]
	v_mfma_f32_16x16x32_bf16 v[20:23], v[168:171], v[212:215], v[20:23]
	v_mfma_f32_16x16x32_bf16 v[16:19], v[176:179], v[212:215], v[16:19]
	v_mfma_f32_16x16x32_bf16 v[4:7], v[168:171], v[220:223], v[4:7]
	v_mfma_f32_16x16x32_bf16 v[0:3], v[176:179], v[220:223], v[0:3]
	s_setprio 0
	s_barrier
	s_add_i32 s34, 0, 0x18000
	s_add_i32 s35, 0, 0x1c000
	v_add_u32_e32 v140, s34, v159
	v_add_u32_e32 v176, s35, v159
	ds_read_b128 v[128:131], v140
	ds_read_b128 v[132:135], v140 offset:1024
	ds_read_b128 v[136:139], v140 offset:2048
	ds_read_b128 v[140:143], v140 offset:3072
	ds_read_b128 v[164:167], v176
	ds_read_b128 v[168:171], v176 offset:1024
	ds_read_b128 v[172:175], v176 offset:2048
	ds_read_b128 v[176:179], v176 offset:3072
	s_add_u32 s16, s48, 0x40000
	s_addc_u32 s17, s49, 0
	s_mov_b32 m0, s55
	s_nop 0
	global_load_lds_dwordx4 v[228:229], off
	s_mov_b32 m0, s56
	v_lshl_add_u64 v[230:231], s[16:17], 0, v[144:145]
	ds_read_b128 v[180:183], v163 offset:32768
	ds_read_b128 v[184:187], v163 offset:33792
	ds_read_b128 v[188:191], v163 offset:34816
	ds_read_b128 v[192:195], v163 offset:35840
	ds_read_b128 v[196:199], v163 offset:36864
	ds_read_b128 v[212:215], v163 offset:37888
	ds_read_b128 v[216:219], v163 offset:38912
	ds_read_b128 v[220:223], v163 offset:39936
	global_load_lds_dwordx4 v[230:231], off
	v_lshl_add_u64 v[230:231], s[16:17], 0, v[146:147]
	s_mov_b32 m0, s57
	s_nop 0
	global_load_lds_dwordx4 v[230:231], off
	s_waitcnt vmcnt(8)
	s_waitcnt lgkmcnt(0)
	s_barrier
	s_setprio 1
	s_waitcnt lgkmcnt(0)
	v_mfma_f32_16x16x32_bf16 v[124:127], v[128:131], v[180:183], v[124:127]
	v_mfma_f32_16x16x32_bf16 v[120:123], v[136:139], v[180:183], v[120:123]
	v_mfma_f32_16x16x32_bf16 v[108:111], v[128:131], v[188:191], v[108:111]
	v_mfma_f32_16x16x32_bf16 v[104:107], v[136:139], v[188:191], v[104:107]
	v_mfma_f32_16x16x32_bf16 v[92:95], v[128:131], v[196:199], v[92:95]
	v_mfma_f32_16x16x32_bf16 v[88:91], v[136:139], v[196:199], v[88:91]
	v_mfma_f32_16x16x32_bf16 v[76:79], v[128:131], v[216:219], v[76:79]
	v_mfma_f32_16x16x32_bf16 v[72:75], v[136:139], v[216:219], v[72:75]
	v_mfma_f32_16x16x32_bf16 v[124:127], v[132:135], v[184:187], v[124:127]
	v_mfma_f32_16x16x32_bf16 v[120:123], v[140:143], v[184:187], v[120:123]
	v_mfma_f32_16x16x32_bf16 v[108:111], v[132:135], v[192:195], v[108:111]
	v_mfma_f32_16x16x32_bf16 v[104:107], v[140:143], v[192:195], v[104:107]
	v_mfma_f32_16x16x32_bf16 v[92:95], v[132:135], v[212:215], v[92:95]
	v_mfma_f32_16x16x32_bf16 v[88:91], v[140:143], v[212:215], v[88:91]
	v_mfma_f32_16x16x32_bf16 v[76:79], v[132:135], v[220:223], v[76:79]
	v_mfma_f32_16x16x32_bf16 v[72:75], v[140:143], v[220:223], v[72:75]
	s_setprio 0
	s_setprio 1
	v_mfma_f32_16x16x32_bf16 v[116:119], v[164:167], v[180:183], v[116:119]
	v_mfma_f32_16x16x32_bf16 v[112:115], v[172:175], v[180:183], v[112:115]
	v_mfma_f32_16x16x32_bf16 v[100:103], v[164:167], v[188:191], v[100:103]
	v_mfma_f32_16x16x32_bf16 v[96:99], v[172:175], v[188:191], v[96:99]
	v_mfma_f32_16x16x32_bf16 v[84:87], v[164:167], v[196:199], v[84:87]
	v_mfma_f32_16x16x32_bf16 v[80:83], v[172:175], v[196:199], v[80:83]
	v_mfma_f32_16x16x32_bf16 v[68:71], v[164:167], v[216:219], v[68:71]
	v_mfma_f32_16x16x32_bf16 v[64:67], v[172:175], v[216:219], v[64:67]
	v_mfma_f32_16x16x32_bf16 v[116:119], v[168:171], v[184:187], v[116:119]
	v_mfma_f32_16x16x32_bf16 v[112:115], v[176:179], v[184:187], v[112:115]
	v_mfma_f32_16x16x32_bf16 v[100:103], v[168:171], v[192:195], v[100:103]
	v_mfma_f32_16x16x32_bf16 v[96:99], v[176:179], v[192:195], v[96:99]
	v_mfma_f32_16x16x32_bf16 v[84:87], v[168:171], v[212:215], v[84:87]
	v_mfma_f32_16x16x32_bf16 v[80:83], v[176:179], v[212:215], v[80:83]
	v_mfma_f32_16x16x32_bf16 v[68:71], v[168:171], v[220:223], v[68:71]
	v_mfma_f32_16x16x32_bf16 v[64:67], v[176:179], v[220:223], v[64:67]
	s_setprio 0
	s_barrier
; #define PG8_STAGE(bufoff, gbase, voff) do { _Pragma("unroll") for (int _i = 0; _i < 2; ++_i) \
;         __builtin_amdgcn_global_load_lds((const unsigned*)((const char*)(gbase) + (voff)[_i]), (PG8_LAS unsigned*)(lds + (bufoff) + ldsw + _i * 8192), 16, 0, 0); } while (0)
; #define PG8_LDA(dst, b, h) do { _Pragma("unroll") for (int m = 0; m < 4; ++m) _Pragma("unroll") for (int k = 0; k < 2; ++k) dst[m][k] = *(const PG8_LAS bf16x8*)(lds + PG8_SA(b, h) + aoff + m * 2048 + k * 1024); } while (0)
; #define PG8_WAIT_V(n) asm volatile("s_waitcnt vmcnt(" #n ")" ::: "memory")
; #define PG8_WAIT_L(n) asm volatile("s_waitcnt lgkmcnt(" #n ")" ::: "memory")
; #define PG8_BAR __builtin_amdgcn_s_barrier()
; #define PG8_SCHED __builtin_amdgcn_sched_barrier(0)
; #define PG8_MMA2(ai) PG8_MMA(ai, 0, At, B0)
; #define PG8_MMA2(ai) PG8_MMA(ai, 1, At, B1)
; #define PG8_MMA2(ai) do { PG8_MMA(ai, 0, At, B0); PG8_MMA(ai, 1, At, B1); } while (0)
;     ...
;         for (int t = 0; t < nt; t += 2) {
;             const bool last = (t == nt - 2);
;             const char* a1 = cA + (size_t)(t + 1) * kstep;
;             const char* a2 = last ? nA : cA + (size_t)(t + 2) * kstep; const char* b2 = last ? nB : cB + (size_t)(t + 2) * kstep;
;             const char* a3 = a2 + kstep; const char* b3 = b2 + kstep;
;     ...
;             PG8_LDA(At, 1, 1); PG8_STAGE(PG8_SB(1, 0), b3, voffB); PG8_STAGE(PG8_SB(1, 1), b3 + hstep, voffB); PG8_STAGE(PG8_SA(1, 0), a3, voffA);
;             PG8_WAIT_V(8); PG8_WAIT_L(0); PG8_BAR; PG8_MMA2(1); PG8_BAR; PG8_SCHED;
	s_add_i32 s16, s34, s54
	v_lshl_add_u64 v[156:157], v[156:157], 0, s[18:19]
	s_mov_b32 m0, s16
	ds_read_b128 v[180:183], v163 offset:49152
	ds_read_b128 v[184:187], v163 offset:50176
	ds_read_b128 v[188:191], v163 offset:51200
	ds_read_b128 v[192:195], v163 offset:52224
	ds_read_b128 v[196:199], v163 offset:53248
	ds_read_b128 v[212:215], v163 offset:54272
	ds_read_b128 v[216:219], v163 offset:55296
	ds_read_b128 v[220:223], v163 offset:56320
	global_load_lds_dwordx4 v[156:157], off
	s_add_i32 m0, s16, 0x2000
	s_add_u32 s16, s46, 0x40080
	v_lshl_add_u64 v[156:157], v[224:225], 0, s[18:19]
	s_addc_u32 s17, s47, 0
	s_add_i32 s34, s35, s54
	global_load_lds_dwordx4 v[156:157], off
	v_lshl_add_u64 v[156:157], s[16:17], 0, v[144:145]
	s_mov_b32 m0, s34
	s_nop 0
	global_load_lds_dwordx4 v[156:157], off
	v_lshl_add_u64 v[156:157], s[16:17], 0, v[146:147]
	s_add_i32 m0, s34, 0x2000
	s_nop 0
	global_load_lds_dwordx4 v[156:157], off
	v_lshl_add_u64 v[156:157], v[226:227], 0, s[18:19]
	s_mov_b32 m0, s63
	s_nop 0
	global_load_lds_dwordx4 v[156:157], off
	v_lshl_add_u64 v[156:157], v[228:229], 0, s[18:19]
	s_nop 0
	s_cmp_lg_u32 s71, 12
	s_cbranch_scc1 .Ldf_skipD_3
	s_mov_b32 m0, s64
	s_nop 0
	global_load_lds_dwordx4 v[156:157], off
.Ldf_skipD_3:
	s_waitcnt vmcnt(7)
	s_waitcnt lgkmcnt(0)
	s_barrier
	s_setprio 1
	s_waitcnt lgkmcnt(0)
	v_mfma_f32_16x16x32_bf16 v[60:63], v[128:131], v[180:183], v[60:63]
	v_mfma_f32_16x16x32_bf16 v[56:59], v[136:139], v[180:183], v[56:59]
	v_mfma_f32_16x16x32_bf16 v[44:47], v[128:131], v[188:191], v[44:47]
	v_mfma_f32_16x16x32_bf16 v[40:43], v[136:139], v[188:191], v[40:43]
	v_mfma_f32_16x16x32_bf16 v[28:31], v[128:131], v[196:199], v[28:31]
	v_mfma_f32_16x16x32_bf16 v[24:27], v[136:139], v[196:199], v[24:27]
	v_mfma_f32_16x16x32_bf16 v[12:15], v[128:131], v[216:219], v[12:15]
	v_mfma_f32_16x16x32_bf16 v[8:11], v[136:139], v[216:219], v[8:11]
	v_mfma_f32_16x16x32_bf16 v[60:63], v[132:135], v[184:187], v[60:63]
	v_mfma_f32_16x16x32_bf16 v[56:59], v[140:143], v[184:187], v[56:59]
	v_mfma_f32_16x16x32_bf16 v[44:47], v[132:135], v[192:195], v[44:47]
	v_mfma_f32_16x16x32_bf16 v[40:43], v[140:143], v[192:195], v[40:43]
	v_mfma_f32_16x16x32_bf16 v[28:31], v[132:135], v[212:215], v[28:31]
	v_mfma_f32_16x16x32_bf16 v[24:27], v[140:143], v[212:215], v[24:27]
	v_mfma_f32_16x16x32_bf16 v[12:15], v[132:135], v[220:223], v[12:15]
	v_mfma_f32_16x16x32_bf16 v[8:11], v[140:143], v[220:223], v[8:11]
	s_setprio 0
	s_setprio 1
	v_mfma_f32_16x16x32_bf16 v[52:55], v[164:167], v[180:183], v[52:55]
	v_mfma_f32_16x16x32_bf16 v[48:51], v[172:175], v[180:183], v[48:51]
	v_mfma_f32_16x16x32_bf16 v[36:39], v[164:167], v[188:191], v[36:39]
	v_mfma_f32_16x16x32_bf16 v[32:35], v[172:175], v[188:191], v[32:35]
	v_mfma_f32_16x16x32_bf16 v[20:23], v[164:167], v[196:199], v[20:23]
	v_mfma_f32_16x16x32_bf16 v[16:19], v[172:175], v[196:199], v[16:19]
	v_mfma_f32_16x16x32_bf16 v[4:7], v[164:167], v[216:219], v[4:7]
	v_mfma_f32_16x16x32_bf16 v[0:3], v[172:175], v[216:219], v[0:3]
	v_mfma_f32_16x16x32_bf16 v[52:55], v[168:171], v[184:187], v[52:55]
	v_mfma_f32_16x16x32_bf16 v[48:51], v[176:179], v[184:187], v[48:51]
	v_mfma_f32_16x16x32_bf16 v[36:39], v[168:171], v[192:195], v[36:39]
	v_mfma_f32_16x16x32_bf16 v[32:35], v[176:179], v[192:195], v[32:35]
	v_mfma_f32_16x16x32_bf16 v[20:23], v[168:171], v[212:215], v[20:23]
	v_mfma_f32_16x16x32_bf16 v[16:19], v[176:179], v[212:215], v[16:19]
	v_mfma_f32_16x16x32_bf16 v[4:7], v[168:171], v[220:223], v[4:7]
	v_mfma_f32_16x16x32_bf16 v[0:3], v[176:179], v[220:223], v[0:3]
	s_setprio 0
	s_barrier
	s_add_i32 s71, s71, 2
	s_add_u32 s27, s27, 0x100
	s_addc_u32 s70, s70, 0
	s_cmp_gt_u32 s71, 13
	s_mov_b64 s[42:43], s[44:45]
	s_cbranch_scc0 .LBB0_1123
	s_and_b64 vcc, exec, s[20:21]
	s_cbranch_vccz .LBB0_1126
	s_barrier

; #define PG8_STAGE(bufoff, gbase, voff) do { _Pragma("unroll") for (int _i = 0; _i < 2; ++_i) \
;         __builtin_amdgcn_global_load_lds((const unsigned*)((const char*)(gbase) + (voff)[_i]), (PG8_LAS unsigned*)(lds + (bufoff) + ldsw + _i * 8192), 16, 0, 0); } while (0)
; #define PG8_LDA(dst, b, h) do { _Pragma("unroll") for (int m = 0; m < 4; ++m) _Pragma("unroll") for (int k = 0; k < 2; ++k) dst[m][k] = *(const PG8_LAS bf16x8*)(lds + PG8_SA(b, h) + aoff + m * 2048 + k * 1024); } while (0)
; #define PG8_LDB(dst, b, h) do { _Pragma("unroll") for (int n = 0; n < 2; ++n) _Pragma("unroll") for (int k = 0; k < 2; ++k) dst[n][k] = *(const PG8_LAS bf16x8*)(lds + PG8_SB(b, h) + boff + n * 2048 + k * 1024); } while (0)
; #define PG8_WAIT_V(n) asm volatile("s_waitcnt vmcnt(" #n ")" ::: "memory")
; #define PG8_WAIT_L(n) asm volatile("s_waitcnt lgkmcnt(" #n ")" ::: "memory")
; #define PG8_BAR __builtin_amdgcn_s_barrier()
; #define PG8_SCHED __builtin_amdgcn_sched_barrier(0)
; #define PG8_MMA2(ai) PG8_MMA(ai, 0, At, B0)
; #define PG8_MMA2(ai) PG8_MMA(ai, 1, At, B1)
; #define PG8_MMA2(ai) do { PG8_MMA(ai, 0, At, B0); PG8_MMA(ai, 1, At, B1); } while (0)
;     ...
;             const bool last = (t == nt - 2);
;             const char* a1 = cA + (size_t)(t + 1) * kstep;
;             const char* a2 = last ? nA : cA + (size_t)(t + 2) * kstep; const char* b2 = last ? nB : cB + (size_t)(t + 2) * kstep;
;             const char* a3 = a2 + kstep; const char* b3 = b2 + kstep;
;             if (last && has_next) S.a_ready(nxt);
;             if constexpr (SP2) {
;             PG8_LDB(B0, 0, 0); PG8_LDB(B1, 0, 1); PG8_SCHED; PG8_LDA(At, 0, 0); PG8_STAGE(PG8_SA(1, 1), a1 + hstep, voffA);
;             PG8_WAIT_V(8); PG8_WAIT_L(0); PG8_BAR; PG8_MMA2(0); PG8_BAR; PG8_SCHED;
;             PG8_LDA(At, 0, 1); PG8_STAGE(PG8_SB(0, 0), b2, voffB); PG8_STAGE(PG8_SB(0, 1), b2 + hstep, voffB); PG8_STAGE(PG8_SA(0, 0), a2, voffA);
;             PG8_WAIT_V(8); PG8_WAIT_L(0); PG8_BAR; PG8_MMA2(1); PG8_BAR; PG8_SCHED;
.LBB0_1263:
	s_cmp_eq_u32 s64, -2
	s_cbranch_scc1 .Ldf_skipA_4
	s_mov_b32 m0, s58
	s_nop 0
	global_load_lds_dwordx4 v[144:145], off
.Ldf_skipA_4:
	ds_read_b128 v[152:155], v149
	ds_read_b128 v[156:159], v149 offset:1024
	ds_read_b128 v[160:163], v149 offset:2048
	ds_read_b128 v[164:167], v149 offset:3072
	ds_read_b128 v[168:171], v150
	ds_read_b128 v[172:175], v150 offset:1024
	ds_read_b128 v[176:179], v150 offset:2048
	ds_read_b128 v[180:183], v150 offset:3072
	s_add_u32 s34, s42, 0xfffc0080
	s_addc_u32 s35, s43, -1
	s_cmp_eq_u32 s64, 12
	s_cselect_b32 s47, s7, s35
	s_cselect_b32 s46, s8, s34
	s_cselect_b32 s45, s9, s63
	s_cselect_b32 s44, s23, s27
	v_lshl_add_u64 v[144:145], s[42:43], 0, v[138:139]
	s_add_i32 m0, s41, 0xc000
	ds_read_b128 v[184:187], v151
	ds_read_b128 v[188:191], v151 offset:1024
	ds_read_b128 v[192:195], v151 offset:2048
	ds_read_b128 v[196:199], v151 offset:3072
	ds_read_b128 v[212:215], v151 offset:4096
	ds_read_b128 v[216:219], v151 offset:5120
	ds_read_b128 v[220:223], v151 offset:6144
	ds_read_b128 v[224:227], v151 offset:7168
	global_load_lds_dwordx4 v[144:145], off
	v_lshl_add_u64 v[144:145], s[42:43], 0, v[136:137]
	s_add_i32 m0, s41, 0xe000
	s_nop 0
	global_load_lds_dwordx4 v[144:145], off
	s_waitcnt vmcnt(8)
	s_waitcnt lgkmcnt(0)
	s_barrier
	s_setprio 1
	s_waitcnt lgkmcnt(0)
	v_mfma_f32_16x16x32_bf16 v[124:127], v[152:155], v[184:187], v[124:127]
	v_mfma_f32_16x16x32_bf16 v[120:123], v[160:163], v[184:187], v[120:123]
	v_mfma_f32_16x16x32_bf16 v[108:111], v[152:155], v[192:195], v[108:111]
	v_mfma_f32_16x16x32_bf16 v[104:107], v[160:163], v[192:195], v[104:107]
	v_mfma_f32_16x16x32_bf16 v[92:95], v[152:155], v[212:215], v[92:95]
	v_mfma_f32_16x16x32_bf16 v[88:91], v[160:163], v[212:215], v[88:91]
	v_mfma_f32_16x16x32_bf16 v[76:79], v[152:155], v[220:223], v[76:79]
	v_mfma_f32_16x16x32_bf16 v[72:75], v[160:163], v[220:223], v[72:75]
	v_mfma_f32_16x16x32_bf16 v[124:127], v[156:159], v[188:191], v[124:127]
	v_mfma_f32_16x16x32_bf16 v[120:123], v[164:167], v[188:191], v[120:123]
	v_mfma_f32_16x16x32_bf16 v[108:111], v[156:159], v[196:199], v[108:111]
	v_mfma_f32_16x16x32_bf16 v[104:107], v[164:167], v[196:199], v[104:107]
	v_mfma_f32_16x16x32_bf16 v[92:95], v[156:159], v[216:219], v[92:95]
	v_mfma_f32_16x16x32_bf16 v[88:91], v[164:167], v[216:219], v[88:91]
	v_mfma_f32_16x16x32_bf16 v[76:79], v[156:159], v[224:227], v[76:79]
	v_mfma_f32_16x16x32_bf16 v[72:75], v[164:167], v[224:227], v[72:75]
	s_setprio 0
	s_setprio 1
	v_mfma_f32_16x16x32_bf16 v[116:119], v[168:171], v[184:187], v[116:119]
	v_mfma_f32_16x16x32_bf16 v[112:115], v[176:179], v[184:187], v[112:115]
	v_mfma_f32_16x16x32_bf16 v[100:103], v[168:171], v[192:195], v[100:103]
	v_mfma_f32_16x16x32_bf16 v[96:99], v[176:179], v[192:195], v[96:99]
	v_mfma_f32_16x16x32_bf16 v[84:87], v[168:171], v[212:215], v[84:87]
	v_mfma_f32_16x16x32_bf16 v[80:83], v[176:179], v[212:215], v[80:83]
	v_mfma_f32_16x16x32_bf16 v[68:71], v[168:171], v[220:223], v[68:71]
	v_mfma_f32_16x16x32_bf16 v[64:67], v[176:179], v[220:223], v[64:67]
	v_mfma_f32_16x16x32_bf16 v[116:119], v[172:175], v[188:191], v[116:119]
	v_mfma_f32_16x16x32_bf16 v[112:115], v[180:183], v[188:191], v[112:115]
	v_mfma_f32_16x16x32_bf16 v[100:103], v[172:175], v[196:199], v[100:103]
	v_mfma_f32_16x16x32_bf16 v[96:99], v[180:183], v[196:199], v[96:99]
	v_mfma_f32_16x16x32_bf16 v[84:87], v[172:175], v[216:219], v[84:87]
	v_mfma_f32_16x16x32_bf16 v[80:83], v[180:183], v[216:219], v[80:83]
	v_mfma_f32_16x16x32_bf16 v[68:71], v[172:175], v[224:227], v[68:71]
	v_mfma_f32_16x16x32_bf16 v[64:67], v[180:183], v[224:227], v[64:67]
	s_setprio 0
	s_barrier
	s_add_i32 s34, s3, s52
	v_lshl_add_u64 v[144:145], s[44:45], 0, v[130:131]
	s_mov_b32 m0, s34
	ds_read_b128 v[184:187], v151 offset:16384
	ds_read_b128 v[188:191], v151 offset:17408
	ds_read_b128 v[192:195], v151 offset:18432
	ds_read_b128 v[196:199], v151 offset:19456
	ds_read_b128 v[212:215], v151 offset:20480
	ds_read_b128 v[216:219], v151 offset:21504
	ds_read_b128 v[220:223], v151 offset:22528
	ds_read_b128 v[224:227], v151 offset:23552
	global_load_lds_dwordx4 v[144:145], off
	s_add_i32 m0, s34, 0x2000
	s_add_u32 s34, s44, 0x40000
	v_lshl_add_u64 v[228:229], s[44:45], 0, v[134:135]
	s_addc_u32 s35, s45, 0
	s_add_i32 s65, s61, s52
	global_load_lds_dwordx4 v[228:229], off
	v_lshl_add_u64 v[230:231], s[34:35], 0, v[130:131]
	s_mov_b32 m0, s65
	v_lshl_add_u64 v[232:233], s[46:47], 0, v[132:133]
	global_load_lds_dwordx4 v[230:231], off
	v_lshl_add_u64 v[230:231], s[34:35], 0, v[134:135]
	s_add_i32 m0, s65, 0x2000
	s_nop 0
	global_load_lds_dwordx4 v[230:231], off
	v_lshl_add_u64 v[230:231], s[46:47], 0, v[128:129]
	s_mov_b32 m0, s41
	s_nop 0
	global_load_lds_dwordx4 v[230:231], off
	s_nop 0
	s_waitcnt vmcnt(7)
	s_waitcnt lgkmcnt(0)
	s_barrier
; #define PG8_STAGE(bufoff, gbase, voff) do { _Pragma("unroll") for (int _i = 0; _i < 2; ++_i) \
;         __builtin_amdgcn_global_load_lds((const unsigned*)((const char*)(gbase) + (voff)[_i]), (PG8_LAS unsigned*)(lds + (bufoff) + ldsw + _i * 8192), 16, 0, 0); } while (0)
; #define PG8_LDA(dst, b, h) do { _Pragma("unroll") for (int m = 0; m < 4; ++m) _Pragma("unroll") for (int k = 0; k < 2; ++k) dst[m][k] = *(const PG8_LAS bf16x8*)(lds + PG8_SA(b, h) + aoff + m * 2048 + k * 1024); } while (0)
; #define PG8_LDB(dst, b, h) do { _Pragma("unroll") for (int n = 0; n < 2; ++n) _Pragma("unroll") for (int k = 0; k < 2; ++k) dst[n][k] = *(const PG8_LAS bf16x8*)(lds + PG8_SB(b, h) + boff + n * 2048 + k * 1024); } while (0)
; #define PG8_WAIT_V(n) asm volatile("s_waitcnt vmcnt(" #n ")" ::: "memory")
; #define PG8_WAIT_L(n) asm volatile("s_waitcnt lgkmcnt(" #n ")" ::: "memory")
; #define PG8_BAR __builtin_amdgcn_s_barrier()
; #define PG8_SCHED __builtin_amdgcn_sched_barrier(0)
; #define PG8_MMA2(ai) PG8_MMA(ai, 0, At, B0)
; #define PG8_MMA2(ai) PG8_MMA(ai, 1, At, B1)
; #define PG8_MMA2(ai) do { PG8_MMA(ai, 0, At, B0); PG8_MMA(ai, 1, At, B1); } while (0)
;     ...
;             PG8_WAIT_V(8); PG8_WAIT_L(0); PG8_BAR; PG8_MMA2(1); PG8_BAR; PG8_SCHED;
;             PG8_LDB(B0, 1, 0); PG8_LDB(B1, 1, 1); PG8_SCHED; PG8_LDA(At, 1, 0); PG8_STAGE(PG8_SA(0, 1), a2 + hstep, voffA);
;             PG8_WAIT_V(8); PG8_WAIT_L(0); PG8_BAR; PG8_MMA2(0); PG8_BAR; PG8_SCHED;
	s_setprio 1
	s_waitcnt lgkmcnt(0)
	v_mfma_f32_16x16x32_bf16 v[60:63], v[152:155], v[184:187], v[60:63]
	v_mfma_f32_16x16x32_bf16 v[56:59], v[160:163], v[184:187], v[56:59]
	v_mfma_f32_16x16x32_bf16 v[44:47], v[152:155], v[192:195], v[44:47]
	v_mfma_f32_16x16x32_bf16 v[40:43], v[160:163], v[192:195], v[40:43]
	v_mfma_f32_16x16x32_bf16 v[28:31], v[152:155], v[212:215], v[28:31]
	v_mfma_f32_16x16x32_bf16 v[24:27], v[160:163], v[212:215], v[24:27]
	v_mfma_f32_16x16x32_bf16 v[12:15], v[152:155], v[220:223], v[12:15]
	v_mfma_f32_16x16x32_bf16 v[8:11], v[160:163], v[220:223], v[8:11]
	v_mfma_f32_16x16x32_bf16 v[60:63], v[156:159], v[188:191], v[60:63]
	v_mfma_f32_16x16x32_bf16 v[56:59], v[164:167], v[188:191], v[56:59]
	v_mfma_f32_16x16x32_bf16 v[44:47], v[156:159], v[196:199], v[44:47]
	v_mfma_f32_16x16x32_bf16 v[40:43], v[164:167], v[196:199], v[40:43]
	v_mfma_f32_16x16x32_bf16 v[28:31], v[156:159], v[216:219], v[28:31]
	v_mfma_f32_16x16x32_bf16 v[24:27], v[164:167], v[216:219], v[24:27]
	v_mfma_f32_16x16x32_bf16 v[12:15], v[156:159], v[224:227], v[12:15]
	v_mfma_f32_16x16x32_bf16 v[8:11], v[164:167], v[224:227], v[8:11]
	s_setprio 0
	s_setprio 1
	v_mfma_f32_16x16x32_bf16 v[52:55], v[168:171], v[184:187], v[52:55]
	v_mfma_f32_16x16x32_bf16 v[48:51], v[176:179], v[184:187], v[48:51]
	v_mfma_f32_16x16x32_bf16 v[36:39], v[168:171], v[192:195], v[36:39]
	v_mfma_f32_16x16x32_bf16 v[32:35], v[176:179], v[192:195], v[32:35]
	v_mfma_f32_16x16x32_bf16 v[20:23], v[168:171], v[212:215], v[20:23]
	v_mfma_f32_16x16x32_bf16 v[16:19], v[176:179], v[212:215], v[16:19]
	v_mfma_f32_16x16x32_bf16 v[4:7], v[168:171], v[220:223], v[4:7]
	v_mfma_f32_16x16x32_bf16 v[0:3], v[176:179], v[220:223], v[0:3]
	v_mfma_f32_16x16x32_bf16 v[52:55], v[172:175], v[188:191], v[52:55]
	v_mfma_f32_16x16x32_bf16 v[48:51], v[180:183], v[188:191], v[48:51]
	v_mfma_f32_16x16x32_bf16 v[36:39], v[172:175], v[196:199], v[36:39]
	v_mfma_f32_16x16x32_bf16 v[32:35], v[180:183], v[196:199], v[32:35]
	v_mfma_f32_16x16x32_bf16 v[20:23], v[172:175], v[216:219], v[20:23]
	v_mfma_f32_16x16x32_bf16 v[16:19], v[180:183], v[216:219], v[16:19]
	v_mfma_f32_16x16x32_bf16 v[4:7], v[172:175], v[224:227], v[4:7]
	v_mfma_f32_16x16x32_bf16 v[0:3], v[180:183], v[224:227], v[0:3]
	s_setprio 0
	s_barrier
	s_add_i32 s65, 0, 0x18000
	s_add_i32 s66, 0, 0x1c000
	v_add_u32_e32 v164, s65, v147
	v_add_u32_e32 v180, s66, v147
	ds_read_b128 v[152:155], v164
	ds_read_b128 v[156:159], v164 offset:1024
	ds_read_b128 v[160:163], v164 offset:2048
	ds_read_b128 v[164:167], v164 offset:3072
	ds_read_b128 v[168:171], v180
	ds_read_b128 v[172:175], v180 offset:1024
	ds_read_b128 v[176:179], v180 offset:2048
	ds_read_b128 v[180:183], v180 offset:3072
	s_add_u32 s34, s46, 0x40000
	s_addc_u32 s35, s47, 0
	s_mov_b32 m0, s53
	s_nop 0
	global_load_lds_dwordx4 v[232:233], off
	s_mov_b32 m0, s54
	v_lshl_add_u64 v[234:235], s[34:35], 0, v[128:129]
	ds_read_b128 v[184:187], v151 offset:32768
	ds_read_b128 v[188:191], v151 offset:33792
	ds_read_b128 v[192:195], v151 offset:34816
	ds_read_b128 v[196:199], v151 offset:35840
	ds_read_b128 v[212:215], v151 offset:36864
	ds_read_b128 v[216:219], v151 offset:37888
	ds_read_b128 v[220:223], v151 offset:38912
	ds_read_b128 v[224:227], v151 offset:39936
	global_load_lds_dwordx4 v[234:235], off
	v_lshl_add_u64 v[234:235], s[34:35], 0, v[132:133]
	s_mov_b32 m0, s55
	s_nop 0
	global_load_lds_dwordx4 v[234:235], off
	s_waitcnt vmcnt(8)
	s_waitcnt lgkmcnt(0)
	s_barrier
	s_setprio 1
	s_waitcnt lgkmcnt(0)
	v_mfma_f32_16x16x32_bf16 v[124:127], v[152:155], v[184:187], v[124:127]
	v_mfma_f32_16x16x32_bf16 v[120:123], v[160:163], v[184:187], v[120:123]
	v_mfma_f32_16x16x32_bf16 v[108:111], v[152:155], v[192:195], v[108:111]
	v_mfma_f32_16x16x32_bf16 v[104:107], v[160:163], v[192:195], v[104:107]
	v_mfma_f32_16x16x32_bf16 v[92:95], v[152:155], v[212:215], v[92:95]
	v_mfma_f32_16x16x32_bf16 v[88:91], v[160:163], v[212:215], v[88:91]
	v_mfma_f32_16x16x32_bf16 v[76:79], v[152:155], v[220:223], v[76:79]
	v_mfma_f32_16x16x32_bf16 v[72:75], v[160:163], v[220:223], v[72:75]
	v_mfma_f32_16x16x32_bf16 v[124:127], v[156:159], v[188:191], v[124:127]
	v_mfma_f32_16x16x32_bf16 v[120:123], v[164:167], v[188:191], v[120:123]
	v_mfma_f32_16x16x32_bf16 v[108:111], v[156:159], v[196:199], v[108:111]
	v_mfma_f32_16x16x32_bf16 v[104:107], v[164:167], v[196:199], v[104:107]
	v_mfma_f32_16x16x32_bf16 v[92:95], v[156:159], v[216:219], v[92:95]
	v_mfma_f32_16x16x32_bf16 v[88:91], v[164:167], v[216:219], v[88:91]
	v_mfma_f32_16x16x32_bf16 v[76:79], v[156:159], v[224:227], v[76:79]
	v_mfma_f32_16x16x32_bf16 v[72:75], v[164:167], v[224:227], v[72:75]
	s_setprio 0
	s_setprio 1
	v_mfma_f32_16x16x32_bf16 v[116:119], v[168:171], v[184:187], v[116:119]
	v_mfma_f32_16x16x32_bf16 v[112:115], v[176:179], v[184:187], v[112:115]
	v_mfma_f32_16x16x32_bf16 v[100:103], v[168:171], v[192:195], v[100:103]
	v_mfma_f32_16x16x32_bf16 v[96:99], v[176:179], v[192:195], v[96:99]
	v_mfma_f32_16x16x32_bf16 v[84:87], v[168:171], v[212:215], v[84:87]
	v_mfma_f32_16x16x32_bf16 v[80:83], v[176:179], v[212:215], v[80:83]
	v_mfma_f32_16x16x32_bf16 v[68:71], v[168:171], v[220:223], v[68:71]
	v_mfma_f32_16x16x32_bf16 v[64:67], v[176:179], v[220:223], v[64:67]
	v_mfma_f32_16x16x32_bf16 v[116:119], v[172:175], v[188:191], v[116:119]
	v_mfma_f32_16x16x32_bf16 v[112:115], v[180:183], v[188:191], v[112:115]
	v_mfma_f32_16x16x32_bf16 v[100:103], v[172:175], v[196:199], v[100:103]
	v_mfma_f32_16x16x32_bf16 v[96:99], v[180:183], v[196:199], v[96:99]
	v_mfma_f32_16x16x32_bf16 v[84:87], v[172:175], v[216:219], v[84:87]
	v_mfma_f32_16x16x32_bf16 v[80:83], v[180:183], v[216:219], v[80:83]
	v_mfma_f32_16x16x32_bf16 v[68:71], v[172:175], v[224:227], v[68:71]
	v_mfma_f32_16x16x32_bf16 v[64:67], v[180:183], v[224:227], v[64:67]
	s_setprio 0
	s_barrier
; #define PG8_STAGE(bufoff, gbase, voff) do { _Pragma("unroll") for (int _i = 0; _i < 2; ++_i) \
;         __builtin_amdgcn_global_load_lds((const unsigned*)((const char*)(gbase) + (voff)[_i]), (PG8_LAS unsigned*)(lds + (bufoff) + ldsw + _i * 8192), 16, 0, 0); } while (0)
; #define PG8_LDA(dst, b, h) do { _Pragma("unroll") for (int m = 0; m < 4; ++m) _Pragma("unroll") for (int k = 0; k < 2; ++k) dst[m][k] = *(const PG8_LAS bf16x8*)(lds + PG8_SA(b, h) + aoff + m * 2048 + k * 1024); } while (0)
; #define PG8_WAIT_V(n) asm volatile("s_waitcnt vmcnt(" #n ")" ::: "memory")
; #define PG8_WAIT_L(n) asm volatile("s_waitcnt lgkmcnt(" #n ")" ::: "memory")
; #define PG8_BAR __builtin_amdgcn_s_barrier()
; #define PG8_SCHED __builtin_amdgcn_sched_barrier(0)
; #define PG8_MMA2(ai) PG8_MMA(ai, 0, At, B0)
; #define PG8_MMA2(ai) PG8_MMA(ai, 1, At, B1)
; #define PG8_MMA2(ai) do { PG8_MMA(ai, 0, At, B0); PG8_MMA(ai, 1, At, B1); } while (0)
;     ...
;         for (int t = 0; t < nt; t += 2) {
;             const bool last = (t == nt - 2);
;             const char* a1 = cA + (size_t)(t + 1) * kstep;
;             const char* a2 = last ? nA : cA + (size_t)(t + 2) * kstep; const char* b2 = last ? nB : cB + (size_t)(t + 2) * kstep;
;             const char* a3 = a2 + kstep; const char* b3 = b2 + kstep;
;     ...
;             PG8_LDA(At, 1, 1); PG8_STAGE(PG8_SB(1, 0), b3, voffB); PG8_STAGE(PG8_SB(1, 1), b3 + hstep, voffB); PG8_STAGE(PG8_SA(1, 0), a3, voffA);
;             PG8_WAIT_V(8); PG8_WAIT_L(0); PG8_BAR; PG8_MMA2(1); PG8_BAR; PG8_SCHED;
	s_add_i32 s34, s65, s52
	v_lshl_add_u64 v[144:145], v[144:145], 0, s[18:19]
	s_mov_b32 m0, s34
	ds_read_b128 v[184:187], v151 offset:49152
	ds_read_b128 v[188:191], v151 offset:50176
	ds_read_b128 v[192:195], v151 offset:51200
	ds_read_b128 v[196:199], v151 offset:52224
	ds_read_b128 v[212:215], v151 offset:53248
	ds_read_b128 v[216:219], v151 offset:54272
	ds_read_b128 v[220:223], v151 offset:55296
	ds_read_b128 v[224:227], v151 offset:56320
	global_load_lds_dwordx4 v[144:145], off
	s_add_i32 m0, s34, 0x2000
	s_add_u32 s34, s44, 0x40080
	v_lshl_add_u64 v[144:145], v[228:229], 0, s[18:19]
	s_addc_u32 s35, s45, 0
	s_add_i32 s44, s66, s52
	global_load_lds_dwordx4 v[144:145], off
	v_lshl_add_u64 v[144:145], s[34:35], 0, v[130:131]
	s_mov_b32 m0, s44
	s_nop 0
	global_load_lds_dwordx4 v[144:145], off
	v_lshl_add_u64 v[144:145], s[34:35], 0, v[134:135]
	s_add_i32 m0, s44, 0x2000
	s_nop 0
	global_load_lds_dwordx4 v[144:145], off
	v_lshl_add_u64 v[144:145], v[230:231], 0, s[18:19]
	s_mov_b32 m0, s57
	s_nop 0
	global_load_lds_dwordx4 v[144:145], off
	v_lshl_add_u64 v[144:145], v[232:233], 0, s[18:19]
	s_nop 0
	s_cmp_lg_u32 s64, 12
	s_cbranch_scc1 .Ldf_skipD_4
	s_mov_b32 m0, s58
	s_nop 0
	global_load_lds_dwordx4 v[144:145], off
.Ldf_skipD_4:
	s_waitcnt vmcnt(7)
	s_waitcnt lgkmcnt(0)
	s_barrier
	s_setprio 1
	s_waitcnt lgkmcnt(0)
	v_mfma_f32_16x16x32_bf16 v[60:63], v[152:155], v[184:187], v[60:63]
	v_mfma_f32_16x16x32_bf16 v[56:59], v[160:163], v[184:187], v[56:59]
	v_mfma_f32_16x16x32_bf16 v[44:47], v[152:155], v[192:195], v[44:47]
	v_mfma_f32_16x16x32_bf16 v[40:43], v[160:163], v[192:195], v[40:43]
	v_mfma_f32_16x16x32_bf16 v[28:31], v[152:155], v[212:215], v[28:31]
	v_mfma_f32_16x16x32_bf16 v[24:27], v[160:163], v[212:215], v[24:27]
	v_mfma_f32_16x16x32_bf16 v[12:15], v[152:155], v[220:223], v[12:15]
	v_mfma_f32_16x16x32_bf16 v[8:11], v[160:163], v[220:223], v[8:11]
	v_mfma_f32_16x16x32_bf16 v[60:63], v[156:159], v[188:191], v[60:63]
	v_mfma_f32_16x16x32_bf16 v[56:59], v[164:167], v[188:191], v[56:59]
	v_mfma_f32_16x16x32_bf16 v[44:47], v[156:159], v[196:199], v[44:47]
	v_mfma_f32_16x16x32_bf16 v[40:43], v[164:167], v[196:199], v[40:43]
	v_mfma_f32_16x16x32_bf16 v[28:31], v[156:159], v[216:219], v[28:31]
	v_mfma_f32_16x16x32_bf16 v[24:27], v[164:167], v[216:219], v[24:27]
	v_mfma_f32_16x16x32_bf16 v[12:15], v[156:159], v[224:227], v[12:15]
	v_mfma_f32_16x16x32_bf16 v[8:11], v[164:167], v[224:227], v[8:11]
	s_setprio 0
	s_setprio 1
	v_mfma_f32_16x16x32_bf16 v[52:55], v[168:171], v[184:187], v[52:55]
	v_mfma_f32_16x16x32_bf16 v[48:51], v[176:179], v[184:187], v[48:51]
	v_mfma_f32_16x16x32_bf16 v[36:39], v[168:171], v[192:195], v[36:39]
	v_mfma_f32_16x16x32_bf16 v[32:35], v[176:179], v[192:195], v[32:35]
	v_mfma_f32_16x16x32_bf16 v[20:23], v[168:171], v[212:215], v[20:23]
	v_mfma_f32_16x16x32_bf16 v[16:19], v[176:179], v[212:215], v[16:19]
	v_mfma_f32_16x16x32_bf16 v[4:7], v[168:171], v[220:223], v[4:7]
	v_mfma_f32_16x16x32_bf16 v[0:3], v[176:179], v[220:223], v[0:3]
	v_mfma_f32_16x16x32_bf16 v[52:55], v[172:175], v[188:191], v[52:55]
	v_mfma_f32_16x16x32_bf16 v[48:51], v[180:183], v[188:191], v[48:51]
	v_mfma_f32_16x16x32_bf16 v[36:39], v[172:175], v[196:199], v[36:39]
	v_mfma_f32_16x16x32_bf16 v[32:35], v[180:183], v[196:199], v[32:35]
	v_mfma_f32_16x16x32_bf16 v[20:23], v[172:175], v[216:219], v[20:23]
	v_mfma_f32_16x16x32_bf16 v[16:19], v[180:183], v[216:219], v[16:19]
	v_mfma_f32_16x16x32_bf16 v[4:7], v[172:175], v[224:227], v[4:7]
	v_mfma_f32_16x16x32_bf16 v[0:3], v[180:183], v[224:227], v[0:3]
	s_setprio 0
	s_barrier
	s_add_i32 s64, s64, 2
	s_add_u32 s27, s27, 0x100
	s_addc_u32 s63, s63, 0
	s_add_u32 s42, s42, 0x100
	s_addc_u32 s43, s43, 0
	s_cmp_gt_u32 s64, 13
	s_cbranch_scc0 .LBB0_1263
	s_and_b64 vcc, exec, s[20:21]
	s_cbranch_vccz .LBB0_1266
	s_barrier

; #define PG8_STAGE(bufoff, gbase, voff) do { _Pragma("unroll") for (int _i = 0; _i < 2; ++_i) \
;         __builtin_amdgcn_global_load_lds((const unsigned*)((const char*)(gbase) + (voff)[_i]), (PG8_LAS unsigned*)(lds + (bufoff) + ldsw + _i * 8192), 16, 0, 0); } while (0)
; #define PG8_LDA(dst, b, h) do { _Pragma("unroll") for (int m = 0; m < 4; ++m) _Pragma("unroll") for (int k = 0; k < 2; ++k) dst[m][k] = *(const PG8_LAS bf16x8*)(lds + PG8_SA(b, h) + aoff + m * 2048 + k * 1024); } while (0)
; #define PG8_LDB(dst, b, h) do { _Pragma("unroll") for (int n = 0; n < 2; ++n) _Pragma("unroll") for (int k = 0; k < 2; ++k) dst[n][k] = *(const PG8_LAS bf16x8*)(lds + PG8_SB(b, h) + boff + n * 2048 + k * 1024); } while (0)
; #define PG8_WAIT_V(n) asm volatile("s_waitcnt vmcnt(" #n ")" ::: "memory")
; #define PG8_WAIT_L(n) asm volatile("s_waitcnt lgkmcnt(" #n ")" ::: "memory")
; #define PG8_BAR __builtin_amdgcn_s_barrier()
; #define PG8_SCHED __builtin_amdgcn_sched_barrier(0)
; #define PG8_MMA2(ai) PG8_MMA(ai, 0, At, B0)
; #define PG8_MMA2(ai) PG8_MMA(ai, 1, At, B1)
; #define PG8_MMA2(ai) do { PG8_MMA(ai, 0, At, B0); PG8_MMA(ai, 1, At, B1); } while (0)
;     ...
;             const bool last = (t == nt - 2);
;             const char* a1 = cA + (size_t)(t + 1) * kstep;
;             const char* a2 = last ? nA : cA + (size_t)(t + 2) * kstep; const char* b2 = last ? nB : cB + (size_t)(t + 2) * kstep;
;             const char* a3 = a2 + kstep; const char* b3 = b2 + kstep;
;             if (last && has_next) S.a_ready(nxt);
;             if constexpr (SP2) {
;             PG8_LDB(B0, 0, 0); PG8_LDB(B1, 0, 1); PG8_SCHED; PG8_LDA(At, 0, 0); PG8_STAGE(PG8_SA(1, 1), a1 + hstep, voffA);
;             PG8_WAIT_V(8); PG8_WAIT_L(0); PG8_BAR; PG8_MMA2(0); PG8_BAR; PG8_SCHED;
;             PG8_LDA(At, 0, 1); PG8_STAGE(PG8_SB(0, 0), b2, voffB); PG8_STAGE(PG8_SB(0, 1), b2 + hstep, voffB); PG8_STAGE(PG8_SA(0, 0), a2, voffA);
;             PG8_WAIT_V(8); PG8_WAIT_L(0); PG8_BAR; PG8_MMA2(1); PG8_BAR; PG8_SCHED;
.LBB0_1343:
	s_cmp_eq_u32 s67, -2
	s_cbranch_scc1 .Ldf_skipA_5
	s_mov_b32 m0, s59
	s_nop 0
	global_load_lds_dwordx4 v[156:157], off
.Ldf_skipA_5:
	ds_read_b128 v[140:143], v161
	ds_read_b128 v[144:147], v161 offset:1024
	ds_read_b128 v[148:151], v161 offset:2048
	ds_read_b128 v[152:155], v161 offset:3072
	ds_read_b128 v[164:167], v162
	ds_read_b128 v[168:171], v162 offset:1024
	ds_read_b128 v[172:175], v162 offset:2048
	ds_read_b128 v[176:179], v162 offset:3072
	s_add_u32 s38, s36, 0x100
	s_addc_u32 s39, s37, 0
	s_cmp_eq_u32 s67, 40
	s_cselect_b32 s43, s15, s39
	s_cselect_b32 s42, s14, s38
	s_cselect_b32 s41, s27, s9
	s_cselect_b32 s40, s26, s8
	v_lshl_add_u64 v[156:157], s[36:37], 0, v[134:135]
	s_add_i32 m0, s49, 0xc000
	ds_read_b128 v[180:183], v163
	ds_read_b128 v[184:187], v163 offset:1024
	ds_read_b128 v[188:191], v163 offset:2048
	ds_read_b128 v[192:195], v163 offset:3072
	ds_read_b128 v[196:199], v163 offset:4096
	ds_read_b128 v[212:215], v163 offset:5120
	ds_read_b128 v[216:219], v163 offset:6144
	ds_read_b128 v[220:223], v163 offset:7168
	global_load_lds_dwordx4 v[156:157], off
	v_lshl_add_u64 v[156:157], s[36:37], 0, v[132:133]
	s_add_i32 m0, s49, 0xe000
	s_nop 0
	global_load_lds_dwordx4 v[156:157], off
	s_waitcnt vmcnt(8)
	s_waitcnt lgkmcnt(0)
	s_barrier
	s_setprio 1
	s_waitcnt lgkmcnt(0)
	v_mfma_f32_16x16x32_bf16 v[124:127], v[140:143], v[180:183], v[124:127]
	v_mfma_f32_16x16x32_bf16 v[120:123], v[148:151], v[180:183], v[120:123]
	v_mfma_f32_16x16x32_bf16 v[108:111], v[140:143], v[188:191], v[108:111]
	v_mfma_f32_16x16x32_bf16 v[104:107], v[148:151], v[188:191], v[104:107]
	v_mfma_f32_16x16x32_bf16 v[92:95], v[140:143], v[196:199], v[92:95]
	v_mfma_f32_16x16x32_bf16 v[88:91], v[148:151], v[196:199], v[88:91]
	v_mfma_f32_16x16x32_bf16 v[76:79], v[140:143], v[216:219], v[76:79]
	v_mfma_f32_16x16x32_bf16 v[72:75], v[148:151], v[216:219], v[72:75]
	v_mfma_f32_16x16x32_bf16 v[124:127], v[144:147], v[184:187], v[124:127]
	v_mfma_f32_16x16x32_bf16 v[120:123], v[152:155], v[184:187], v[120:123]
	v_mfma_f32_16x16x32_bf16 v[108:111], v[144:147], v[192:195], v[108:111]
	v_mfma_f32_16x16x32_bf16 v[104:107], v[152:155], v[192:195], v[104:107]
	v_mfma_f32_16x16x32_bf16 v[92:95], v[144:147], v[212:215], v[92:95]
	v_mfma_f32_16x16x32_bf16 v[88:91], v[152:155], v[212:215], v[88:91]
	v_mfma_f32_16x16x32_bf16 v[76:79], v[144:147], v[220:223], v[76:79]
	v_mfma_f32_16x16x32_bf16 v[72:75], v[152:155], v[220:223], v[72:75]
	s_setprio 0
	s_setprio 1
	v_mfma_f32_16x16x32_bf16 v[116:119], v[164:167], v[180:183], v[116:119]
	v_mfma_f32_16x16x32_bf16 v[112:115], v[172:175], v[180:183], v[112:115]
	v_mfma_f32_16x16x32_bf16 v[100:103], v[164:167], v[188:191], v[100:103]
	v_mfma_f32_16x16x32_bf16 v[96:99], v[172:175], v[188:191], v[96:99]
	v_mfma_f32_16x16x32_bf16 v[84:87], v[164:167], v[196:199], v[84:87]
	v_mfma_f32_16x16x32_bf16 v[80:83], v[172:175], v[196:199], v[80:83]
	v_mfma_f32_16x16x32_bf16 v[68:71], v[164:167], v[216:219], v[68:71]
	v_mfma_f32_16x16x32_bf16 v[64:67], v[172:175], v[216:219], v[64:67]
	v_mfma_f32_16x16x32_bf16 v[116:119], v[168:171], v[184:187], v[116:119]
	v_mfma_f32_16x16x32_bf16 v[112:115], v[176:179], v[184:187], v[112:115]
	v_mfma_f32_16x16x32_bf16 v[100:103], v[168:171], v[192:195], v[100:103]
	v_mfma_f32_16x16x32_bf16 v[96:99], v[176:179], v[192:195], v[96:99]
	v_mfma_f32_16x16x32_bf16 v[84:87], v[168:171], v[212:215], v[84:87]
	v_mfma_f32_16x16x32_bf16 v[80:83], v[176:179], v[212:215], v[80:83]
	v_mfma_f32_16x16x32_bf16 v[68:71], v[168:171], v[220:223], v[68:71]
	v_mfma_f32_16x16x32_bf16 v[64:67], v[176:179], v[220:223], v[64:67]
	s_setprio 0
	s_barrier
	s_add_i32 s34, s3, s48
	v_lshl_add_u64 v[156:157], s[40:41], 0, v[128:129]
	s_mov_b32 m0, s34
	ds_read_b128 v[180:183], v163 offset:16384
	ds_read_b128 v[184:187], v163 offset:17408
	ds_read_b128 v[188:191], v163 offset:18432
	ds_read_b128 v[192:195], v163 offset:19456
	ds_read_b128 v[196:199], v163 offset:20480
	ds_read_b128 v[212:215], v163 offset:21504
	ds_read_b128 v[216:219], v163 offset:22528
	ds_read_b128 v[220:223], v163 offset:23552
	global_load_lds_dwordx4 v[156:157], off
	s_add_i32 m0, s34, 0x2000
	s_add_u32 s34, s40, 0xb0000
	v_lshl_add_u64 v[224:225], s[40:41], 0, v[130:131]
	s_addc_u32 s35, s41, 0
	s_add_i32 s36, s63, s48
	global_load_lds_dwordx4 v[224:225], off
	v_lshl_add_u64 v[226:227], s[34:35], 0, v[128:129]
	s_mov_b32 m0, s36
	v_lshl_add_u64 v[228:229], s[42:43], 0, v[130:131]
	global_load_lds_dwordx4 v[226:227], off
	v_lshl_add_u64 v[226:227], s[34:35], 0, v[130:131]
	s_add_i32 m0, s36, 0x2000
	s_nop 0
	global_load_lds_dwordx4 v[226:227], off
	v_lshl_add_u64 v[226:227], s[42:43], 0, v[128:129]
	s_mov_b32 m0, s49
	s_nop 0
	global_load_lds_dwordx4 v[226:227], off
	s_nop 0
	s_waitcnt vmcnt(7)
	s_waitcnt lgkmcnt(0)
	s_barrier
; #define PG8_STAGE(bufoff, gbase, voff) do { _Pragma("unroll") for (int _i = 0; _i < 2; ++_i) \
;         __builtin_amdgcn_global_load_lds((const unsigned*)((const char*)(gbase) + (voff)[_i]), (PG8_LAS unsigned*)(lds + (bufoff) + ldsw + _i * 8192), 16, 0, 0); } while (0)
; #define PG8_LDA(dst, b, h) do { _Pragma("unroll") for (int m = 0; m < 4; ++m) _Pragma("unroll") for (int k = 0; k < 2; ++k) dst[m][k] = *(const PG8_LAS bf16x8*)(lds + PG8_SA(b, h) + aoff + m * 2048 + k * 1024); } while (0)
; #define PG8_LDB(dst, b, h) do { _Pragma("unroll") for (int n = 0; n < 2; ++n) _Pragma("unroll") for (int k = 0; k < 2; ++k) dst[n][k] = *(const PG8_LAS bf16x8*)(lds + PG8_SB(b, h) + boff + n * 2048 + k * 1024); } while (0)
; #define PG8_WAIT_V(n) asm volatile("s_waitcnt vmcnt(" #n ")" ::: "memory")
; #define PG8_WAIT_L(n) asm volatile("s_waitcnt lgkmcnt(" #n ")" ::: "memory")
; #define PG8_BAR __builtin_amdgcn_s_barrier()
; #define PG8_SCHED __builtin_amdgcn_sched_barrier(0)
; #define PG8_MMA2(ai) PG8_MMA(ai, 0, At, B0)
; #define PG8_MMA2(ai) PG8_MMA(ai, 1, At, B1)
; #define PG8_MMA2(ai) do { PG8_MMA(ai, 0, At, B0); PG8_MMA(ai, 1, At, B1); } while (0)
;     ...
;             PG8_WAIT_V(8); PG8_WAIT_L(0); PG8_BAR; PG8_MMA2(1); PG8_BAR; PG8_SCHED;
;             PG8_LDB(B0, 1, 0); PG8_LDB(B1, 1, 1); PG8_SCHED; PG8_LDA(At, 1, 0); PG8_STAGE(PG8_SA(0, 1), a2 + hstep, voffA);
;             PG8_WAIT_V(8); PG8_WAIT_L(0); PG8_BAR; PG8_MMA2(0); PG8_BAR; PG8_SCHED;
	s_setprio 1
	s_waitcnt lgkmcnt(0)
	v_mfma_f32_16x16x32_bf16 v[60:63], v[140:143], v[180:183], v[60:63]
	v_mfma_f32_16x16x32_bf16 v[56:59], v[148:151], v[180:183], v[56:59]
	v_mfma_f32_16x16x32_bf16 v[44:47], v[140:143], v[188:191], v[44:47]
	v_mfma_f32_16x16x32_bf16 v[40:43], v[148:151], v[188:191], v[40:43]
	v_mfma_f32_16x16x32_bf16 v[28:31], v[140:143], v[196:199], v[28:31]
	v_mfma_f32_16x16x32_bf16 v[24:27], v[148:151], v[196:199], v[24:27]
	v_mfma_f32_16x16x32_bf16 v[12:15], v[140:143], v[216:219], v[12:15]
	v_mfma_f32_16x16x32_bf16 v[8:11], v[148:151], v[216:219], v[8:11]
	v_mfma_f32_16x16x32_bf16 v[60:63], v[144:147], v[184:187], v[60:63]
	v_mfma_f32_16x16x32_bf16 v[56:59], v[152:155], v[184:187], v[56:59]
	v_mfma_f32_16x16x32_bf16 v[44:47], v[144:147], v[192:195], v[44:47]
	v_mfma_f32_16x16x32_bf16 v[40:43], v[152:155], v[192:195], v[40:43]
	v_mfma_f32_16x16x32_bf16 v[28:31], v[144:147], v[212:215], v[28:31]
	v_mfma_f32_16x16x32_bf16 v[24:27], v[152:155], v[212:215], v[24:27]
	v_mfma_f32_16x16x32_bf16 v[12:15], v[144:147], v[220:223], v[12:15]
	v_mfma_f32_16x16x32_bf16 v[8:11], v[152:155], v[220:223], v[8:11]
	s_setprio 0
	s_setprio 1
	v_mfma_f32_16x16x32_bf16 v[52:55], v[164:167], v[180:183], v[52:55]
	v_mfma_f32_16x16x32_bf16 v[48:51], v[172:175], v[180:183], v[48:51]
	v_mfma_f32_16x16x32_bf16 v[36:39], v[164:167], v[188:191], v[36:39]
	v_mfma_f32_16x16x32_bf16 v[32:35], v[172:175], v[188:191], v[32:35]
	v_mfma_f32_16x16x32_bf16 v[20:23], v[164:167], v[196:199], v[20:23]
	v_mfma_f32_16x16x32_bf16 v[16:19], v[172:175], v[196:199], v[16:19]
	v_mfma_f32_16x16x32_bf16 v[4:7], v[164:167], v[216:219], v[4:7]
	v_mfma_f32_16x16x32_bf16 v[0:3], v[172:175], v[216:219], v[0:3]
	v_mfma_f32_16x16x32_bf16 v[52:55], v[168:171], v[184:187], v[52:55]
	v_mfma_f32_16x16x32_bf16 v[48:51], v[176:179], v[184:187], v[48:51]
	v_mfma_f32_16x16x32_bf16 v[36:39], v[168:171], v[192:195], v[36:39]
	v_mfma_f32_16x16x32_bf16 v[32:35], v[176:179], v[192:195], v[32:35]
	v_mfma_f32_16x16x32_bf16 v[20:23], v[168:171], v[212:215], v[20:23]
	v_mfma_f32_16x16x32_bf16 v[16:19], v[176:179], v[212:215], v[16:19]
	v_mfma_f32_16x16x32_bf16 v[4:7], v[168:171], v[220:223], v[4:7]
	v_mfma_f32_16x16x32_bf16 v[0:3], v[176:179], v[220:223], v[0:3]
	s_setprio 0
	s_barrier
	s_add_i32 s36, 0, 0x18000
	s_add_i32 s37, 0, 0x1c000
	v_add_u32_e32 v152, s36, v159
	v_add_u32_e32 v176, s37, v159
	ds_read_b128 v[140:143], v152
	ds_read_b128 v[144:147], v152 offset:1024
	ds_read_b128 v[148:151], v152 offset:2048
	ds_read_b128 v[152:155], v152 offset:3072
	ds_read_b128 v[164:167], v176
	ds_read_b128 v[168:171], v176 offset:1024
	ds_read_b128 v[172:175], v176 offset:2048
	ds_read_b128 v[176:179], v176 offset:3072
	s_add_u32 s34, s42, 0xb0000
	s_addc_u32 s35, s43, 0
	s_mov_b32 m0, s50
	s_nop 0
	global_load_lds_dwordx4 v[228:229], off
	s_mov_b32 m0, s51
	v_lshl_add_u64 v[230:231], s[34:35], 0, v[128:129]
	ds_read_b128 v[180:183], v163 offset:32768
	ds_read_b128 v[184:187], v163 offset:33792
	ds_read_b128 v[188:191], v163 offset:34816
	ds_read_b128 v[192:195], v163 offset:35840
	ds_read_b128 v[196:199], v163 offset:36864
	ds_read_b128 v[212:215], v163 offset:37888
	ds_read_b128 v[216:219], v163 offset:38912
	ds_read_b128 v[220:223], v163 offset:39936
	global_load_lds_dwordx4 v[230:231], off
	v_lshl_add_u64 v[230:231], s[34:35], 0, v[130:131]
	s_mov_b32 m0, s52
	s_nop 0
	global_load_lds_dwordx4 v[230:231], off
	s_waitcnt vmcnt(8)
	s_waitcnt lgkmcnt(0)
	s_barrier
	s_setprio 1
	s_waitcnt lgkmcnt(0)
	v_mfma_f32_16x16x32_bf16 v[124:127], v[140:143], v[180:183], v[124:127]
	v_mfma_f32_16x16x32_bf16 v[120:123], v[148:151], v[180:183], v[120:123]
	v_mfma_f32_16x16x32_bf16 v[108:111], v[140:143], v[188:191], v[108:111]
	v_mfma_f32_16x16x32_bf16 v[104:107], v[148:151], v[188:191], v[104:107]
	v_mfma_f32_16x16x32_bf16 v[92:95], v[140:143], v[196:199], v[92:95]
	v_mfma_f32_16x16x32_bf16 v[88:91], v[148:151], v[196:199], v[88:91]
	v_mfma_f32_16x16x32_bf16 v[76:79], v[140:143], v[216:219], v[76:79]
	v_mfma_f32_16x16x32_bf16 v[72:75], v[148:151], v[216:219], v[72:75]
	v_mfma_f32_16x16x32_bf16 v[124:127], v[144:147], v[184:187], v[124:127]
	v_mfma_f32_16x16x32_bf16 v[120:123], v[152:155], v[184:187], v[120:123]
	v_mfma_f32_16x16x32_bf16 v[108:111], v[144:147], v[192:195], v[108:111]
	v_mfma_f32_16x16x32_bf16 v[104:107], v[152:155], v[192:195], v[104:107]
	v_mfma_f32_16x16x32_bf16 v[92:95], v[144:147], v[212:215], v[92:95]
	v_mfma_f32_16x16x32_bf16 v[88:91], v[152:155], v[212:215], v[88:91]
	v_mfma_f32_16x16x32_bf16 v[76:79], v[144:147], v[220:223], v[76:79]
	v_mfma_f32_16x16x32_bf16 v[72:75], v[152:155], v[220:223], v[72:75]
	s_setprio 0
	s_setprio 1
	v_mfma_f32_16x16x32_bf16 v[116:119], v[164:167], v[180:183], v[116:119]
	v_mfma_f32_16x16x32_bf16 v[112:115], v[172:175], v[180:183], v[112:115]
	v_mfma_f32_16x16x32_bf16 v[100:103], v[164:167], v[188:191], v[100:103]
	v_mfma_f32_16x16x32_bf16 v[96:99], v[172:175], v[188:191], v[96:99]
	v_mfma_f32_16x16x32_bf16 v[84:87], v[164:167], v[196:199], v[84:87]
	v_mfma_f32_16x16x32_bf16 v[80:83], v[172:175], v[196:199], v[80:83]
	v_mfma_f32_16x16x32_bf16 v[68:71], v[164:167], v[216:219], v[68:71]
	v_mfma_f32_16x16x32_bf16 v[64:67], v[172:175], v[216:219], v[64:67]
	v_mfma_f32_16x16x32_bf16 v[116:119], v[168:171], v[184:187], v[116:119]
	v_mfma_f32_16x16x32_bf16 v[112:115], v[176:179], v[184:187], v[112:115]
	v_mfma_f32_16x16x32_bf16 v[100:103], v[168:171], v[192:195], v[100:103]
	v_mfma_f32_16x16x32_bf16 v[96:99], v[176:179], v[192:195], v[96:99]
	v_mfma_f32_16x16x32_bf16 v[84:87], v[168:171], v[212:215], v[84:87]
	v_mfma_f32_16x16x32_bf16 v[80:83], v[176:179], v[212:215], v[80:83]
	v_mfma_f32_16x16x32_bf16 v[68:71], v[168:171], v[220:223], v[68:71]
	v_mfma_f32_16x16x32_bf16 v[64:67], v[176:179], v[220:223], v[64:67]
	s_setprio 0
	s_barrier
; #define PG8_STAGE(bufoff, gbase, voff) do { _Pragma("unroll") for (int _i = 0; _i < 2; ++_i) \
;         __builtin_amdgcn_global_load_lds((const unsigned*)((const char*)(gbase) + (voff)[_i]), (PG8_LAS unsigned*)(lds + (bufoff) + ldsw + _i * 8192), 16, 0, 0); } while (0)
; #define PG8_LDA(dst, b, h) do { _Pragma("unroll") for (int m = 0; m < 4; ++m) _Pragma("unroll") for (int k = 0; k < 2; ++k) dst[m][k] = *(const PG8_LAS bf16x8*)(lds + PG8_SA(b, h) + aoff + m * 2048 + k * 1024); } while (0)
; #define PG8_WAIT_V(n) asm volatile("s_waitcnt vmcnt(" #n ")" ::: "memory")
; #define PG8_WAIT_L(n) asm volatile("s_waitcnt lgkmcnt(" #n ")" ::: "memory")
; #define PG8_BAR __builtin_amdgcn_s_barrier()
; #define PG8_SCHED __builtin_amdgcn_sched_barrier(0)
; #define PG8_MMA2(ai) PG8_MMA(ai, 0, At, B0)
; #define PG8_MMA2(ai) PG8_MMA(ai, 1, At, B1)
; #define PG8_MMA2(ai) do { PG8_MMA(ai, 0, At, B0); PG8_MMA(ai, 1, At, B1); } while (0)
;     ...
;         for (int t = 0; t < nt; t += 2) {
;             const bool last = (t == nt - 2);
;             const char* a1 = cA + (size_t)(t + 1) * kstep;
;             const char* a2 = last ? nA : cA + (size_t)(t + 2) * kstep; const char* b2 = last ? nB : cB + (size_t)(t + 2) * kstep;
;             const char* a3 = a2 + kstep; const char* b3 = b2 + kstep;
;     ...
;             PG8_LDA(At, 1, 1); PG8_STAGE(PG8_SB(1, 0), b3, voffB); PG8_STAGE(PG8_SB(1, 1), b3 + hstep, voffB); PG8_STAGE(PG8_SA(1, 0), a3, voffA);
;             PG8_WAIT_V(8); PG8_WAIT_L(0); PG8_BAR; PG8_MMA2(1); PG8_BAR; PG8_SCHED;
	s_add_i32 s34, s36, s48
	v_lshl_add_u64 v[156:157], v[156:157], 0, s[20:21]
	s_mov_b32 m0, s34
	ds_read_b128 v[180:183], v163 offset:49152
	ds_read_b128 v[184:187], v163 offset:50176
	ds_read_b128 v[188:191], v163 offset:51200
	ds_read_b128 v[192:195], v163 offset:52224
	ds_read_b128 v[196:199], v163 offset:53248
	ds_read_b128 v[212:215], v163 offset:54272
	ds_read_b128 v[216:219], v163 offset:55296
	ds_read_b128 v[220:223], v163 offset:56320
	global_load_lds_dwordx4 v[156:157], off
	s_add_i32 m0, s34, 0x2000
	s_add_u32 s34, s40, 0xb0080
	v_lshl_add_u64 v[156:157], v[224:225], 0, s[20:21]
	s_addc_u32 s35, s41, 0
	s_add_i32 s36, s37, s48
	global_load_lds_dwordx4 v[156:157], off
	v_lshl_add_u64 v[156:157], s[34:35], 0, v[128:129]
	s_mov_b32 m0, s36
	s_nop 0
	global_load_lds_dwordx4 v[156:157], off
	v_lshl_add_u64 v[156:157], s[34:35], 0, v[130:131]
	s_add_i32 m0, s36, 0x2000
	s_nop 0
	global_load_lds_dwordx4 v[156:157], off
	v_lshl_add_u64 v[156:157], v[226:227], 0, s[20:21]
	s_mov_b32 m0, s58
	s_nop 0
	global_load_lds_dwordx4 v[156:157], off
	v_lshl_add_u64 v[156:157], v[228:229], 0, s[20:21]
	s_nop 0
	s_cmp_lg_u32 s67, 40
	s_cbranch_scc1 .Ldf_skipD_5
	s_mov_b32 m0, s59
	s_nop 0
	global_load_lds_dwordx4 v[156:157], off
.Ldf_skipD_5:
	s_waitcnt vmcnt(7)
	s_waitcnt lgkmcnt(0)
	s_barrier
	s_setprio 1
	s_waitcnt lgkmcnt(0)
	v_mfma_f32_16x16x32_bf16 v[60:63], v[140:143], v[180:183], v[60:63]
	v_mfma_f32_16x16x32_bf16 v[56:59], v[148:151], v[180:183], v[56:59]
	v_mfma_f32_16x16x32_bf16 v[44:47], v[140:143], v[188:191], v[44:47]
	v_mfma_f32_16x16x32_bf16 v[40:43], v[148:151], v[188:191], v[40:43]
	v_mfma_f32_16x16x32_bf16 v[28:31], v[140:143], v[196:199], v[28:31]
	v_mfma_f32_16x16x32_bf16 v[24:27], v[148:151], v[196:199], v[24:27]
	v_mfma_f32_16x16x32_bf16 v[12:15], v[140:143], v[216:219], v[12:15]
	v_mfma_f32_16x16x32_bf16 v[8:11], v[148:151], v[216:219], v[8:11]
	v_mfma_f32_16x16x32_bf16 v[60:63], v[144:147], v[184:187], v[60:63]
	v_mfma_f32_16x16x32_bf16 v[56:59], v[152:155], v[184:187], v[56:59]
	v_mfma_f32_16x16x32_bf16 v[44:47], v[144:147], v[192:195], v[44:47]
	v_mfma_f32_16x16x32_bf16 v[40:43], v[152:155], v[192:195], v[40:43]
	v_mfma_f32_16x16x32_bf16 v[28:31], v[144:147], v[212:215], v[28:31]
	v_mfma_f32_16x16x32_bf16 v[24:27], v[152:155], v[212:215], v[24:27]
	v_mfma_f32_16x16x32_bf16 v[12:15], v[144:147], v[220:223], v[12:15]
	v_mfma_f32_16x16x32_bf16 v[8:11], v[152:155], v[220:223], v[8:11]
	s_setprio 0
	s_setprio 1
	v_mfma_f32_16x16x32_bf16 v[52:55], v[164:167], v[180:183], v[52:55]
	v_mfma_f32_16x16x32_bf16 v[48:51], v[172:175], v[180:183], v[48:51]
	v_mfma_f32_16x16x32_bf16 v[36:39], v[164:167], v[188:191], v[36:39]
	v_mfma_f32_16x16x32_bf16 v[32:35], v[172:175], v[188:191], v[32:35]
	v_mfma_f32_16x16x32_bf16 v[20:23], v[164:167], v[196:199], v[20:23]
	v_mfma_f32_16x16x32_bf16 v[16:19], v[172:175], v[196:199], v[16:19]
	v_mfma_f32_16x16x32_bf16 v[4:7], v[164:167], v[216:219], v[4:7]
	v_mfma_f32_16x16x32_bf16 v[0:3], v[172:175], v[216:219], v[0:3]
	v_mfma_f32_16x16x32_bf16 v[52:55], v[168:171], v[184:187], v[52:55]
	v_mfma_f32_16x16x32_bf16 v[48:51], v[176:179], v[184:187], v[48:51]
	v_mfma_f32_16x16x32_bf16 v[36:39], v[168:171], v[192:195], v[36:39]
	v_mfma_f32_16x16x32_bf16 v[32:35], v[176:179], v[192:195], v[32:35]
	v_mfma_f32_16x16x32_bf16 v[20:23], v[168:171], v[212:215], v[20:23]
	v_mfma_f32_16x16x32_bf16 v[16:19], v[176:179], v[212:215], v[16:19]
	v_mfma_f32_16x16x32_bf16 v[4:7], v[168:171], v[220:223], v[4:7]
	v_mfma_f32_16x16x32_bf16 v[0:3], v[176:179], v[220:223], v[0:3]
	s_setprio 0
	s_barrier
	s_add_i32 s67, s67, 2
	s_add_u32 s8, s8, 0x100
	s_addc_u32 s9, s9, 0
	s_cmp_gt_u32 s67, 41
	s_mov_b64 s[36:37], s[38:39]
	s_cbranch_scc0 .LBB0_1343
	s_and_b64 vcc, exec, s[22:23]
	s_cbranch_vccz .LBB0_1346
	s_barrier

; #define PG8_STAGE(bufoff, gbase, voff) do { _Pragma("unroll") for (int _i = 0; _i < 2; ++_i) \
;         __builtin_amdgcn_global_load_lds((const unsigned*)((const char*)(gbase) + (voff)[_i]), (PG8_LAS unsigned*)(lds + (bufoff) + ldsw + _i * 8192), 16, 0, 0); } while (0)
; #define PG8_LDA(dst, b, h) do { _Pragma("unroll") for (int m = 0; m < 4; ++m) _Pragma("unroll") for (int k = 0; k < 2; ++k) dst[m][k] = *(const PG8_LAS bf16x8*)(lds + PG8_SA(b, h) + aoff + m * 2048 + k * 1024); } while (0)
; #define PG8_LDB(dst, b, h) do { _Pragma("unroll") for (int n = 0; n < 2; ++n) _Pragma("unroll") for (int k = 0; k < 2; ++k) dst[n][k] = *(const PG8_LAS bf16x8*)(lds + PG8_SB(b, h) + boff + n * 2048 + k * 1024); } while (0)
; #define PG8_WAIT_V(n) asm volatile("s_waitcnt vmcnt(" #n ")" ::: "memory")
; #define PG8_WAIT_L(n) asm volatile("s_waitcnt lgkmcnt(" #n ")" ::: "memory")
; #define PG8_BAR __builtin_amdgcn_s_barrier()
; #define PG8_SCHED __builtin_amdgcn_sched_barrier(0)
; #define PG8_MMA2(ai) PG8_MMA(ai, 0, At, B0)
; #define PG8_MMA2(ai) PG8_MMA(ai, 1, At, B1)
; #define PG8_MMA2(ai) do { PG8_MMA(ai, 0, At, B0); PG8_MMA(ai, 1, At, B1); } while (0)
;     ...
;             const bool last = (t == nt - 2);
;             const char* a1 = cA + (size_t)(t + 1) * kstep;
;             const char* a2 = last ? nA : cA + (size_t)(t + 2) * kstep; const char* b2 = last ? nB : cB + (size_t)(t + 2) * kstep;
;             const char* a3 = a2 + kstep; const char* b3 = b2 + kstep;
;             if (last && has_next) S.a_ready(nxt);
;             if constexpr (SP2) {
;             PG8_LDB(B0, 0, 0); PG8_LDB(B1, 0, 1); PG8_SCHED; PG8_LDA(At, 0, 0); PG8_STAGE(PG8_SA(1, 1), a1 + hstep, voffA);
;             PG8_WAIT_V(8); PG8_WAIT_L(0); PG8_BAR; PG8_MMA2(0); PG8_BAR; PG8_SCHED;
;             PG8_LDA(At, 0, 1); PG8_STAGE(PG8_SB(0, 0), b2, voffB); PG8_STAGE(PG8_SB(0, 1), b2 + hstep, voffB); PG8_STAGE(PG8_SA(0, 0), a2, voffA);
;             PG8_WAIT_V(8); PG8_WAIT_L(0); PG8_BAR; PG8_MMA2(1); PG8_BAR; PG8_SCHED;
.LBB0_1483:
	s_cmp_eq_u32 s62, -2
	s_cbranch_scc1 .Ldf_skipA_6
	s_mov_b32 m0, s56
	s_nop 0
	global_load_lds_dwordx4 v[144:145], off
.Ldf_skipA_6:
	ds_read_b128 v[152:155], v149
	ds_read_b128 v[156:159], v149 offset:1024
	ds_read_b128 v[160:163], v149 offset:2048
	ds_read_b128 v[164:167], v149 offset:3072
	ds_read_b128 v[168:171], v150
	ds_read_b128 v[172:175], v150 offset:1024
	ds_read_b128 v[176:179], v150 offset:2048
	ds_read_b128 v[180:183], v150 offset:3072
	s_add_u32 s34, s40, 0xfffc0080
	s_addc_u32 s35, s41, -1
	s_cmp_eq_u32 s62, 12
	s_cselect_b32 s45, s7, s35
	s_cselect_b32 s44, s8, s34
	s_cselect_b32 s43, s9, s61
	s_cselect_b32 s42, s21, s23
	v_lshl_add_u64 v[144:145], s[40:41], 0, v[138:139]
	s_add_i32 m0, s39, 0xc000
	ds_read_b128 v[184:187], v151
	ds_read_b128 v[188:191], v151 offset:1024
	ds_read_b128 v[192:195], v151 offset:2048
	ds_read_b128 v[196:199], v151 offset:3072
	ds_read_b128 v[212:215], v151 offset:4096
	ds_read_b128 v[216:219], v151 offset:5120
	ds_read_b128 v[220:223], v151 offset:6144
	ds_read_b128 v[224:227], v151 offset:7168
	global_load_lds_dwordx4 v[144:145], off
	v_lshl_add_u64 v[144:145], s[40:41], 0, v[136:137]
	s_add_i32 m0, s39, 0xe000
	s_nop 0
	global_load_lds_dwordx4 v[144:145], off
	s_waitcnt vmcnt(8)
	s_waitcnt lgkmcnt(0)
	s_barrier
	s_setprio 1
	s_waitcnt lgkmcnt(0)
	v_mfma_f32_16x16x32_bf16 v[124:127], v[152:155], v[184:187], v[124:127]
	v_mfma_f32_16x16x32_bf16 v[120:123], v[160:163], v[184:187], v[120:123]
	v_mfma_f32_16x16x32_bf16 v[108:111], v[152:155], v[192:195], v[108:111]
	v_mfma_f32_16x16x32_bf16 v[104:107], v[160:163], v[192:195], v[104:107]
	v_mfma_f32_16x16x32_bf16 v[92:95], v[152:155], v[212:215], v[92:95]
	v_mfma_f32_16x16x32_bf16 v[88:91], v[160:163], v[212:215], v[88:91]
	v_mfma_f32_16x16x32_bf16 v[76:79], v[152:155], v[220:223], v[76:79]
	v_mfma_f32_16x16x32_bf16 v[72:75], v[160:163], v[220:223], v[72:75]
	v_mfma_f32_16x16x32_bf16 v[124:127], v[156:159], v[188:191], v[124:127]
	v_mfma_f32_16x16x32_bf16 v[120:123], v[164:167], v[188:191], v[120:123]
	v_mfma_f32_16x16x32_bf16 v[108:111], v[156:159], v[196:199], v[108:111]
	v_mfma_f32_16x16x32_bf16 v[104:107], v[164:167], v[196:199], v[104:107]
	v_mfma_f32_16x16x32_bf16 v[92:95], v[156:159], v[216:219], v[92:95]
	v_mfma_f32_16x16x32_bf16 v[88:91], v[164:167], v[216:219], v[88:91]
	v_mfma_f32_16x16x32_bf16 v[76:79], v[156:159], v[224:227], v[76:79]
	v_mfma_f32_16x16x32_bf16 v[72:75], v[164:167], v[224:227], v[72:75]
	s_setprio 0
	s_setprio 1
	v_mfma_f32_16x16x32_bf16 v[116:119], v[168:171], v[184:187], v[116:119]
	v_mfma_f32_16x16x32_bf16 v[112:115], v[176:179], v[184:187], v[112:115]
	v_mfma_f32_16x16x32_bf16 v[100:103], v[168:171], v[192:195], v[100:103]
	v_mfma_f32_16x16x32_bf16 v[96:99], v[176:179], v[192:195], v[96:99]
	v_mfma_f32_16x16x32_bf16 v[84:87], v[168:171], v[212:215], v[84:87]
	v_mfma_f32_16x16x32_bf16 v[80:83], v[176:179], v[212:215], v[80:83]
	v_mfma_f32_16x16x32_bf16 v[68:71], v[168:171], v[220:223], v[68:71]
	v_mfma_f32_16x16x32_bf16 v[64:67], v[176:179], v[220:223], v[64:67]
	v_mfma_f32_16x16x32_bf16 v[116:119], v[172:175], v[188:191], v[116:119]
	v_mfma_f32_16x16x32_bf16 v[112:115], v[180:183], v[188:191], v[112:115]
	v_mfma_f32_16x16x32_bf16 v[100:103], v[172:175], v[196:199], v[100:103]
	v_mfma_f32_16x16x32_bf16 v[96:99], v[180:183], v[196:199], v[96:99]
	v_mfma_f32_16x16x32_bf16 v[84:87], v[172:175], v[216:219], v[84:87]
	v_mfma_f32_16x16x32_bf16 v[80:83], v[180:183], v[216:219], v[80:83]
	v_mfma_f32_16x16x32_bf16 v[68:71], v[172:175], v[224:227], v[68:71]
	v_mfma_f32_16x16x32_bf16 v[64:67], v[180:183], v[224:227], v[64:67]
	s_setprio 0
	s_barrier
	s_add_i32 s34, s3, s50
	v_lshl_add_u64 v[144:145], s[42:43], 0, v[130:131]
	s_mov_b32 m0, s34
	ds_read_b128 v[184:187], v151 offset:16384
	ds_read_b128 v[188:191], v151 offset:17408
	ds_read_b128 v[192:195], v151 offset:18432
	ds_read_b128 v[196:199], v151 offset:19456
	ds_read_b128 v[212:215], v151 offset:20480
	ds_read_b128 v[216:219], v151 offset:21504
	ds_read_b128 v[220:223], v151 offset:22528
	ds_read_b128 v[224:227], v151 offset:23552
	global_load_lds_dwordx4 v[144:145], off
	s_add_i32 m0, s34, 0x2000
	s_add_u32 s34, s42, 0x40000
	v_lshl_add_u64 v[228:229], s[42:43], 0, v[134:135]
	s_addc_u32 s35, s43, 0
	s_add_i32 s63, s59, s50
	global_load_lds_dwordx4 v[228:229], off
	v_lshl_add_u64 v[230:231], s[34:35], 0, v[130:131]
	s_mov_b32 m0, s63
	v_lshl_add_u64 v[232:233], s[44:45], 0, v[132:133]
	global_load_lds_dwordx4 v[230:231], off
	v_lshl_add_u64 v[230:231], s[34:35], 0, v[134:135]
	s_add_i32 m0, s63, 0x2000
	s_nop 0
	global_load_lds_dwordx4 v[230:231], off
	v_lshl_add_u64 v[230:231], s[44:45], 0, v[128:129]
	s_mov_b32 m0, s39
	s_nop 0
	global_load_lds_dwordx4 v[230:231], off
	s_nop 0
	s_waitcnt vmcnt(7)
	s_waitcnt lgkmcnt(0)
	s_barrier
; #define PG8_STAGE(bufoff, gbase, voff) do { _Pragma("unroll") for (int _i = 0; _i < 2; ++_i) \
;         __builtin_amdgcn_global_load_lds((const unsigned*)((const char*)(gbase) + (voff)[_i]), (PG8_LAS unsigned*)(lds + (bufoff) + ldsw + _i * 8192), 16, 0, 0); } while (0)
; #define PG8_LDA(dst, b, h) do { _Pragma("unroll") for (int m = 0; m < 4; ++m) _Pragma("unroll") for (int k = 0; k < 2; ++k) dst[m][k] = *(const PG8_LAS bf16x8*)(lds + PG8_SA(b, h) + aoff + m * 2048 + k * 1024); } while (0)
; #define PG8_LDB(dst, b, h) do { _Pragma("unroll") for (int n = 0; n < 2; ++n) _Pragma("unroll") for (int k = 0; k < 2; ++k) dst[n][k] = *(const PG8_LAS bf16x8*)(lds + PG8_SB(b, h) + boff + n * 2048 + k * 1024); } while (0)
; #define PG8_WAIT_V(n) asm volatile("s_waitcnt vmcnt(" #n ")" ::: "memory")
; #define PG8_WAIT_L(n) asm volatile("s_waitcnt lgkmcnt(" #n ")" ::: "memory")
; #define PG8_BAR __builtin_amdgcn_s_barrier()
; #define PG8_SCHED __builtin_amdgcn_sched_barrier(0)
; #define PG8_MMA2(ai) PG8_MMA(ai, 0, At, B0)
; #define PG8_MMA2(ai) PG8_MMA(ai, 1, At, B1)
; #define PG8_MMA2(ai) do { PG8_MMA(ai, 0, At, B0); PG8_MMA(ai, 1, At, B1); } while (0)
;     ...
;             PG8_WAIT_V(8); PG8_WAIT_L(0); PG8_BAR; PG8_MMA2(1); PG8_BAR; PG8_SCHED;
;             PG8_LDB(B0, 1, 0); PG8_LDB(B1, 1, 1); PG8_SCHED; PG8_LDA(At, 1, 0); PG8_STAGE(PG8_SA(0, 1), a2 + hstep, voffA);
;             PG8_WAIT_V(8); PG8_WAIT_L(0); PG8_BAR; PG8_MMA2(0); PG8_BAR; PG8_SCHED;
	s_setprio 1
	s_waitcnt lgkmcnt(0)
	v_mfma_f32_16x16x32_bf16 v[60:63], v[152:155], v[184:187], v[60:63]
	v_mfma_f32_16x16x32_bf16 v[56:59], v[160:163], v[184:187], v[56:59]
	v_mfma_f32_16x16x32_bf16 v[44:47], v[152:155], v[192:195], v[44:47]
	v_mfma_f32_16x16x32_bf16 v[40:43], v[160:163], v[192:195], v[40:43]
	v_mfma_f32_16x16x32_bf16 v[28:31], v[152:155], v[212:215], v[28:31]
	v_mfma_f32_16x16x32_bf16 v[24:27], v[160:163], v[212:215], v[24:27]
	v_mfma_f32_16x16x32_bf16 v[12:15], v[152:155], v[220:223], v[12:15]
	v_mfma_f32_16x16x32_bf16 v[8:11], v[160:163], v[220:223], v[8:11]
	v_mfma_f32_16x16x32_bf16 v[60:63], v[156:159], v[188:191], v[60:63]
	v_mfma_f32_16x16x32_bf16 v[56:59], v[164:167], v[188:191], v[56:59]
	v_mfma_f32_16x16x32_bf16 v[44:47], v[156:159], v[196:199], v[44:47]
	v_mfma_f32_16x16x32_bf16 v[40:43], v[164:167], v[196:199], v[40:43]
	v_mfma_f32_16x16x32_bf16 v[28:31], v[156:159], v[216:219], v[28:31]
	v_mfma_f32_16x16x32_bf16 v[24:27], v[164:167], v[216:219], v[24:27]
	v_mfma_f32_16x16x32_bf16 v[12:15], v[156:159], v[224:227], v[12:15]
	v_mfma_f32_16x16x32_bf16 v[8:11], v[164:167], v[224:227], v[8:11]
	s_setprio 0
	s_setprio 1
	v_mfma_f32_16x16x32_bf16 v[52:55], v[168:171], v[184:187], v[52:55]
	v_mfma_f32_16x16x32_bf16 v[48:51], v[176:179], v[184:187], v[48:51]
	v_mfma_f32_16x16x32_bf16 v[36:39], v[168:171], v[192:195], v[36:39]
	v_mfma_f32_16x16x32_bf16 v[32:35], v[176:179], v[192:195], v[32:35]
	v_mfma_f32_16x16x32_bf16 v[20:23], v[168:171], v[212:215], v[20:23]
	v_mfma_f32_16x16x32_bf16 v[16:19], v[176:179], v[212:215], v[16:19]
	v_mfma_f32_16x16x32_bf16 v[4:7], v[168:171], v[220:223], v[4:7]
	v_mfma_f32_16x16x32_bf16 v[0:3], v[176:179], v[220:223], v[0:3]
	v_mfma_f32_16x16x32_bf16 v[52:55], v[172:175], v[188:191], v[52:55]
	v_mfma_f32_16x16x32_bf16 v[48:51], v[180:183], v[188:191], v[48:51]
	v_mfma_f32_16x16x32_bf16 v[36:39], v[172:175], v[196:199], v[36:39]
	v_mfma_f32_16x16x32_bf16 v[32:35], v[180:183], v[196:199], v[32:35]
	v_mfma_f32_16x16x32_bf16 v[20:23], v[172:175], v[216:219], v[20:23]
	v_mfma_f32_16x16x32_bf16 v[16:19], v[180:183], v[216:219], v[16:19]
	v_mfma_f32_16x16x32_bf16 v[4:7], v[172:175], v[224:227], v[4:7]
	v_mfma_f32_16x16x32_bf16 v[0:3], v[180:183], v[224:227], v[0:3]
	s_setprio 0
	s_barrier
	s_add_i32 s63, 0, 0x18000
	s_add_i32 s64, 0, 0x1c000
	v_add_u32_e32 v164, s63, v147
	v_add_u32_e32 v180, s64, v147
	ds_read_b128 v[152:155], v164
	ds_read_b128 v[156:159], v164 offset:1024
	ds_read_b128 v[160:163], v164 offset:2048
	ds_read_b128 v[164:167], v164 offset:3072
	ds_read_b128 v[168:171], v180
	ds_read_b128 v[172:175], v180 offset:1024
	ds_read_b128 v[176:179], v180 offset:2048
	ds_read_b128 v[180:183], v180 offset:3072
	s_add_u32 s34, s44, 0x40000
	s_addc_u32 s35, s45, 0
	s_mov_b32 m0, s51
	s_nop 0
	global_load_lds_dwordx4 v[232:233], off
	s_mov_b32 m0, s52
	v_lshl_add_u64 v[234:235], s[34:35], 0, v[128:129]
	ds_read_b128 v[184:187], v151 offset:32768
	ds_read_b128 v[188:191], v151 offset:33792
	ds_read_b128 v[192:195], v151 offset:34816
	ds_read_b128 v[196:199], v151 offset:35840
	ds_read_b128 v[212:215], v151 offset:36864
	ds_read_b128 v[216:219], v151 offset:37888
	ds_read_b128 v[220:223], v151 offset:38912
	ds_read_b128 v[224:227], v151 offset:39936
	global_load_lds_dwordx4 v[234:235], off
	v_lshl_add_u64 v[234:235], s[34:35], 0, v[132:133]
	s_mov_b32 m0, s53
	s_nop 0
	global_load_lds_dwordx4 v[234:235], off
	s_waitcnt vmcnt(8)
	s_waitcnt lgkmcnt(0)
	s_barrier
	s_setprio 1
	s_waitcnt lgkmcnt(0)
	v_mfma_f32_16x16x32_bf16 v[124:127], v[152:155], v[184:187], v[124:127]
	v_mfma_f32_16x16x32_bf16 v[120:123], v[160:163], v[184:187], v[120:123]
	v_mfma_f32_16x16x32_bf16 v[108:111], v[152:155], v[192:195], v[108:111]
	v_mfma_f32_16x16x32_bf16 v[104:107], v[160:163], v[192:195], v[104:107]
	v_mfma_f32_16x16x32_bf16 v[92:95], v[152:155], v[212:215], v[92:95]
	v_mfma_f32_16x16x32_bf16 v[88:91], v[160:163], v[212:215], v[88:91]
	v_mfma_f32_16x16x32_bf16 v[76:79], v[152:155], v[220:223], v[76:79]
	v_mfma_f32_16x16x32_bf16 v[72:75], v[160:163], v[220:223], v[72:75]
	v_mfma_f32_16x16x32_bf16 v[124:127], v[156:159], v[188:191], v[124:127]
	v_mfma_f32_16x16x32_bf16 v[120:123], v[164:167], v[188:191], v[120:123]
	v_mfma_f32_16x16x32_bf16 v[108:111], v[156:159], v[196:199], v[108:111]
	v_mfma_f32_16x16x32_bf16 v[104:107], v[164:167], v[196:199], v[104:107]
	v_mfma_f32_16x16x32_bf16 v[92:95], v[156:159], v[216:219], v[92:95]
	v_mfma_f32_16x16x32_bf16 v[88:91], v[164:167], v[216:219], v[88:91]
	v_mfma_f32_16x16x32_bf16 v[76:79], v[156:159], v[224:227], v[76:79]
	v_mfma_f32_16x16x32_bf16 v[72:75], v[164:167], v[224:227], v[72:75]
	s_setprio 0
	s_setprio 1
	v_mfma_f32_16x16x32_bf16 v[116:119], v[168:171], v[184:187], v[116:119]
	v_mfma_f32_16x16x32_bf16 v[112:115], v[176:179], v[184:187], v[112:115]
	v_mfma_f32_16x16x32_bf16 v[100:103], v[168:171], v[192:195], v[100:103]
	v_mfma_f32_16x16x32_bf16 v[96:99], v[176:179], v[192:195], v[96:99]
	v_mfma_f32_16x16x32_bf16 v[84:87], v[168:171], v[212:215], v[84:87]
	v_mfma_f32_16x16x32_bf16 v[80:83], v[176:179], v[212:215], v[80:83]
	v_mfma_f32_16x16x32_bf16 v[68:71], v[168:171], v[220:223], v[68:71]
	v_mfma_f32_16x16x32_bf16 v[64:67], v[176:179], v[220:223], v[64:67]
	v_mfma_f32_16x16x32_bf16 v[116:119], v[172:175], v[188:191], v[116:119]
	v_mfma_f32_16x16x32_bf16 v[112:115], v[180:183], v[188:191], v[112:115]
	v_mfma_f32_16x16x32_bf16 v[100:103], v[172:175], v[196:199], v[100:103]
	v_mfma_f32_16x16x32_bf16 v[96:99], v[180:183], v[196:199], v[96:99]
	v_mfma_f32_16x16x32_bf16 v[84:87], v[172:175], v[216:219], v[84:87]
	v_mfma_f32_16x16x32_bf16 v[80:83], v[180:183], v[216:219], v[80:83]
	v_mfma_f32_16x16x32_bf16 v[68:71], v[172:175], v[224:227], v[68:71]
	v_mfma_f32_16x16x32_bf16 v[64:67], v[180:183], v[224:227], v[64:67]
	s_setprio 0
	s_barrier
; #define PG8_STAGE(bufoff, gbase, voff) do { _Pragma("unroll") for (int _i = 0; _i < 2; ++_i) \
;         __builtin_amdgcn_global_load_lds((const unsigned*)((const char*)(gbase) + (voff)[_i]), (PG8_LAS unsigned*)(lds + (bufoff) + ldsw + _i * 8192), 16, 0, 0); } while (0)
; #define PG8_LDA(dst, b, h) do { _Pragma("unroll") for (int m = 0; m < 4; ++m) _Pragma("unroll") for (int k = 0; k < 2; ++k) dst[m][k] = *(const PG8_LAS bf16x8*)(lds + PG8_SA(b, h) + aoff + m * 2048 + k * 1024); } while (0)
; #define PG8_WAIT_V(n) asm volatile("s_waitcnt vmcnt(" #n ")" ::: "memory")
; #define PG8_WAIT_L(n) asm volatile("s_waitcnt lgkmcnt(" #n ")" ::: "memory")
; #define PG8_BAR __builtin_amdgcn_s_barrier()
; #define PG8_SCHED __builtin_amdgcn_sched_barrier(0)
; #define PG8_MMA2(ai) PG8_MMA(ai, 0, At, B0)
; #define PG8_MMA2(ai) PG8_MMA(ai, 1, At, B1)
; #define PG8_MMA2(ai) do { PG8_MMA(ai, 0, At, B0); PG8_MMA(ai, 1, At, B1); } while (0)
;     ...
;         for (int t = 0; t < nt; t += 2) {
;             const bool last = (t == nt - 2);
;             const char* a1 = cA + (size_t)(t + 1) * kstep;
;             const char* a2 = last ? nA : cA + (size_t)(t + 2) * kstep; const char* b2 = last ? nB : cB + (size_t)(t + 2) * kstep;
;             const char* a3 = a2 + kstep; const char* b3 = b2 + kstep;
;     ...
;             PG8_LDA(At, 1, 1); PG8_STAGE(PG8_SB(1, 0), b3, voffB); PG8_STAGE(PG8_SB(1, 1), b3 + hstep, voffB); PG8_STAGE(PG8_SA(1, 0), a3, voffA);
;             PG8_WAIT_V(8); PG8_WAIT_L(0); PG8_BAR; PG8_MMA2(1); PG8_BAR; PG8_SCHED;
	s_add_i32 s34, s63, s50
	v_lshl_add_u64 v[144:145], v[144:145], 0, s[16:17]
	s_mov_b32 m0, s34
	ds_read_b128 v[184:187], v151 offset:49152
	ds_read_b128 v[188:191], v151 offset:50176
	ds_read_b128 v[192:195], v151 offset:51200
	ds_read_b128 v[196:199], v151 offset:52224
	ds_read_b128 v[212:215], v151 offset:53248
	ds_read_b128 v[216:219], v151 offset:54272
	ds_read_b128 v[220:223], v151 offset:55296
	ds_read_b128 v[224:227], v151 offset:56320
	global_load_lds_dwordx4 v[144:145], off
	s_add_i32 m0, s34, 0x2000
	s_add_u32 s34, s42, 0x40080
	v_lshl_add_u64 v[144:145], v[228:229], 0, s[16:17]
	s_addc_u32 s35, s43, 0
	s_add_i32 s42, s64, s50
	global_load_lds_dwordx4 v[144:145], off
	v_lshl_add_u64 v[144:145], s[34:35], 0, v[130:131]
	s_mov_b32 m0, s42
	s_nop 0
	global_load_lds_dwordx4 v[144:145], off
	v_lshl_add_u64 v[144:145], s[34:35], 0, v[134:135]
	s_add_i32 m0, s42, 0x2000
	s_nop 0
	global_load_lds_dwordx4 v[144:145], off
	v_lshl_add_u64 v[144:145], v[230:231], 0, s[16:17]
	s_mov_b32 m0, s55
	s_nop 0
	global_load_lds_dwordx4 v[144:145], off
	v_lshl_add_u64 v[144:145], v[232:233], 0, s[16:17]
	s_nop 0
	s_cmp_lg_u32 s62, 12
	s_cbranch_scc1 .Ldf_skipD_6
	s_mov_b32 m0, s56
	s_nop 0
	global_load_lds_dwordx4 v[144:145], off
.Ldf_skipD_6:
	s_waitcnt vmcnt(7)
	s_waitcnt lgkmcnt(0)
	s_barrier
	s_setprio 1
	s_waitcnt lgkmcnt(0)
	v_mfma_f32_16x16x32_bf16 v[60:63], v[152:155], v[184:187], v[60:63]
	v_mfma_f32_16x16x32_bf16 v[56:59], v[160:163], v[184:187], v[56:59]
	v_mfma_f32_16x16x32_bf16 v[44:47], v[152:155], v[192:195], v[44:47]
	v_mfma_f32_16x16x32_bf16 v[40:43], v[160:163], v[192:195], v[40:43]
	v_mfma_f32_16x16x32_bf16 v[28:31], v[152:155], v[212:215], v[28:31]
	v_mfma_f32_16x16x32_bf16 v[24:27], v[160:163], v[212:215], v[24:27]
	v_mfma_f32_16x16x32_bf16 v[12:15], v[152:155], v[220:223], v[12:15]
	v_mfma_f32_16x16x32_bf16 v[8:11], v[160:163], v[220:223], v[8:11]
	v_mfma_f32_16x16x32_bf16 v[60:63], v[156:159], v[188:191], v[60:63]
	v_mfma_f32_16x16x32_bf16 v[56:59], v[164:167], v[188:191], v[56:59]
	v_mfma_f32_16x16x32_bf16 v[44:47], v[156:159], v[196:199], v[44:47]
	v_mfma_f32_16x16x32_bf16 v[40:43], v[164:167], v[196:199], v[40:43]
	v_mfma_f32_16x16x32_bf16 v[28:31], v[156:159], v[216:219], v[28:31]
	v_mfma_f32_16x16x32_bf16 v[24:27], v[164:167], v[216:219], v[24:27]
	v_mfma_f32_16x16x32_bf16 v[12:15], v[156:159], v[224:227], v[12:15]
	v_mfma_f32_16x16x32_bf16 v[8:11], v[164:167], v[224:227], v[8:11]
	s_setprio 0
	s_setprio 1
	v_mfma_f32_16x16x32_bf16 v[52:55], v[168:171], v[184:187], v[52:55]
	v_mfma_f32_16x16x32_bf16 v[48:51], v[176:179], v[184:187], v[48:51]
	v_mfma_f32_16x16x32_bf16 v[36:39], v[168:171], v[192:195], v[36:39]
	v_mfma_f32_16x16x32_bf16 v[32:35], v[176:179], v[192:195], v[32:35]
	v_mfma_f32_16x16x32_bf16 v[20:23], v[168:171], v[212:215], v[20:23]
	v_mfma_f32_16x16x32_bf16 v[16:19], v[176:179], v[212:215], v[16:19]
	v_mfma_f32_16x16x32_bf16 v[4:7], v[168:171], v[220:223], v[4:7]
	v_mfma_f32_16x16x32_bf16 v[0:3], v[176:179], v[220:223], v[0:3]
	v_mfma_f32_16x16x32_bf16 v[52:55], v[172:175], v[188:191], v[52:55]
	v_mfma_f32_16x16x32_bf16 v[48:51], v[180:183], v[188:191], v[48:51]
	v_mfma_f32_16x16x32_bf16 v[36:39], v[172:175], v[196:199], v[36:39]
	v_mfma_f32_16x16x32_bf16 v[32:35], v[180:183], v[196:199], v[32:35]
	v_mfma_f32_16x16x32_bf16 v[20:23], v[172:175], v[216:219], v[20:23]
	v_mfma_f32_16x16x32_bf16 v[16:19], v[180:183], v[216:219], v[16:19]
	v_mfma_f32_16x16x32_bf16 v[4:7], v[172:175], v[224:227], v[4:7]
	v_mfma_f32_16x16x32_bf16 v[0:3], v[180:183], v[224:227], v[0:3]
	s_setprio 0
	s_barrier
	s_add_i32 s62, s62, 2
	s_add_u32 s23, s23, 0x100
	s_addc_u32 s61, s61, 0
	s_add_u32 s40, s40, 0x100
	s_addc_u32 s41, s41, 0
	s_cmp_gt_u32 s62, 13
	s_cbranch_scc0 .LBB0_1483
	s_and_b64 vcc, exec, s[18:19]
	s_cbranch_vccz .LBB0_1486
	s_barrier

; #define PG8_STAGE(bufoff, gbase, voff) do { _Pragma("unroll") for (int _i = 0; _i < 2; ++_i) \
;         __builtin_amdgcn_global_load_lds((const unsigned*)((const char*)(gbase) + (voff)[_i]), (PG8_LAS unsigned*)(lds + (bufoff) + ldsw + _i * 8192), 16, 0, 0); } while (0)
; #define PG8_LDA(dst, b, h) do { _Pragma("unroll") for (int m = 0; m < 4; ++m) _Pragma("unroll") for (int k = 0; k < 2; ++k) dst[m][k] = *(const PG8_LAS bf16x8*)(lds + PG8_SA(b, h) + aoff + m * 2048 + k * 1024); } while (0)
; #define PG8_LDB(dst, b, h) do { _Pragma("unroll") for (int n = 0; n < 2; ++n) _Pragma("unroll") for (int k = 0; k < 2; ++k) dst[n][k] = *(const PG8_LAS bf16x8*)(lds + PG8_SB(b, h) + boff + n * 2048 + k * 1024); } while (0)
; #define PG8_WAIT_V(n) asm volatile("s_waitcnt vmcnt(" #n ")" ::: "memory")
; #define PG8_WAIT_L(n) asm volatile("s_waitcnt lgkmcnt(" #n ")" ::: "memory")
; #define PG8_BAR __builtin_amdgcn_s_barrier()
; #define PG8_SCHED __builtin_amdgcn_sched_barrier(0)
; #define PG8_MMA2(ai) PG8_MMA(ai, 0, At, B0)
; #define PG8_MMA2(ai) PG8_MMA(ai, 1, At, B1)
; #define PG8_MMA2(ai) do { PG8_MMA(ai, 0, At, B0); PG8_MMA(ai, 1, At, B1); } while (0)
;     ...
;             const bool last = (t == nt - 2);
;             const char* a1 = cA + (size_t)(t + 1) * kstep;
;             const char* a2 = last ? nA : cA + (size_t)(t + 2) * kstep; const char* b2 = last ? nB : cB + (size_t)(t + 2) * kstep;
;             const char* a3 = a2 + kstep; const char* b3 = b2 + kstep;
;             if (last && has_next) S.a_ready(nxt);
;             if constexpr (SP2) {
;             PG8_LDB(B0, 0, 0); PG8_LDB(B1, 0, 1); PG8_SCHED; PG8_LDA(At, 0, 0); PG8_STAGE(PG8_SA(1, 1), a1 + hstep, voffA);
;             PG8_WAIT_V(8); PG8_WAIT_L(0); PG8_BAR; PG8_MMA2(0); PG8_BAR; PG8_SCHED;
;             PG8_LDA(At, 0, 1); PG8_STAGE(PG8_SB(0, 0), b2, voffB); PG8_STAGE(PG8_SB(0, 1), b2 + hstep, voffB); PG8_STAGE(PG8_SA(0, 0), a2, voffA);
;             PG8_WAIT_V(8); PG8_WAIT_L(0); PG8_BAR; PG8_MMA2(1); PG8_BAR; PG8_SCHED;
.LBB0_1563:
	s_cmp_eq_u32 s65, -2
	s_cbranch_scc1 .Ldf_skipA_7
	s_mov_b32 m0, s57
	s_nop 0
	global_load_lds_dwordx4 v[156:157], off
.Ldf_skipA_7:
	ds_read_b128 v[140:143], v161
	ds_read_b128 v[144:147], v161 offset:1024
	ds_read_b128 v[148:151], v161 offset:2048
	ds_read_b128 v[152:155], v161 offset:3072
	ds_read_b128 v[164:167], v162
	ds_read_b128 v[168:171], v162 offset:1024
	ds_read_b128 v[172:175], v162 offset:2048
	ds_read_b128 v[176:179], v162 offset:3072
	s_add_u32 s36, s26, 0x100
	s_addc_u32 s37, s27, 0
	s_cmp_eq_u32 s65, 40
	s_cselect_b32 s41, s13, s37
	s_cselect_b32 s40, s12, s36
	s_cselect_b32 s39, s23, s9
	s_cselect_b32 s38, s22, s8
	v_lshl_add_u64 v[156:157], s[26:27], 0, v[134:135]
	s_add_i32 m0, s47, 0xc000
	ds_read_b128 v[180:183], v163
	ds_read_b128 v[184:187], v163 offset:1024
	ds_read_b128 v[188:191], v163 offset:2048
	ds_read_b128 v[192:195], v163 offset:3072
	ds_read_b128 v[196:199], v163 offset:4096
	ds_read_b128 v[212:215], v163 offset:5120
	ds_read_b128 v[216:219], v163 offset:6144
	ds_read_b128 v[220:223], v163 offset:7168
	global_load_lds_dwordx4 v[156:157], off
	v_lshl_add_u64 v[156:157], s[26:27], 0, v[132:133]
	s_add_i32 m0, s47, 0xe000
	s_nop 0
	global_load_lds_dwordx4 v[156:157], off
	s_waitcnt vmcnt(8)
	s_waitcnt lgkmcnt(0)
	s_barrier
	s_setprio 1
	s_waitcnt lgkmcnt(0)
	v_mfma_f32_16x16x32_bf16 v[124:127], v[140:143], v[180:183], v[124:127]
	v_mfma_f32_16x16x32_bf16 v[120:123], v[148:151], v[180:183], v[120:123]
	v_mfma_f32_16x16x32_bf16 v[108:111], v[140:143], v[188:191], v[108:111]
	v_mfma_f32_16x16x32_bf16 v[104:107], v[148:151], v[188:191], v[104:107]
	v_mfma_f32_16x16x32_bf16 v[92:95], v[140:143], v[196:199], v[92:95]
	v_mfma_f32_16x16x32_bf16 v[88:91], v[148:151], v[196:199], v[88:91]
	v_mfma_f32_16x16x32_bf16 v[76:79], v[140:143], v[216:219], v[76:79]
	v_mfma_f32_16x16x32_bf16 v[72:75], v[148:151], v[216:219], v[72:75]
	v_mfma_f32_16x16x32_bf16 v[124:127], v[144:147], v[184:187], v[124:127]
	v_mfma_f32_16x16x32_bf16 v[120:123], v[152:155], v[184:187], v[120:123]
	v_mfma_f32_16x16x32_bf16 v[108:111], v[144:147], v[192:195], v[108:111]
	v_mfma_f32_16x16x32_bf16 v[104:107], v[152:155], v[192:195], v[104:107]
	v_mfma_f32_16x16x32_bf16 v[92:95], v[144:147], v[212:215], v[92:95]
	v_mfma_f32_16x16x32_bf16 v[88:91], v[152:155], v[212:215], v[88:91]
	v_mfma_f32_16x16x32_bf16 v[76:79], v[144:147], v[220:223], v[76:79]
	v_mfma_f32_16x16x32_bf16 v[72:75], v[152:155], v[220:223], v[72:75]
	s_setprio 0
	s_setprio 1
	v_mfma_f32_16x16x32_bf16 v[116:119], v[164:167], v[180:183], v[116:119]
	v_mfma_f32_16x16x32_bf16 v[112:115], v[172:175], v[180:183], v[112:115]
	v_mfma_f32_16x16x32_bf16 v[100:103], v[164:167], v[188:191], v[100:103]
	v_mfma_f32_16x16x32_bf16 v[96:99], v[172:175], v[188:191], v[96:99]
	v_mfma_f32_16x16x32_bf16 v[84:87], v[164:167], v[196:199], v[84:87]
	v_mfma_f32_16x16x32_bf16 v[80:83], v[172:175], v[196:199], v[80:83]
	v_mfma_f32_16x16x32_bf16 v[68:71], v[164:167], v[216:219], v[68:71]
	v_mfma_f32_16x16x32_bf16 v[64:67], v[172:175], v[216:219], v[64:67]
	v_mfma_f32_16x16x32_bf16 v[116:119], v[168:171], v[184:187], v[116:119]
	v_mfma_f32_16x16x32_bf16 v[112:115], v[176:179], v[184:187], v[112:115]
	v_mfma_f32_16x16x32_bf16 v[100:103], v[168:171], v[192:195], v[100:103]
	v_mfma_f32_16x16x32_bf16 v[96:99], v[176:179], v[192:195], v[96:99]
	v_mfma_f32_16x16x32_bf16 v[84:87], v[168:171], v[212:215], v[84:87]
	v_mfma_f32_16x16x32_bf16 v[80:83], v[176:179], v[212:215], v[80:83]
	v_mfma_f32_16x16x32_bf16 v[68:71], v[168:171], v[220:223], v[68:71]
	v_mfma_f32_16x16x32_bf16 v[64:67], v[176:179], v[220:223], v[64:67]
	s_setprio 0
	s_barrier
	s_add_i32 s26, s3, s46
	v_lshl_add_u64 v[156:157], s[38:39], 0, v[128:129]
	s_mov_b32 m0, s26
	ds_read_b128 v[180:183], v163 offset:16384
	ds_read_b128 v[184:187], v163 offset:17408
	ds_read_b128 v[188:191], v163 offset:18432
	ds_read_b128 v[192:195], v163 offset:19456
	ds_read_b128 v[196:199], v163 offset:20480
	ds_read_b128 v[212:215], v163 offset:21504
	ds_read_b128 v[216:219], v163 offset:22528
	ds_read_b128 v[220:223], v163 offset:23552
	global_load_lds_dwordx4 v[156:157], off
	s_add_i32 m0, s26, 0x2000
	s_add_u32 s26, s38, 0xb0000
	v_lshl_add_u64 v[224:225], s[38:39], 0, v[130:131]
	s_addc_u32 s27, s39, 0
	s_add_i32 s34, s61, s46
	global_load_lds_dwordx4 v[224:225], off
	v_lshl_add_u64 v[226:227], s[26:27], 0, v[128:129]
	s_mov_b32 m0, s34
	v_lshl_add_u64 v[228:229], s[40:41], 0, v[130:131]
	global_load_lds_dwordx4 v[226:227], off
	v_lshl_add_u64 v[226:227], s[26:27], 0, v[130:131]
	s_add_i32 m0, s34, 0x2000
	s_nop 0
	global_load_lds_dwordx4 v[226:227], off
	v_lshl_add_u64 v[226:227], s[40:41], 0, v[128:129]
	s_mov_b32 m0, s47
	s_nop 0
	global_load_lds_dwordx4 v[226:227], off
	s_nop 0
	s_waitcnt vmcnt(7)
	s_waitcnt lgkmcnt(0)
	s_barrier
; #define PG8_STAGE(bufoff, gbase, voff) do { _Pragma("unroll") for (int _i = 0; _i < 2; ++_i) \
;         __builtin_amdgcn_global_load_lds((const unsigned*)((const char*)(gbase) + (voff)[_i]), (PG8_LAS unsigned*)(lds + (bufoff) + ldsw + _i * 8192), 16, 0, 0); } while (0)
; #define PG8_LDA(dst, b, h) do { _Pragma("unroll") for (int m = 0; m < 4; ++m) _Pragma("unroll") for (int k = 0; k < 2; ++k) dst[m][k] = *(const PG8_LAS bf16x8*)(lds + PG8_SA(b, h) + aoff + m * 2048 + k * 1024); } while (0)
; #define PG8_LDB(dst, b, h) do { _Pragma("unroll") for (int n = 0; n < 2; ++n) _Pragma("unroll") for (int k = 0; k < 2; ++k) dst[n][k] = *(const PG8_LAS bf16x8*)(lds + PG8_SB(b, h) + boff + n * 2048 + k * 1024); } while (0)
; #define PG8_WAIT_V(n) asm volatile("s_waitcnt vmcnt(" #n ")" ::: "memory")
; #define PG8_WAIT_L(n) asm volatile("s_waitcnt lgkmcnt(" #n ")" ::: "memory")
; #define PG8_BAR __builtin_amdgcn_s_barrier()
; #define PG8_SCHED __builtin_amdgcn_sched_barrier(0)
; #define PG8_MMA2(ai) PG8_MMA(ai, 0, At, B0)
; #define PG8_MMA2(ai) PG8_MMA(ai, 1, At, B1)
; #define PG8_MMA2(ai) do { PG8_MMA(ai, 0, At, B0); PG8_MMA(ai, 1, At, B1); } while (0)
;     ...
;             PG8_WAIT_V(8); PG8_WAIT_L(0); PG8_BAR; PG8_MMA2(1); PG8_BAR; PG8_SCHED;
;             PG8_LDB(B0, 1, 0); PG8_LDB(B1, 1, 1); PG8_SCHED; PG8_LDA(At, 1, 0); PG8_STAGE(PG8_SA(0, 1), a2 + hstep, voffA);
;             PG8_WAIT_V(8); PG8_WAIT_L(0); PG8_BAR; PG8_MMA2(0); PG8_BAR; PG8_SCHED;
	s_setprio 1
	s_waitcnt lgkmcnt(0)
	v_mfma_f32_16x16x32_bf16 v[60:63], v[140:143], v[180:183], v[60:63]
	v_mfma_f32_16x16x32_bf16 v[56:59], v[148:151], v[180:183], v[56:59]
	v_mfma_f32_16x16x32_bf16 v[44:47], v[140:143], v[188:191], v[44:47]
	v_mfma_f32_16x16x32_bf16 v[40:43], v[148:151], v[188:191], v[40:43]
	v_mfma_f32_16x16x32_bf16 v[28:31], v[140:143], v[196:199], v[28:31]
	v_mfma_f32_16x16x32_bf16 v[24:27], v[148:151], v[196:199], v[24:27]
	v_mfma_f32_16x16x32_bf16 v[12:15], v[140:143], v[216:219], v[12:15]
	v_mfma_f32_16x16x32_bf16 v[8:11], v[148:151], v[216:219], v[8:11]
	v_mfma_f32_16x16x32_bf16 v[60:63], v[144:147], v[184:187], v[60:63]
	v_mfma_f32_16x16x32_bf16 v[56:59], v[152:155], v[184:187], v[56:59]
	v_mfma_f32_16x16x32_bf16 v[44:47], v[144:147], v[192:195], v[44:47]
	v_mfma_f32_16x16x32_bf16 v[40:43], v[152:155], v[192:195], v[40:43]
	v_mfma_f32_16x16x32_bf16 v[28:31], v[144:147], v[212:215], v[28:31]
	v_mfma_f32_16x16x32_bf16 v[24:27], v[152:155], v[212:215], v[24:27]
	v_mfma_f32_16x16x32_bf16 v[12:15], v[144:147], v[220:223], v[12:15]
	v_mfma_f32_16x16x32_bf16 v[8:11], v[152:155], v[220:223], v[8:11]
	s_setprio 0
	s_setprio 1
	v_mfma_f32_16x16x32_bf16 v[52:55], v[164:167], v[180:183], v[52:55]
	v_mfma_f32_16x16x32_bf16 v[48:51], v[172:175], v[180:183], v[48:51]
	v_mfma_f32_16x16x32_bf16 v[36:39], v[164:167], v[188:191], v[36:39]
	v_mfma_f32_16x16x32_bf16 v[32:35], v[172:175], v[188:191], v[32:35]
	v_mfma_f32_16x16x32_bf16 v[20:23], v[164:167], v[196:199], v[20:23]
	v_mfma_f32_16x16x32_bf16 v[16:19], v[172:175], v[196:199], v[16:19]
	v_mfma_f32_16x16x32_bf16 v[4:7], v[164:167], v[216:219], v[4:7]
	v_mfma_f32_16x16x32_bf16 v[0:3], v[172:175], v[216:219], v[0:3]
	v_mfma_f32_16x16x32_bf16 v[52:55], v[168:171], v[184:187], v[52:55]
	v_mfma_f32_16x16x32_bf16 v[48:51], v[176:179], v[184:187], v[48:51]
	v_mfma_f32_16x16x32_bf16 v[36:39], v[168:171], v[192:195], v[36:39]
	v_mfma_f32_16x16x32_bf16 v[32:35], v[176:179], v[192:195], v[32:35]
	v_mfma_f32_16x16x32_bf16 v[20:23], v[168:171], v[212:215], v[20:23]
	v_mfma_f32_16x16x32_bf16 v[16:19], v[176:179], v[212:215], v[16:19]
	v_mfma_f32_16x16x32_bf16 v[4:7], v[168:171], v[220:223], v[4:7]
	v_mfma_f32_16x16x32_bf16 v[0:3], v[176:179], v[220:223], v[0:3]
	s_setprio 0
	s_barrier
	s_add_i32 s34, 0, 0x18000
	s_add_i32 s35, 0, 0x1c000
	v_add_u32_e32 v152, s34, v159
	v_add_u32_e32 v176, s35, v159
	ds_read_b128 v[140:143], v152
	ds_read_b128 v[144:147], v152 offset:1024
	ds_read_b128 v[148:151], v152 offset:2048
	ds_read_b128 v[152:155], v152 offset:3072
	ds_read_b128 v[164:167], v176
	ds_read_b128 v[168:171], v176 offset:1024
	ds_read_b128 v[172:175], v176 offset:2048
	ds_read_b128 v[176:179], v176 offset:3072
	s_add_u32 s26, s40, 0xb0000
	s_addc_u32 s27, s41, 0
	s_mov_b32 m0, s48
	s_nop 0
	global_load_lds_dwordx4 v[228:229], off
	s_mov_b32 m0, s49
	v_lshl_add_u64 v[230:231], s[26:27], 0, v[128:129]
	ds_read_b128 v[180:183], v163 offset:32768
	ds_read_b128 v[184:187], v163 offset:33792
	ds_read_b128 v[188:191], v163 offset:34816
	ds_read_b128 v[192:195], v163 offset:35840
	ds_read_b128 v[196:199], v163 offset:36864
	ds_read_b128 v[212:215], v163 offset:37888
	ds_read_b128 v[216:219], v163 offset:38912
	ds_read_b128 v[220:223], v163 offset:39936
	global_load_lds_dwordx4 v[230:231], off
	v_lshl_add_u64 v[230:231], s[26:27], 0, v[130:131]
	s_mov_b32 m0, s50
	s_nop 0
	global_load_lds_dwordx4 v[230:231], off
	s_waitcnt vmcnt(8)
	s_waitcnt lgkmcnt(0)
	s_barrier
	s_setprio 1
	s_waitcnt lgkmcnt(0)
	v_mfma_f32_16x16x32_bf16 v[124:127], v[140:143], v[180:183], v[124:127]
	v_mfma_f32_16x16x32_bf16 v[120:123], v[148:151], v[180:183], v[120:123]
	v_mfma_f32_16x16x32_bf16 v[108:111], v[140:143], v[188:191], v[108:111]
	v_mfma_f32_16x16x32_bf16 v[104:107], v[148:151], v[188:191], v[104:107]
	v_mfma_f32_16x16x32_bf16 v[92:95], v[140:143], v[196:199], v[92:95]
	v_mfma_f32_16x16x32_bf16 v[88:91], v[148:151], v[196:199], v[88:91]
	v_mfma_f32_16x16x32_bf16 v[76:79], v[140:143], v[216:219], v[76:79]
	v_mfma_f32_16x16x32_bf16 v[72:75], v[148:151], v[216:219], v[72:75]
	v_mfma_f32_16x16x32_bf16 v[124:127], v[144:147], v[184:187], v[124:127]
	v_mfma_f32_16x16x32_bf16 v[120:123], v[152:155], v[184:187], v[120:123]
	v_mfma_f32_16x16x32_bf16 v[108:111], v[144:147], v[192:195], v[108:111]
	v_mfma_f32_16x16x32_bf16 v[104:107], v[152:155], v[192:195], v[104:107]
	v_mfma_f32_16x16x32_bf16 v[92:95], v[144:147], v[212:215], v[92:95]
	v_mfma_f32_16x16x32_bf16 v[88:91], v[152:155], v[212:215], v[88:91]
	v_mfma_f32_16x16x32_bf16 v[76:79], v[144:147], v[220:223], v[76:79]
	v_mfma_f32_16x16x32_bf16 v[72:75], v[152:155], v[220:223], v[72:75]
	s_setprio 0
	s_setprio 1
	v_mfma_f32_16x16x32_bf16 v[116:119], v[164:167], v[180:183], v[116:119]
	v_mfma_f32_16x16x32_bf16 v[112:115], v[172:175], v[180:183], v[112:115]
	v_mfma_f32_16x16x32_bf16 v[100:103], v[164:167], v[188:191], v[100:103]
	v_mfma_f32_16x16x32_bf16 v[96:99], v[172:175], v[188:191], v[96:99]
	v_mfma_f32_16x16x32_bf16 v[84:87], v[164:167], v[196:199], v[84:87]
	v_mfma_f32_16x16x32_bf16 v[80:83], v[172:175], v[196:199], v[80:83]
	v_mfma_f32_16x16x32_bf16 v[68:71], v[164:167], v[216:219], v[68:71]
	v_mfma_f32_16x16x32_bf16 v[64:67], v[172:175], v[216:219], v[64:67]
	v_mfma_f32_16x16x32_bf16 v[116:119], v[168:171], v[184:187], v[116:119]
	v_mfma_f32_16x16x32_bf16 v[112:115], v[176:179], v[184:187], v[112:115]
	v_mfma_f32_16x16x32_bf16 v[100:103], v[168:171], v[192:195], v[100:103]
	v_mfma_f32_16x16x32_bf16 v[96:99], v[176:179], v[192:195], v[96:99]
	v_mfma_f32_16x16x32_bf16 v[84:87], v[168:171], v[212:215], v[84:87]
	v_mfma_f32_16x16x32_bf16 v[80:83], v[176:179], v[212:215], v[80:83]
	v_mfma_f32_16x16x32_bf16 v[68:71], v[168:171], v[220:223], v[68:71]
	v_mfma_f32_16x16x32_bf16 v[64:67], v[176:179], v[220:223], v[64:67]
	s_setprio 0
	s_barrier
; #define PG8_STAGE(bufoff, gbase, voff) do { _Pragma("unroll") for (int _i = 0; _i < 2; ++_i) \
;         __builtin_amdgcn_global_load_lds((const unsigned*)((const char*)(gbase) + (voff)[_i]), (PG8_LAS unsigned*)(lds + (bufoff) + ldsw + _i * 8192), 16, 0, 0); } while (0)
; #define PG8_LDA(dst, b, h) do { _Pragma("unroll") for (int m = 0; m < 4; ++m) _Pragma("unroll") for (int k = 0; k < 2; ++k) dst[m][k] = *(const PG8_LAS bf16x8*)(lds + PG8_SA(b, h) + aoff + m * 2048 + k * 1024); } while (0)
; #define PG8_WAIT_V(n) asm volatile("s_waitcnt vmcnt(" #n ")" ::: "memory")
; #define PG8_WAIT_L(n) asm volatile("s_waitcnt lgkmcnt(" #n ")" ::: "memory")
; #define PG8_BAR __builtin_amdgcn_s_barrier()
; #define PG8_SCHED __builtin_amdgcn_sched_barrier(0)
; #define PG8_MMA2(ai) PG8_MMA(ai, 0, At, B0)
; #define PG8_MMA2(ai) PG8_MMA(ai, 1, At, B1)
; #define PG8_MMA2(ai) do { PG8_MMA(ai, 0, At, B0); PG8_MMA(ai, 1, At, B1); } while (0)
;     ...
;         for (int t = 0; t < nt; t += 2) {
;             const bool last = (t == nt - 2);
;             const char* a1 = cA + (size_t)(t + 1) * kstep;
;             const char* a2 = last ? nA : cA + (size_t)(t + 2) * kstep; const char* b2 = last ? nB : cB + (size_t)(t + 2) * kstep;
;             const char* a3 = a2 + kstep; const char* b3 = b2 + kstep;
;     ...
;             PG8_LDA(At, 1, 1); PG8_STAGE(PG8_SB(1, 0), b3, voffB); PG8_STAGE(PG8_SB(1, 1), b3 + hstep, voffB); PG8_STAGE(PG8_SA(1, 0), a3, voffA);
;             PG8_WAIT_V(8); PG8_WAIT_L(0); PG8_BAR; PG8_MMA2(1); PG8_BAR; PG8_SCHED;
	s_add_i32 s26, s34, s46
	v_lshl_add_u64 v[156:157], v[156:157], 0, s[18:19]
	s_mov_b32 m0, s26
	ds_read_b128 v[180:183], v163 offset:49152
	ds_read_b128 v[184:187], v163 offset:50176
	ds_read_b128 v[188:191], v163 offset:51200
	ds_read_b128 v[192:195], v163 offset:52224
	ds_read_b128 v[196:199], v163 offset:53248
	ds_read_b128 v[212:215], v163 offset:54272
	ds_read_b128 v[216:219], v163 offset:55296
	ds_read_b128 v[220:223], v163 offset:56320
	global_load_lds_dwordx4 v[156:157], off
	s_add_i32 m0, s26, 0x2000
	s_add_u32 s26, s38, 0xb0080
	v_lshl_add_u64 v[156:157], v[224:225], 0, s[18:19]
	s_addc_u32 s27, s39, 0
	s_add_i32 s34, s35, s46
	global_load_lds_dwordx4 v[156:157], off
	v_lshl_add_u64 v[156:157], s[26:27], 0, v[128:129]
	s_mov_b32 m0, s34
	s_nop 0
	global_load_lds_dwordx4 v[156:157], off
	v_lshl_add_u64 v[156:157], s[26:27], 0, v[130:131]
	s_add_i32 m0, s34, 0x2000
	s_nop 0
	global_load_lds_dwordx4 v[156:157], off
	v_lshl_add_u64 v[156:157], v[226:227], 0, s[18:19]
	s_mov_b32 m0, s56
	s_nop 0
	global_load_lds_dwordx4 v[156:157], off
	v_lshl_add_u64 v[156:157], v[228:229], 0, s[18:19]
	s_nop 0
	s_cmp_lg_u32 s65, 40
	s_cbranch_scc1 .Ldf_skipD_7
	s_mov_b32 m0, s57
	s_nop 0
	global_load_lds_dwordx4 v[156:157], off
.Ldf_skipD_7:
	s_waitcnt vmcnt(7)
	s_waitcnt lgkmcnt(0)
	s_barrier
	s_setprio 1
	s_waitcnt lgkmcnt(0)
	v_mfma_f32_16x16x32_bf16 v[60:63], v[140:143], v[180:183], v[60:63]
	v_mfma_f32_16x16x32_bf16 v[56:59], v[148:151], v[180:183], v[56:59]
	v_mfma_f32_16x16x32_bf16 v[44:47], v[140:143], v[188:191], v[44:47]
	v_mfma_f32_16x16x32_bf16 v[40:43], v[148:151], v[188:191], v[40:43]
	v_mfma_f32_16x16x32_bf16 v[28:31], v[140:143], v[196:199], v[28:31]
	v_mfma_f32_16x16x32_bf16 v[24:27], v[148:151], v[196:199], v[24:27]
	v_mfma_f32_16x16x32_bf16 v[12:15], v[140:143], v[216:219], v[12:15]
	v_mfma_f32_16x16x32_bf16 v[8:11], v[148:151], v[216:219], v[8:11]
	v_mfma_f32_16x16x32_bf16 v[60:63], v[144:147], v[184:187], v[60:63]
	v_mfma_f32_16x16x32_bf16 v[56:59], v[152:155], v[184:187], v[56:59]
	v_mfma_f32_16x16x32_bf16 v[44:47], v[144:147], v[192:195], v[44:47]
	v_mfma_f32_16x16x32_bf16 v[40:43], v[152:155], v[192:195], v[40:43]
	v_mfma_f32_16x16x32_bf16 v[28:31], v[144:147], v[212:215], v[28:31]
	v_mfma_f32_16x16x32_bf16 v[24:27], v[152:155], v[212:215], v[24:27]
	v_mfma_f32_16x16x32_bf16 v[12:15], v[144:147], v[220:223], v[12:15]
	v_mfma_f32_16x16x32_bf16 v[8:11], v[152:155], v[220:223], v[8:11]
	s_setprio 0
	s_setprio 1
	v_mfma_f32_16x16x32_bf16 v[52:55], v[164:167], v[180:183], v[52:55]
	v_mfma_f32_16x16x32_bf16 v[48:51], v[172:175], v[180:183], v[48:51]
	v_mfma_f32_16x16x32_bf16 v[36:39], v[164:167], v[188:191], v[36:39]
	v_mfma_f32_16x16x32_bf16 v[32:35], v[172:175], v[188:191], v[32:35]
	v_mfma_f32_16x16x32_bf16 v[20:23], v[164:167], v[196:199], v[20:23]
	v_mfma_f32_16x16x32_bf16 v[16:19], v[172:175], v[196:199], v[16:19]
	v_mfma_f32_16x16x32_bf16 v[4:7], v[164:167], v[216:219], v[4:7]
	v_mfma_f32_16x16x32_bf16 v[0:3], v[172:175], v[216:219], v[0:3]
	v_mfma_f32_16x16x32_bf16 v[52:55], v[168:171], v[184:187], v[52:55]
	v_mfma_f32_16x16x32_bf16 v[48:51], v[176:179], v[184:187], v[48:51]
	v_mfma_f32_16x16x32_bf16 v[36:39], v[168:171], v[192:195], v[36:39]
	v_mfma_f32_16x16x32_bf16 v[32:35], v[176:179], v[192:195], v[32:35]
	v_mfma_f32_16x16x32_bf16 v[20:23], v[168:171], v[212:215], v[20:23]
	v_mfma_f32_16x16x32_bf16 v[16:19], v[176:179], v[212:215], v[16:19]
	v_mfma_f32_16x16x32_bf16 v[4:7], v[168:171], v[220:223], v[4:7]
	v_mfma_f32_16x16x32_bf16 v[0:3], v[176:179], v[220:223], v[0:3]
	s_setprio 0
	s_barrier
	s_add_i32 s65, s65, 2
	s_add_u32 s8, s8, 0x100
	s_addc_u32 s9, s9, 0
	s_cmp_gt_u32 s65, 41
	s_mov_b64 s[26:27], s[36:37]
	s_cbranch_scc0 .LBB0_1563
	s_and_b64 vcc, exec, s[20:21]
	s_cbranch_vccz .LBB0_1566
	s_barrier

; #define PG8_STAGE(bufoff, gbase, voff) do { _Pragma("unroll") for (int _i = 0; _i < 2; ++_i) \
;         __builtin_amdgcn_global_load_lds((const unsigned*)((const char*)(gbase) + (voff)[_i]), (PG8_LAS unsigned*)(lds + (bufoff) + ldsw + _i * 8192), 16, 0, 0); } while (0)
; #define PG8_LDA(dst, b, h) do { _Pragma("unroll") for (int m = 0; m < 4; ++m) _Pragma("unroll") for (int k = 0; k < 2; ++k) dst[m][k] = *(const PG8_LAS bf16x8*)(lds + PG8_SA(b, h) + aoff + m * 2048 + k * 1024); } while (0)
; #define PG8_LDB(dst, b, h) do { _Pragma("unroll") for (int n = 0; n < 2; ++n) _Pragma("unroll") for (int k = 0; k < 2; ++k) dst[n][k] = *(const PG8_LAS bf16x8*)(lds + PG8_SB(b, h) + boff + n * 2048 + k * 1024); } while (0)
; #define PG8_WAIT_V(n) asm volatile("s_waitcnt vmcnt(" #n ")" ::: "memory")
; #define PG8_WAIT_L(n) asm volatile("s_waitcnt lgkmcnt(" #n ")" ::: "memory")
; #define PG8_BAR __builtin_amdgcn_s_barrier()
; #define PG8_SCHED __builtin_amdgcn_sched_barrier(0)
; #define PG8_MMA2(ai) PG8_MMA(ai, 0, At, B0)
; #define PG8_MMA2(ai) PG8_MMA(ai, 1, At, B1)
; #define PG8_MMA2(ai) do { PG8_MMA(ai, 0, At, B0); PG8_MMA(ai, 1, At, B1); } while (0)
;     ...
;             const bool last = (t == nt - 2);
;             const char* a1 = cA + (size_t)(t + 1) * kstep;
;             const char* a2 = last ? nA : cA + (size_t)(t + 2) * kstep; const char* b2 = last ? nB : cB + (size_t)(t + 2) * kstep;
;             const char* a3 = a2 + kstep; const char* b3 = b2 + kstep;
;             if (last && has_next) S.a_ready(nxt);
;             if constexpr (SP2) {
;             PG8_LDB(B0, 0, 0); PG8_LDB(B1, 0, 1); PG8_SCHED; PG8_LDA(At, 0, 0); PG8_STAGE(PG8_SA(1, 1), a1 + hstep, voffA);
;             PG8_WAIT_V(8); PG8_WAIT_L(0); PG8_BAR; PG8_MMA2(0); PG8_BAR; PG8_SCHED;
;             PG8_LDA(At, 0, 1); PG8_STAGE(PG8_SB(0, 0), b2, voffB); PG8_STAGE(PG8_SB(0, 1), b2 + hstep, voffB); PG8_STAGE(PG8_SA(0, 0), a2, voffA);
;             PG8_WAIT_V(8); PG8_WAIT_L(0); PG8_BAR; PG8_MMA2(1); PG8_BAR; PG8_SCHED;
.LBB0_1705:
	s_cmp_eq_u32 s67, -2
	s_cbranch_scc1 .Ldf_skipA_8
	s_mov_b32 m0, s86
	s_nop 0
	global_load_lds_dwordx4 v[172:173], off
.Ldf_skipA_8:
	s_waitcnt lgkmcnt(0)
	ds_read_b128 v[128:131], v182
	ds_read_b128 v[132:135], v182 offset:1024
	ds_read_b128 v[136:139], v182 offset:2048
	ds_read_b128 v[140:143], v182 offset:3072
	ds_read_b128 v[168:171], v183
	ds_read_b128 v[188:191], v183 offset:1024
	ds_read_b128 v[192:195], v183 offset:2048
	ds_read_b128 v[196:199], v183 offset:3072
	s_add_u32 s34, s14, 0xfffc0080
	s_addc_u32 s35, s15, -1
	s_cmp_eq_u32 s67, 12
	s_cselect_b32 s71, s8, s35
	s_cselect_b32 s70, s9, s34
	s_cselect_b32 s69, s17, s61
	s_cselect_b32 s68, s20, s59
	v_lshl_add_u64 v[172:173], s[14:15], 0, v[162:163]
	s_add_i32 m0, s76, 0xc000
	ds_read_b128 v[212:215], v184
	ds_read_b128 v[216:219], v184 offset:1024
	ds_read_b128 v[220:223], v184 offset:2048
	ds_read_b128 v[224:227], v184 offset:3072
	ds_read_b128 v[228:231], v184 offset:4096
	ds_read_b128 v[232:235], v184 offset:5120
	ds_read_b128 v[236:239], v184 offset:6144
	ds_read_b128 v[240:243], v184 offset:7168
	global_load_lds_dwordx4 v[172:173], off
	v_lshl_add_u64 v[172:173], s[14:15], 0, v[160:161]
	s_add_i32 m0, s76, 0xe000
	s_nop 0
	global_load_lds_dwordx4 v[172:173], off
	s_waitcnt vmcnt(8)
	s_waitcnt lgkmcnt(0)
	s_barrier
	s_setprio 1
	s_waitcnt lgkmcnt(0)
	v_mfma_f32_16x16x32_bf16 v[124:127], v[128:131], v[212:215], v[124:127]
	v_mfma_f32_16x16x32_bf16 v[120:123], v[136:139], v[212:215], v[120:123]
	v_mfma_f32_16x16x32_bf16 v[108:111], v[128:131], v[220:223], v[108:111]
	v_mfma_f32_16x16x32_bf16 v[104:107], v[136:139], v[220:223], v[104:107]
	v_mfma_f32_16x16x32_bf16 v[92:95], v[128:131], v[228:231], v[92:95]
	v_mfma_f32_16x16x32_bf16 v[88:91], v[136:139], v[228:231], v[88:91]
	v_mfma_f32_16x16x32_bf16 v[76:79], v[128:131], v[236:239], v[76:79]
	v_mfma_f32_16x16x32_bf16 v[72:75], v[136:139], v[236:239], v[72:75]
	v_mfma_f32_16x16x32_bf16 v[124:127], v[132:135], v[216:219], v[124:127]
	v_mfma_f32_16x16x32_bf16 v[120:123], v[140:143], v[216:219], v[120:123]
	v_mfma_f32_16x16x32_bf16 v[108:111], v[132:135], v[224:227], v[108:111]
	v_mfma_f32_16x16x32_bf16 v[104:107], v[140:143], v[224:227], v[104:107]
	v_mfma_f32_16x16x32_bf16 v[92:95], v[132:135], v[232:235], v[92:95]
	v_mfma_f32_16x16x32_bf16 v[88:91], v[140:143], v[232:235], v[88:91]
	v_mfma_f32_16x16x32_bf16 v[76:79], v[132:135], v[240:243], v[76:79]
	v_mfma_f32_16x16x32_bf16 v[72:75], v[140:143], v[240:243], v[72:75]
	s_setprio 0
	s_setprio 1
	v_mfma_f32_16x16x32_bf16 v[116:119], v[168:171], v[212:215], v[116:119]
	v_mfma_f32_16x16x32_bf16 v[112:115], v[192:195], v[212:215], v[112:115]
	v_mfma_f32_16x16x32_bf16 v[100:103], v[168:171], v[220:223], v[100:103]
	v_mfma_f32_16x16x32_bf16 v[96:99], v[192:195], v[220:223], v[96:99]
	v_mfma_f32_16x16x32_bf16 v[84:87], v[168:171], v[228:231], v[84:87]
	v_mfma_f32_16x16x32_bf16 v[80:83], v[192:195], v[228:231], v[80:83]
	v_mfma_f32_16x16x32_bf16 v[68:71], v[168:171], v[236:239], v[68:71]
	v_mfma_f32_16x16x32_bf16 v[64:67], v[192:195], v[236:239], v[64:67]
	v_mfma_f32_16x16x32_bf16 v[116:119], v[188:191], v[216:219], v[116:119]
	v_mfma_f32_16x16x32_bf16 v[112:115], v[196:199], v[216:219], v[112:115]
	v_mfma_f32_16x16x32_bf16 v[100:103], v[188:191], v[224:227], v[100:103]
	v_mfma_f32_16x16x32_bf16 v[96:99], v[196:199], v[224:227], v[96:99]
	v_mfma_f32_16x16x32_bf16 v[84:87], v[188:191], v[232:235], v[84:87]
	v_mfma_f32_16x16x32_bf16 v[80:83], v[196:199], v[232:235], v[80:83]
	v_mfma_f32_16x16x32_bf16 v[68:71], v[188:191], v[240:243], v[68:71]
	v_mfma_f32_16x16x32_bf16 v[64:67], v[196:199], v[240:243], v[64:67]
	s_setprio 0
	s_barrier
	s_add_i32 s34, s3, s75
	v_lshl_add_u64 v[172:173], s[68:69], 0, v[146:147]
	s_mov_b32 m0, s34
	ds_read_b128 v[212:215], v184 offset:16384
	ds_read_b128 v[216:219], v184 offset:17408
	ds_read_b128 v[220:223], v184 offset:18432
	ds_read_b128 v[224:227], v184 offset:19456
	ds_read_b128 v[228:231], v184 offset:20480
	ds_read_b128 v[232:235], v184 offset:21504
	ds_read_b128 v[236:239], v184 offset:22528
	ds_read_b128 v[240:243], v184 offset:23552
	global_load_lds_dwordx4 v[172:173], off
	s_add_i32 m0, s34, 0x2000
	s_add_u32 s34, s68, 0x40000
	v_lshl_add_u64 v[244:245], s[68:69], 0, v[150:151]
	s_addc_u32 s35, s69, 0
	s_add_i32 s82, s90, s75
	global_load_lds_dwordx4 v[244:245], off
	v_lshl_add_u64 v[246:247], s[34:35], 0, v[146:147]
	s_mov_b32 m0, s82
	v_lshl_add_u64 v[248:249], s[70:71], 0, v[148:149]
	global_load_lds_dwordx4 v[246:247], off
	v_lshl_add_u64 v[246:247], s[34:35], 0, v[150:151]
	s_add_i32 m0, s82, 0x2000
	s_nop 0
	global_load_lds_dwordx4 v[246:247], off
	v_lshl_add_u64 v[246:247], s[70:71], 0, v[144:145]
	s_mov_b32 m0, s76
	s_nop 0
	global_load_lds_dwordx4 v[246:247], off
	s_nop 0
	s_waitcnt vmcnt(7)
	s_waitcnt lgkmcnt(0)
	s_barrier
; #define PG8_STAGE(bufoff, gbase, voff) do { _Pragma("unroll") for (int _i = 0; _i < 2; ++_i) \
;         __builtin_amdgcn_global_load_lds((const unsigned*)((const char*)(gbase) + (voff)[_i]), (PG8_LAS unsigned*)(lds + (bufoff) + ldsw + _i * 8192), 16, 0, 0); } while (0)
; #define PG8_LDA(dst, b, h) do { _Pragma("unroll") for (int m = 0; m < 4; ++m) _Pragma("unroll") for (int k = 0; k < 2; ++k) dst[m][k] = *(const PG8_LAS bf16x8*)(lds + PG8_SA(b, h) + aoff + m * 2048 + k * 1024); } while (0)
; #define PG8_LDB(dst, b, h) do { _Pragma("unroll") for (int n = 0; n < 2; ++n) _Pragma("unroll") for (int k = 0; k < 2; ++k) dst[n][k] = *(const PG8_LAS bf16x8*)(lds + PG8_SB(b, h) + boff + n * 2048 + k * 1024); } while (0)
; #define PG8_WAIT_V(n) asm volatile("s_waitcnt vmcnt(" #n ")" ::: "memory")
; #define PG8_WAIT_L(n) asm volatile("s_waitcnt lgkmcnt(" #n ")" ::: "memory")
; #define PG8_BAR __builtin_amdgcn_s_barrier()
; #define PG8_SCHED __builtin_amdgcn_sched_barrier(0)
; #define PG8_MMA2(ai) PG8_MMA(ai, 0, At, B0)
; #define PG8_MMA2(ai) PG8_MMA(ai, 1, At, B1)
; #define PG8_MMA2(ai) do { PG8_MMA(ai, 0, At, B0); PG8_MMA(ai, 1, At, B1); } while (0)
;     ...
;             PG8_WAIT_V(8); PG8_WAIT_L(0); PG8_BAR; PG8_MMA2(1); PG8_BAR; PG8_SCHED;
;             PG8_LDB(B0, 1, 0); PG8_LDB(B1, 1, 1); PG8_SCHED; PG8_LDA(At, 1, 0); PG8_STAGE(PG8_SA(0, 1), a2 + hstep, voffA);
;             PG8_WAIT_V(8); PG8_WAIT_L(0); PG8_BAR; PG8_MMA2(0); PG8_BAR; PG8_SCHED;
	s_setprio 1
	s_waitcnt lgkmcnt(0)
	v_mfma_f32_16x16x32_bf16 v[60:63], v[128:131], v[212:215], v[60:63]
	v_mfma_f32_16x16x32_bf16 v[56:59], v[136:139], v[212:215], v[56:59]
	v_mfma_f32_16x16x32_bf16 v[44:47], v[128:131], v[220:223], v[44:47]
	v_mfma_f32_16x16x32_bf16 v[40:43], v[136:139], v[220:223], v[40:43]
	v_mfma_f32_16x16x32_bf16 v[28:31], v[128:131], v[228:231], v[28:31]
	v_mfma_f32_16x16x32_bf16 v[24:27], v[136:139], v[228:231], v[24:27]
	v_mfma_f32_16x16x32_bf16 v[12:15], v[128:131], v[236:239], v[12:15]
	v_mfma_f32_16x16x32_bf16 v[8:11], v[136:139], v[236:239], v[8:11]
	v_mfma_f32_16x16x32_bf16 v[60:63], v[132:135], v[216:219], v[60:63]
	v_mfma_f32_16x16x32_bf16 v[56:59], v[140:143], v[216:219], v[56:59]
	v_mfma_f32_16x16x32_bf16 v[44:47], v[132:135], v[224:227], v[44:47]
	v_mfma_f32_16x16x32_bf16 v[40:43], v[140:143], v[224:227], v[40:43]
	v_mfma_f32_16x16x32_bf16 v[28:31], v[132:135], v[232:235], v[28:31]
	v_mfma_f32_16x16x32_bf16 v[24:27], v[140:143], v[232:235], v[24:27]
	v_mfma_f32_16x16x32_bf16 v[12:15], v[132:135], v[240:243], v[12:15]
	v_mfma_f32_16x16x32_bf16 v[8:11], v[140:143], v[240:243], v[8:11]
	s_setprio 0
	s_setprio 1
	v_mfma_f32_16x16x32_bf16 v[52:55], v[168:171], v[212:215], v[52:55]
	v_mfma_f32_16x16x32_bf16 v[48:51], v[192:195], v[212:215], v[48:51]
	v_mfma_f32_16x16x32_bf16 v[36:39], v[168:171], v[220:223], v[36:39]
	v_mfma_f32_16x16x32_bf16 v[32:35], v[192:195], v[220:223], v[32:35]
	v_mfma_f32_16x16x32_bf16 v[20:23], v[168:171], v[228:231], v[20:23]
	v_mfma_f32_16x16x32_bf16 v[16:19], v[192:195], v[228:231], v[16:19]
	v_mfma_f32_16x16x32_bf16 v[4:7], v[168:171], v[236:239], v[4:7]
	v_mfma_f32_16x16x32_bf16 v[0:3], v[192:195], v[236:239], v[0:3]
	v_mfma_f32_16x16x32_bf16 v[52:55], v[188:191], v[216:219], v[52:55]
	v_mfma_f32_16x16x32_bf16 v[48:51], v[196:199], v[216:219], v[48:51]
	v_mfma_f32_16x16x32_bf16 v[36:39], v[188:191], v[224:227], v[36:39]
	v_mfma_f32_16x16x32_bf16 v[32:35], v[196:199], v[224:227], v[32:35]
	v_mfma_f32_16x16x32_bf16 v[20:23], v[188:191], v[232:235], v[20:23]
	v_mfma_f32_16x16x32_bf16 v[16:19], v[196:199], v[232:235], v[16:19]
	v_mfma_f32_16x16x32_bf16 v[4:7], v[188:191], v[240:243], v[4:7]
	v_mfma_f32_16x16x32_bf16 v[0:3], v[196:199], v[240:243], v[0:3]
	s_setprio 0
	s_barrier
	s_add_i32 s82, 0, 0x18000
	s_add_i32 s83, 0, 0x1c000
	v_add_u32_e32 v140, s82, v174
	v_add_u32_e32 v187, s83, v174
	ds_read_b128 v[128:131], v140
	ds_read_b128 v[132:135], v140 offset:1024
	ds_read_b128 v[136:139], v140 offset:2048
	ds_read_b128 v[140:143], v140 offset:3072
	ds_read_b128 v[168:171], v187
	ds_read_b128 v[188:191], v187 offset:1024
	ds_read_b128 v[192:195], v187 offset:2048
	ds_read_b128 v[196:199], v187 offset:3072
	s_add_u32 s34, s70, 0x40000
	s_addc_u32 s35, s71, 0
	s_mov_b32 m0, s77
	s_nop 0
	global_load_lds_dwordx4 v[248:249], off
	s_mov_b32 m0, s78
	v_lshl_add_u64 v[250:251], s[34:35], 0, v[144:145]
	ds_read_b128 v[212:215], v184 offset:32768
	ds_read_b128 v[216:219], v184 offset:33792
	ds_read_b128 v[220:223], v184 offset:34816
	ds_read_b128 v[224:227], v184 offset:35840
	ds_read_b128 v[228:231], v184 offset:36864
	ds_read_b128 v[232:235], v184 offset:37888
	ds_read_b128 v[236:239], v184 offset:38912
	ds_read_b128 v[240:243], v184 offset:39936
	global_load_lds_dwordx4 v[250:251], off
	v_lshl_add_u64 v[250:251], s[34:35], 0, v[148:149]
	s_mov_b32 m0, s79
	s_nop 0
	global_load_lds_dwordx4 v[250:251], off
	s_waitcnt vmcnt(8)
	s_waitcnt lgkmcnt(0)
	s_barrier
	s_setprio 1
	s_waitcnt lgkmcnt(0)
	v_mfma_f32_16x16x32_bf16 v[124:127], v[128:131], v[212:215], v[124:127]
	v_mfma_f32_16x16x32_bf16 v[120:123], v[136:139], v[212:215], v[120:123]
	v_mfma_f32_16x16x32_bf16 v[108:111], v[128:131], v[220:223], v[108:111]
	v_mfma_f32_16x16x32_bf16 v[104:107], v[136:139], v[220:223], v[104:107]
	v_mfma_f32_16x16x32_bf16 v[92:95], v[128:131], v[228:231], v[92:95]
	v_mfma_f32_16x16x32_bf16 v[88:91], v[136:139], v[228:231], v[88:91]
	v_mfma_f32_16x16x32_bf16 v[76:79], v[128:131], v[236:239], v[76:79]
	v_mfma_f32_16x16x32_bf16 v[72:75], v[136:139], v[236:239], v[72:75]
	v_mfma_f32_16x16x32_bf16 v[124:127], v[132:135], v[216:219], v[124:127]
	v_mfma_f32_16x16x32_bf16 v[120:123], v[140:143], v[216:219], v[120:123]
	v_mfma_f32_16x16x32_bf16 v[108:111], v[132:135], v[224:227], v[108:111]
	v_mfma_f32_16x16x32_bf16 v[104:107], v[140:143], v[224:227], v[104:107]
	v_mfma_f32_16x16x32_bf16 v[92:95], v[132:135], v[232:235], v[92:95]
	v_mfma_f32_16x16x32_bf16 v[88:91], v[140:143], v[232:235], v[88:91]
	v_mfma_f32_16x16x32_bf16 v[76:79], v[132:135], v[240:243], v[76:79]
	v_mfma_f32_16x16x32_bf16 v[72:75], v[140:143], v[240:243], v[72:75]
	s_setprio 0
	s_setprio 1
	v_mfma_f32_16x16x32_bf16 v[116:119], v[168:171], v[212:215], v[116:119]
	v_mfma_f32_16x16x32_bf16 v[112:115], v[192:195], v[212:215], v[112:115]
	v_mfma_f32_16x16x32_bf16 v[100:103], v[168:171], v[220:223], v[100:103]
	v_mfma_f32_16x16x32_bf16 v[96:99], v[192:195], v[220:223], v[96:99]
	v_mfma_f32_16x16x32_bf16 v[84:87], v[168:171], v[228:231], v[84:87]
	v_mfma_f32_16x16x32_bf16 v[80:83], v[192:195], v[228:231], v[80:83]
	v_mfma_f32_16x16x32_bf16 v[68:71], v[168:171], v[236:239], v[68:71]
	v_mfma_f32_16x16x32_bf16 v[64:67], v[192:195], v[236:239], v[64:67]
	v_mfma_f32_16x16x32_bf16 v[116:119], v[188:191], v[216:219], v[116:119]
	v_mfma_f32_16x16x32_bf16 v[112:115], v[196:199], v[216:219], v[112:115]
	v_mfma_f32_16x16x32_bf16 v[100:103], v[188:191], v[224:227], v[100:103]
	v_mfma_f32_16x16x32_bf16 v[96:99], v[196:199], v[224:227], v[96:99]
	v_mfma_f32_16x16x32_bf16 v[84:87], v[188:191], v[232:235], v[84:87]
	v_mfma_f32_16x16x32_bf16 v[80:83], v[196:199], v[232:235], v[80:83]
	v_mfma_f32_16x16x32_bf16 v[68:71], v[188:191], v[240:243], v[68:71]
	v_mfma_f32_16x16x32_bf16 v[64:67], v[196:199], v[240:243], v[64:67]
	s_setprio 0
	s_barrier
; #define PG8_STAGE(bufoff, gbase, voff) do { _Pragma("unroll") for (int _i = 0; _i < 2; ++_i) \
;         __builtin_amdgcn_global_load_lds((const unsigned*)((const char*)(gbase) + (voff)[_i]), (PG8_LAS unsigned*)(lds + (bufoff) + ldsw + _i * 8192), 16, 0, 0); } while (0)
; #define PG8_LDA(dst, b, h) do { _Pragma("unroll") for (int m = 0; m < 4; ++m) _Pragma("unroll") for (int k = 0; k < 2; ++k) dst[m][k] = *(const PG8_LAS bf16x8*)(lds + PG8_SA(b, h) + aoff + m * 2048 + k * 1024); } while (0)
; #define PG8_WAIT_V(n) asm volatile("s_waitcnt vmcnt(" #n ")" ::: "memory")
; #define PG8_WAIT_L(n) asm volatile("s_waitcnt lgkmcnt(" #n ")" ::: "memory")
; #define PG8_BAR __builtin_amdgcn_s_barrier()
; #define PG8_SCHED __builtin_amdgcn_sched_barrier(0)
; #define PG8_MMA2(ai) PG8_MMA(ai, 0, At, B0)
; #define PG8_MMA2(ai) PG8_MMA(ai, 1, At, B1)
; #define PG8_MMA2(ai) do { PG8_MMA(ai, 0, At, B0); PG8_MMA(ai, 1, At, B1); } while (0)
;     ...
;         for (int t = 0; t < nt; t += 2) {
;             const bool last = (t == nt - 2);
;             const char* a1 = cA + (size_t)(t + 1) * kstep;
;             const char* a2 = last ? nA : cA + (size_t)(t + 2) * kstep; const char* b2 = last ? nB : cB + (size_t)(t + 2) * kstep;
;             const char* a3 = a2 + kstep; const char* b3 = b2 + kstep;
;     ...
;             PG8_LDA(At, 1, 1); PG8_STAGE(PG8_SB(1, 0), b3, voffB); PG8_STAGE(PG8_SB(1, 1), b3 + hstep, voffB); PG8_STAGE(PG8_SA(1, 0), a3, voffA);
;             PG8_WAIT_V(8); PG8_WAIT_L(0); PG8_BAR; PG8_MMA2(1); PG8_BAR; PG8_SCHED;
	s_add_i32 s34, s82, s75
	v_lshl_add_u64 v[172:173], v[172:173], 0, s[40:41]
	s_mov_b32 m0, s34
	ds_read_b128 v[212:215], v184 offset:49152
	ds_read_b128 v[216:219], v184 offset:50176
	ds_read_b128 v[220:223], v184 offset:51200
	ds_read_b128 v[224:227], v184 offset:52224
	ds_read_b128 v[228:231], v184 offset:53248
	ds_read_b128 v[232:235], v184 offset:54272
	ds_read_b128 v[236:239], v184 offset:55296
	ds_read_b128 v[240:243], v184 offset:56320
	global_load_lds_dwordx4 v[172:173], off
	s_add_i32 m0, s34, 0x2000
	s_add_u32 s34, s68, 0x40080
	v_lshl_add_u64 v[172:173], v[244:245], 0, s[40:41]
	s_addc_u32 s35, s69, 0
	s_add_i32 s68, s83, s75
	global_load_lds_dwordx4 v[172:173], off
	v_lshl_add_u64 v[172:173], s[34:35], 0, v[146:147]
	s_mov_b32 m0, s68
	s_nop 0
	global_load_lds_dwordx4 v[172:173], off
	v_lshl_add_u64 v[172:173], s[34:35], 0, v[150:151]
	s_add_i32 m0, s68, 0x2000
	s_nop 0
	global_load_lds_dwordx4 v[172:173], off
	v_lshl_add_u64 v[172:173], v[246:247], 0, s[40:41]
	s_mov_b32 m0, s85
	s_nop 0
	global_load_lds_dwordx4 v[172:173], off
	v_lshl_add_u64 v[172:173], v[248:249], 0, s[40:41]
	s_nop 0
	s_cmp_lg_u32 s67, 12
	s_cbranch_scc1 .Ldf_skipD_8
	s_mov_b32 m0, s86
	s_nop 0
	global_load_lds_dwordx4 v[172:173], off
.Ldf_skipD_8:
	s_waitcnt vmcnt(7)
	s_waitcnt lgkmcnt(0)
	s_barrier
	s_setprio 1
	s_waitcnt lgkmcnt(0)
	v_mfma_f32_16x16x32_bf16 v[60:63], v[128:131], v[212:215], v[60:63]
	v_mfma_f32_16x16x32_bf16 v[56:59], v[136:139], v[212:215], v[56:59]
	v_mfma_f32_16x16x32_bf16 v[44:47], v[128:131], v[220:223], v[44:47]
	v_mfma_f32_16x16x32_bf16 v[40:43], v[136:139], v[220:223], v[40:43]
	v_mfma_f32_16x16x32_bf16 v[28:31], v[128:131], v[228:231], v[28:31]
	v_mfma_f32_16x16x32_bf16 v[24:27], v[136:139], v[228:231], v[24:27]
	v_mfma_f32_16x16x32_bf16 v[12:15], v[128:131], v[236:239], v[12:15]
	v_mfma_f32_16x16x32_bf16 v[8:11], v[136:139], v[236:239], v[8:11]
	v_mfma_f32_16x16x32_bf16 v[60:63], v[132:135], v[216:219], v[60:63]
	v_mfma_f32_16x16x32_bf16 v[56:59], v[140:143], v[216:219], v[56:59]
	v_mfma_f32_16x16x32_bf16 v[44:47], v[132:135], v[224:227], v[44:47]
	v_mfma_f32_16x16x32_bf16 v[40:43], v[140:143], v[224:227], v[40:43]
	v_mfma_f32_16x16x32_bf16 v[28:31], v[132:135], v[232:235], v[28:31]
	v_mfma_f32_16x16x32_bf16 v[24:27], v[140:143], v[232:235], v[24:27]
	v_mfma_f32_16x16x32_bf16 v[12:15], v[132:135], v[240:243], v[12:15]
	v_mfma_f32_16x16x32_bf16 v[8:11], v[140:143], v[240:243], v[8:11]
	s_setprio 0
	s_setprio 1
	v_mfma_f32_16x16x32_bf16 v[52:55], v[168:171], v[212:215], v[52:55]
	v_mfma_f32_16x16x32_bf16 v[48:51], v[192:195], v[212:215], v[48:51]
	v_mfma_f32_16x16x32_bf16 v[36:39], v[168:171], v[220:223], v[36:39]
	v_mfma_f32_16x16x32_bf16 v[32:35], v[192:195], v[220:223], v[32:35]
	v_mfma_f32_16x16x32_bf16 v[20:23], v[168:171], v[228:231], v[20:23]
	v_mfma_f32_16x16x32_bf16 v[16:19], v[192:195], v[228:231], v[16:19]
	v_mfma_f32_16x16x32_bf16 v[4:7], v[168:171], v[236:239], v[4:7]
	v_mfma_f32_16x16x32_bf16 v[0:3], v[192:195], v[236:239], v[0:3]
	v_mfma_f32_16x16x32_bf16 v[52:55], v[188:191], v[216:219], v[52:55]
	v_mfma_f32_16x16x32_bf16 v[48:51], v[196:199], v[216:219], v[48:51]
	v_mfma_f32_16x16x32_bf16 v[36:39], v[188:191], v[224:227], v[36:39]
	v_mfma_f32_16x16x32_bf16 v[32:35], v[196:199], v[224:227], v[32:35]
	v_mfma_f32_16x16x32_bf16 v[20:23], v[188:191], v[232:235], v[20:23]
	v_mfma_f32_16x16x32_bf16 v[16:19], v[196:199], v[232:235], v[16:19]
	v_mfma_f32_16x16x32_bf16 v[4:7], v[188:191], v[240:243], v[4:7]
	v_mfma_f32_16x16x32_bf16 v[0:3], v[196:199], v[240:243], v[0:3]
	s_setprio 0
	s_barrier
	s_add_i32 s67, s67, 2
	s_add_u32 s59, s59, 0x100
	s_addc_u32 s61, s61, 0
	s_add_u32 s14, s14, 0x100
	s_addc_u32 s15, s15, 0
	s_cmp_gt_u32 s67, 13
	s_cbranch_scc0 .LBB0_1705
	s_and_b64 vcc, exec, s[42:43]
	s_cbranch_vccz .LBB0_1708
	s_barrier

; #define PG8_STAGE(bufoff, gbase, voff) do { _Pragma("unroll") for (int _i = 0; _i < 2; ++_i) \
;         __builtin_amdgcn_global_load_lds((const unsigned*)((const char*)(gbase) + (voff)[_i]), (PG8_LAS unsigned*)(lds + (bufoff) + ldsw + _i * 8192), 16, 0, 0); } while (0)
; #define PG8_LDA(dst, b, h) do { _Pragma("unroll") for (int m = 0; m < 4; ++m) _Pragma("unroll") for (int k = 0; k < 2; ++k) dst[m][k] = *(const PG8_LAS bf16x8*)(lds + PG8_SA(b, h) + aoff + m * 2048 + k * 1024); } while (0)
; #define PG8_LDB(dst, b, h) do { _Pragma("unroll") for (int n = 0; n < 2; ++n) _Pragma("unroll") for (int k = 0; k < 2; ++k) dst[n][k] = *(const PG8_LAS bf16x8*)(lds + PG8_SB(b, h) + boff + n * 2048 + k * 1024); } while (0)
; #define PG8_WAIT_V(n) asm volatile("s_waitcnt vmcnt(" #n ")" ::: "memory")
; #define PG8_WAIT_L(n) asm volatile("s_waitcnt lgkmcnt(" #n ")" ::: "memory")
; #define PG8_BAR __builtin_amdgcn_s_barrier()
; #define PG8_SCHED __builtin_amdgcn_sched_barrier(0)
; #define PG8_MMA2(ai) PG8_MMA(ai, 0, At, B0)
; #define PG8_MMA2(ai) PG8_MMA(ai, 1, At, B1)
; #define PG8_MMA2(ai) do { PG8_MMA(ai, 0, At, B0); PG8_MMA(ai, 1, At, B1); } while (0)
;     ...
;             const bool last = (t == nt - 2);
;             const char* a1 = cA + (size_t)(t + 1) * kstep;
;             const char* a2 = last ? nA : cA + (size_t)(t + 2) * kstep; const char* b2 = last ? nB : cB + (size_t)(t + 2) * kstep;
;             const char* a3 = a2 + kstep; const char* b3 = b2 + kstep;
;             if (last && has_next) S.a_ready(nxt);
;             if constexpr (SP2) {
;             PG8_LDB(B0, 0, 0); PG8_LDB(B1, 0, 1); PG8_SCHED; PG8_LDA(At, 0, 0); PG8_STAGE(PG8_SA(1, 1), a1 + hstep, voffA);
;             PG8_WAIT_V(8); PG8_WAIT_L(0); PG8_BAR; PG8_MMA2(0); PG8_BAR; PG8_SCHED;
;             PG8_LDA(At, 0, 1); PG8_STAGE(PG8_SB(0, 0), b2, voffB); PG8_STAGE(PG8_SB(0, 1), b2 + hstep, voffB); PG8_STAGE(PG8_SA(0, 0), a2, voffA);
;             PG8_WAIT_V(8); PG8_WAIT_L(0); PG8_BAR; PG8_MMA2(1); PG8_BAR; PG8_SCHED;
.LBB0_2334:
	s_cmp_eq_u32 s69, -2
	s_cbranch_scc1 .Ldf_skipA_9
	s_mov_b32 m0, s58
	s_nop 0
	global_load_lds_dwordx4 v[156:157], off
.Ldf_skipA_9:
	ds_read_b128 v[128:131], v161
	ds_read_b128 v[132:135], v161 offset:1024
	ds_read_b128 v[136:139], v161 offset:2048
	ds_read_b128 v[140:143], v161 offset:3072
	ds_read_b128 v[164:167], v162
	ds_read_b128 v[168:171], v162 offset:1024
	ds_read_b128 v[172:175], v162 offset:2048
	ds_read_b128 v[176:179], v162 offset:3072
	s_add_u32 s38, s36, 0x100
	s_addc_u32 s39, s37, 0
	s_cmp_eq_u32 s69, 12
	s_cselect_b32 s43, s19, s39
	s_cselect_b32 s42, s65, s38
	s_cselect_b32 s41, s17, s68
	s_cselect_b32 s40, s66, s67
	v_lshl_add_u64 v[156:157], s[36:37], 0, v[150:151]
	s_add_i32 m0, s27, 0xc000
	ds_read_b128 v[180:183], v163
	ds_read_b128 v[184:187], v163 offset:1024
	ds_read_b128 v[188:191], v163 offset:2048
	ds_read_b128 v[192:195], v163 offset:3072
	ds_read_b128 v[196:199], v163 offset:4096
	ds_read_b128 v[208:211], v163 offset:5120
	ds_read_b128 v[212:215], v163 offset:6144
	ds_read_b128 v[216:219], v163 offset:7168
	global_load_lds_dwordx4 v[156:157], off
	v_lshl_add_u64 v[156:157], s[36:37], 0, v[148:149]
	s_add_i32 m0, s27, 0xe000
	s_nop 0
	global_load_lds_dwordx4 v[156:157], off
	s_waitcnt vmcnt(8)
	s_waitcnt lgkmcnt(0)
	s_barrier
	s_setprio 1
	s_waitcnt lgkmcnt(0)
	v_mfma_f32_16x16x32_bf16 v[124:127], v[128:131], v[180:183], v[124:127]
	v_mfma_f32_16x16x32_bf16 v[120:123], v[136:139], v[180:183], v[120:123]
	v_mfma_f32_16x16x32_bf16 v[108:111], v[128:131], v[188:191], v[108:111]
	v_mfma_f32_16x16x32_bf16 v[104:107], v[136:139], v[188:191], v[104:107]
	v_mfma_f32_16x16x32_bf16 v[92:95], v[128:131], v[196:199], v[92:95]
	v_mfma_f32_16x16x32_bf16 v[88:91], v[136:139], v[196:199], v[88:91]
	v_mfma_f32_16x16x32_bf16 v[76:79], v[128:131], v[212:215], v[76:79]
	v_mfma_f32_16x16x32_bf16 v[72:75], v[136:139], v[212:215], v[72:75]
	v_mfma_f32_16x16x32_bf16 v[124:127], v[132:135], v[184:187], v[124:127]
	v_mfma_f32_16x16x32_bf16 v[120:123], v[140:143], v[184:187], v[120:123]
	v_mfma_f32_16x16x32_bf16 v[108:111], v[132:135], v[192:195], v[108:111]
	v_mfma_f32_16x16x32_bf16 v[104:107], v[140:143], v[192:195], v[104:107]
	v_mfma_f32_16x16x32_bf16 v[92:95], v[132:135], v[208:211], v[92:95]
	v_mfma_f32_16x16x32_bf16 v[88:91], v[140:143], v[208:211], v[88:91]
	v_mfma_f32_16x16x32_bf16 v[76:79], v[132:135], v[216:219], v[76:79]
	v_mfma_f32_16x16x32_bf16 v[72:75], v[140:143], v[216:219], v[72:75]
	s_setprio 0
	s_setprio 1
	v_mfma_f32_16x16x32_bf16 v[116:119], v[164:167], v[180:183], v[116:119]
	v_mfma_f32_16x16x32_bf16 v[112:115], v[172:175], v[180:183], v[112:115]
	v_mfma_f32_16x16x32_bf16 v[100:103], v[164:167], v[188:191], v[100:103]
	v_mfma_f32_16x16x32_bf16 v[96:99], v[172:175], v[188:191], v[96:99]
	v_mfma_f32_16x16x32_bf16 v[84:87], v[164:167], v[196:199], v[84:87]
	v_mfma_f32_16x16x32_bf16 v[80:83], v[172:175], v[196:199], v[80:83]
	v_mfma_f32_16x16x32_bf16 v[68:71], v[164:167], v[212:215], v[68:71]
	v_mfma_f32_16x16x32_bf16 v[64:67], v[172:175], v[212:215], v[64:67]
	v_mfma_f32_16x16x32_bf16 v[116:119], v[168:171], v[184:187], v[116:119]
	v_mfma_f32_16x16x32_bf16 v[112:115], v[176:179], v[184:187], v[112:115]
	v_mfma_f32_16x16x32_bf16 v[100:103], v[168:171], v[192:195], v[100:103]
	v_mfma_f32_16x16x32_bf16 v[96:99], v[176:179], v[192:195], v[96:99]
	v_mfma_f32_16x16x32_bf16 v[84:87], v[168:171], v[208:211], v[84:87]
	v_mfma_f32_16x16x32_bf16 v[80:83], v[176:179], v[208:211], v[80:83]
	v_mfma_f32_16x16x32_bf16 v[68:71], v[168:171], v[216:219], v[68:71]
	v_mfma_f32_16x16x32_bf16 v[64:67], v[176:179], v[216:219], v[64:67]
	s_setprio 0
	s_barrier
	s_add_i32 s34, s3, s48
	v_lshl_add_u64 v[156:157], s[40:41], 0, v[144:145]
	s_mov_b32 m0, s34
	ds_read_b128 v[180:183], v163 offset:16384
	ds_read_b128 v[184:187], v163 offset:17408
	ds_read_b128 v[188:191], v163 offset:18432
	ds_read_b128 v[192:195], v163 offset:19456
	ds_read_b128 v[196:199], v163 offset:20480
	ds_read_b128 v[208:211], v163 offset:21504
	ds_read_b128 v[212:215], v163 offset:22528
	ds_read_b128 v[216:219], v163 offset:23552
	global_load_lds_dwordx4 v[156:157], off
	s_add_i32 m0, s34, 0x2000
	s_add_u32 s34, s40, 0x40000
	v_lshl_add_u64 v[200:201], s[40:41], 0, v[146:147]
	s_addc_u32 s35, s41, 0
	s_add_i32 s36, s62, s48
	global_load_lds_dwordx4 v[200:201], off
	v_lshl_add_u64 v[220:221], s[34:35], 0, v[144:145]
	s_mov_b32 m0, s36
	v_lshl_add_u64 v[222:223], s[42:43], 0, v[146:147]
	global_load_lds_dwordx4 v[220:221], off
	v_lshl_add_u64 v[220:221], s[34:35], 0, v[146:147]
	s_add_i32 m0, s36, 0x2000
	s_nop 0
	global_load_lds_dwordx4 v[220:221], off
	v_lshl_add_u64 v[220:221], s[42:43], 0, v[144:145]
	s_mov_b32 m0, s27
	s_nop 0
	global_load_lds_dwordx4 v[220:221], off
	s_nop 0
	s_waitcnt vmcnt(7)
	s_waitcnt lgkmcnt(0)
	s_barrier
; #define PG8_STAGE(bufoff, gbase, voff) do { _Pragma("unroll") for (int _i = 0; _i < 2; ++_i) \
;         __builtin_amdgcn_global_load_lds((const unsigned*)((const char*)(gbase) + (voff)[_i]), (PG8_LAS unsigned*)(lds + (bufoff) + ldsw + _i * 8192), 16, 0, 0); } while (0)
; #define PG8_LDA(dst, b, h) do { _Pragma("unroll") for (int m = 0; m < 4; ++m) _Pragma("unroll") for (int k = 0; k < 2; ++k) dst[m][k] = *(const PG8_LAS bf16x8*)(lds + PG8_SA(b, h) + aoff + m * 2048 + k * 1024); } while (0)
; #define PG8_LDB(dst, b, h) do { _Pragma("unroll") for (int n = 0; n < 2; ++n) _Pragma("unroll") for (int k = 0; k < 2; ++k) dst[n][k] = *(const PG8_LAS bf16x8*)(lds + PG8_SB(b, h) + boff + n * 2048 + k * 1024); } while (0)
; #define PG8_WAIT_V(n) asm volatile("s_waitcnt vmcnt(" #n ")" ::: "memory")
; #define PG8_WAIT_L(n) asm volatile("s_waitcnt lgkmcnt(" #n ")" ::: "memory")
; #define PG8_BAR __builtin_amdgcn_s_barrier()
; #define PG8_SCHED __builtin_amdgcn_sched_barrier(0)
; #define PG8_MMA2(ai) PG8_MMA(ai, 0, At, B0)
; #define PG8_MMA2(ai) PG8_MMA(ai, 1, At, B1)
; #define PG8_MMA2(ai) do { PG8_MMA(ai, 0, At, B0); PG8_MMA(ai, 1, At, B1); } while (0)
;     ...
;             PG8_WAIT_V(8); PG8_WAIT_L(0); PG8_BAR; PG8_MMA2(1); PG8_BAR; PG8_SCHED;
;             PG8_LDB(B0, 1, 0); PG8_LDB(B1, 1, 1); PG8_SCHED; PG8_LDA(At, 1, 0); PG8_STAGE(PG8_SA(0, 1), a2 + hstep, voffA);
;             PG8_WAIT_V(8); PG8_WAIT_L(0); PG8_BAR; PG8_MMA2(0); PG8_BAR; PG8_SCHED;
	s_setprio 1
	s_waitcnt lgkmcnt(0)
	v_mfma_f32_16x16x32_bf16 v[60:63], v[128:131], v[180:183], v[60:63]
	v_mfma_f32_16x16x32_bf16 v[56:59], v[136:139], v[180:183], v[56:59]
	v_mfma_f32_16x16x32_bf16 v[44:47], v[128:131], v[188:191], v[44:47]
	v_mfma_f32_16x16x32_bf16 v[40:43], v[136:139], v[188:191], v[40:43]
	v_mfma_f32_16x16x32_bf16 v[28:31], v[128:131], v[196:199], v[28:31]
	v_mfma_f32_16x16x32_bf16 v[24:27], v[136:139], v[196:199], v[24:27]
	v_mfma_f32_16x16x32_bf16 v[12:15], v[128:131], v[212:215], v[12:15]
	v_mfma_f32_16x16x32_bf16 v[8:11], v[136:139], v[212:215], v[8:11]
	v_mfma_f32_16x16x32_bf16 v[60:63], v[132:135], v[184:187], v[60:63]
	v_mfma_f32_16x16x32_bf16 v[56:59], v[140:143], v[184:187], v[56:59]
	v_mfma_f32_16x16x32_bf16 v[44:47], v[132:135], v[192:195], v[44:47]
	v_mfma_f32_16x16x32_bf16 v[40:43], v[140:143], v[192:195], v[40:43]
	v_mfma_f32_16x16x32_bf16 v[28:31], v[132:135], v[208:211], v[28:31]
	v_mfma_f32_16x16x32_bf16 v[24:27], v[140:143], v[208:211], v[24:27]
	v_mfma_f32_16x16x32_bf16 v[12:15], v[132:135], v[216:219], v[12:15]
	v_mfma_f32_16x16x32_bf16 v[8:11], v[140:143], v[216:219], v[8:11]
	s_setprio 0
	s_setprio 1
	v_mfma_f32_16x16x32_bf16 v[52:55], v[164:167], v[180:183], v[52:55]
	v_mfma_f32_16x16x32_bf16 v[48:51], v[172:175], v[180:183], v[48:51]
	v_mfma_f32_16x16x32_bf16 v[36:39], v[164:167], v[188:191], v[36:39]
	v_mfma_f32_16x16x32_bf16 v[32:35], v[172:175], v[188:191], v[32:35]
	v_mfma_f32_16x16x32_bf16 v[20:23], v[164:167], v[196:199], v[20:23]
	v_mfma_f32_16x16x32_bf16 v[16:19], v[172:175], v[196:199], v[16:19]
	v_mfma_f32_16x16x32_bf16 v[4:7], v[164:167], v[212:215], v[4:7]
	v_mfma_f32_16x16x32_bf16 v[0:3], v[172:175], v[212:215], v[0:3]
	v_mfma_f32_16x16x32_bf16 v[52:55], v[168:171], v[184:187], v[52:55]
	v_mfma_f32_16x16x32_bf16 v[48:51], v[176:179], v[184:187], v[48:51]
	v_mfma_f32_16x16x32_bf16 v[36:39], v[168:171], v[192:195], v[36:39]
	v_mfma_f32_16x16x32_bf16 v[32:35], v[176:179], v[192:195], v[32:35]
	v_mfma_f32_16x16x32_bf16 v[20:23], v[168:171], v[208:211], v[20:23]
	v_mfma_f32_16x16x32_bf16 v[16:19], v[176:179], v[208:211], v[16:19]
	v_mfma_f32_16x16x32_bf16 v[4:7], v[168:171], v[216:219], v[4:7]
	v_mfma_f32_16x16x32_bf16 v[0:3], v[176:179], v[216:219], v[0:3]
	s_setprio 0
	s_barrier
	s_add_i32 s36, 0, 0x18000
	s_add_i32 s37, 0, 0x1c000
	v_add_u32_e32 v140, s36, v159
	v_add_u32_e32 v176, s37, v159
	ds_read_b128 v[128:131], v140
	ds_read_b128 v[132:135], v140 offset:1024
	ds_read_b128 v[136:139], v140 offset:2048
	ds_read_b128 v[140:143], v140 offset:3072
	ds_read_b128 v[164:167], v176
	ds_read_b128 v[168:171], v176 offset:1024
	ds_read_b128 v[172:175], v176 offset:2048
	ds_read_b128 v[176:179], v176 offset:3072
	s_add_u32 s34, s42, 0x40000
	s_addc_u32 s35, s43, 0
	s_mov_b32 m0, s49
	s_nop 0
	global_load_lds_dwordx4 v[222:223], off
	s_mov_b32 m0, s50
	v_lshl_add_u64 v[224:225], s[34:35], 0, v[144:145]
	ds_read_b128 v[180:183], v163 offset:32768
	ds_read_b128 v[184:187], v163 offset:33792
	ds_read_b128 v[188:191], v163 offset:34816
	ds_read_b128 v[192:195], v163 offset:35840
	ds_read_b128 v[196:199], v163 offset:36864
	ds_read_b128 v[208:211], v163 offset:37888
	ds_read_b128 v[212:215], v163 offset:38912
	ds_read_b128 v[216:219], v163 offset:39936
	global_load_lds_dwordx4 v[224:225], off
	v_lshl_add_u64 v[224:225], s[34:35], 0, v[146:147]
	s_mov_b32 m0, s51
	s_nop 0
	global_load_lds_dwordx4 v[224:225], off
	s_waitcnt vmcnt(8)
	s_waitcnt lgkmcnt(0)
	s_barrier
	s_setprio 1
	s_waitcnt lgkmcnt(0)
	v_mfma_f32_16x16x32_bf16 v[124:127], v[128:131], v[180:183], v[124:127]
	v_mfma_f32_16x16x32_bf16 v[120:123], v[136:139], v[180:183], v[120:123]
	v_mfma_f32_16x16x32_bf16 v[108:111], v[128:131], v[188:191], v[108:111]
	v_mfma_f32_16x16x32_bf16 v[104:107], v[136:139], v[188:191], v[104:107]
	v_mfma_f32_16x16x32_bf16 v[92:95], v[128:131], v[196:199], v[92:95]
	v_mfma_f32_16x16x32_bf16 v[88:91], v[136:139], v[196:199], v[88:91]
	v_mfma_f32_16x16x32_bf16 v[76:79], v[128:131], v[212:215], v[76:79]
	v_mfma_f32_16x16x32_bf16 v[72:75], v[136:139], v[212:215], v[72:75]
	v_mfma_f32_16x16x32_bf16 v[124:127], v[132:135], v[184:187], v[124:127]
	v_mfma_f32_16x16x32_bf16 v[120:123], v[140:143], v[184:187], v[120:123]
	v_mfma_f32_16x16x32_bf16 v[108:111], v[132:135], v[192:195], v[108:111]
	v_mfma_f32_16x16x32_bf16 v[104:107], v[140:143], v[192:195], v[104:107]
	v_mfma_f32_16x16x32_bf16 v[92:95], v[132:135], v[208:211], v[92:95]
	v_mfma_f32_16x16x32_bf16 v[88:91], v[140:143], v[208:211], v[88:91]
	v_mfma_f32_16x16x32_bf16 v[76:79], v[132:135], v[216:219], v[76:79]
	v_mfma_f32_16x16x32_bf16 v[72:75], v[140:143], v[216:219], v[72:75]
	s_setprio 0
	s_setprio 1
	v_mfma_f32_16x16x32_bf16 v[116:119], v[164:167], v[180:183], v[116:119]
	v_mfma_f32_16x16x32_bf16 v[112:115], v[172:175], v[180:183], v[112:115]
	v_mfma_f32_16x16x32_bf16 v[100:103], v[164:167], v[188:191], v[100:103]
	v_mfma_f32_16x16x32_bf16 v[96:99], v[172:175], v[188:191], v[96:99]
	v_mfma_f32_16x16x32_bf16 v[84:87], v[164:167], v[196:199], v[84:87]
	v_mfma_f32_16x16x32_bf16 v[80:83], v[172:175], v[196:199], v[80:83]
	v_mfma_f32_16x16x32_bf16 v[68:71], v[164:167], v[212:215], v[68:71]
	v_mfma_f32_16x16x32_bf16 v[64:67], v[172:175], v[212:215], v[64:67]
	v_mfma_f32_16x16x32_bf16 v[116:119], v[168:171], v[184:187], v[116:119]
	v_mfma_f32_16x16x32_bf16 v[112:115], v[176:179], v[184:187], v[112:115]
	v_mfma_f32_16x16x32_bf16 v[100:103], v[168:171], v[192:195], v[100:103]
	v_mfma_f32_16x16x32_bf16 v[96:99], v[176:179], v[192:195], v[96:99]
	v_mfma_f32_16x16x32_bf16 v[84:87], v[168:171], v[208:211], v[84:87]
	v_mfma_f32_16x16x32_bf16 v[80:83], v[176:179], v[208:211], v[80:83]
	v_mfma_f32_16x16x32_bf16 v[68:71], v[168:171], v[216:219], v[68:71]
	v_mfma_f32_16x16x32_bf16 v[64:67], v[176:179], v[216:219], v[64:67]
	s_setprio 0
	s_barrier
; #define PG8_STAGE(bufoff, gbase, voff) do { _Pragma("unroll") for (int _i = 0; _i < 2; ++_i) \
;         __builtin_amdgcn_global_load_lds((const unsigned*)((const char*)(gbase) + (voff)[_i]), (PG8_LAS unsigned*)(lds + (bufoff) + ldsw + _i * 8192), 16, 0, 0); } while (0)
; #define PG8_LDA(dst, b, h) do { _Pragma("unroll") for (int m = 0; m < 4; ++m) _Pragma("unroll") for (int k = 0; k < 2; ++k) dst[m][k] = *(const PG8_LAS bf16x8*)(lds + PG8_SA(b, h) + aoff + m * 2048 + k * 1024); } while (0)
; #define PG8_WAIT_V(n) asm volatile("s_waitcnt vmcnt(" #n ")" ::: "memory")
; #define PG8_WAIT_L(n) asm volatile("s_waitcnt lgkmcnt(" #n ")" ::: "memory")
; #define PG8_BAR __builtin_amdgcn_s_barrier()
; #define PG8_SCHED __builtin_amdgcn_sched_barrier(0)
; #define PG8_MMA2(ai) PG8_MMA(ai, 0, At, B0)
; #define PG8_MMA2(ai) PG8_MMA(ai, 1, At, B1)
; #define PG8_MMA2(ai) do { PG8_MMA(ai, 0, At, B0); PG8_MMA(ai, 1, At, B1); } while (0)
;     ...
;             PG8_LDA(At, 1, 1); PG8_STAGE(PG8_SB(1, 0), b3, voffB); PG8_STAGE(PG8_SB(1, 1), b3 + hstep, voffB); PG8_STAGE(PG8_SA(1, 0), a3, voffA);
;             PG8_WAIT_V(8); PG8_WAIT_L(0); PG8_BAR; PG8_MMA2(1); PG8_BAR; PG8_SCHED;
	s_add_i32 s34, s36, s48
	v_lshl_add_u64 v[156:157], v[156:157], 0, s[12:13]
	s_mov_b32 m0, s34
	ds_read_b128 v[180:183], v163 offset:49152
	ds_read_b128 v[184:187], v163 offset:50176
	ds_read_b128 v[188:191], v163 offset:51200
	ds_read_b128 v[192:195], v163 offset:52224
	ds_read_b128 v[196:199], v163 offset:53248
	ds_read_b128 v[208:211], v163 offset:54272
	ds_read_b128 v[212:215], v163 offset:55296
	ds_read_b128 v[216:219], v163 offset:56320
	global_load_lds_dwordx4 v[156:157], off
	s_add_i32 m0, s34, 0x2000
	s_add_u32 s34, s40, 0x40080
	v_lshl_add_u64 v[156:157], v[200:201], 0, s[12:13]
	s_addc_u32 s35, s41, 0
	s_add_i32 s36, s37, s48
	global_load_lds_dwordx4 v[156:157], off
	v_lshl_add_u64 v[156:157], s[34:35], 0, v[144:145]
	s_mov_b32 m0, s36
	s_nop 0
	global_load_lds_dwordx4 v[156:157], off
	v_lshl_add_u64 v[156:157], s[34:35], 0, v[146:147]
	s_add_i32 m0, s36, 0x2000
	s_nop 0
	global_load_lds_dwordx4 v[156:157], off
	v_lshl_add_u64 v[156:157], v[220:221], 0, s[12:13]
	s_mov_b32 m0, s57
	s_nop 0
	global_load_lds_dwordx4 v[156:157], off
	v_lshl_add_u64 v[156:157], v[222:223], 0, s[12:13]
	s_nop 0
	s_cmp_lg_u32 s69, 12
	s_cbranch_scc1 .Ldf_skipD_9
	s_mov_b32 m0, s58
	s_nop 0
	global_load_lds_dwordx4 v[156:157], off
.Ldf_skipD_9:
	s_waitcnt vmcnt(7)
	s_waitcnt lgkmcnt(0)
	s_barrier
	s_setprio 1
	s_waitcnt lgkmcnt(0)
	v_mfma_f32_16x16x32_bf16 v[60:63], v[128:131], v[180:183], v[60:63]
	v_mfma_f32_16x16x32_bf16 v[56:59], v[136:139], v[180:183], v[56:59]
	v_mfma_f32_16x16x32_bf16 v[44:47], v[128:131], v[188:191], v[44:47]
	v_mfma_f32_16x16x32_bf16 v[40:43], v[136:139], v[188:191], v[40:43]
	v_mfma_f32_16x16x32_bf16 v[28:31], v[128:131], v[196:199], v[28:31]
	v_mfma_f32_16x16x32_bf16 v[24:27], v[136:139], v[196:199], v[24:27]
	v_mfma_f32_16x16x32_bf16 v[12:15], v[128:131], v[212:215], v[12:15]
	v_mfma_f32_16x16x32_bf16 v[8:11], v[136:139], v[212:215], v[8:11]
	v_mfma_f32_16x16x32_bf16 v[60:63], v[132:135], v[184:187], v[60:63]
	v_mfma_f32_16x16x32_bf16 v[56:59], v[140:143], v[184:187], v[56:59]
	v_mfma_f32_16x16x32_bf16 v[44:47], v[132:135], v[192:195], v[44:47]
	v_mfma_f32_16x16x32_bf16 v[40:43], v[140:143], v[192:195], v[40:43]
	v_mfma_f32_16x16x32_bf16 v[28:31], v[132:135], v[208:211], v[28:31]
	v_mfma_f32_16x16x32_bf16 v[24:27], v[140:143], v[208:211], v[24:27]
	v_mfma_f32_16x16x32_bf16 v[12:15], v[132:135], v[216:219], v[12:15]
	v_mfma_f32_16x16x32_bf16 v[8:11], v[140:143], v[216:219], v[8:11]
	s_setprio 0
	s_setprio 1
	v_mfma_f32_16x16x32_bf16 v[52:55], v[164:167], v[180:183], v[52:55]
	v_mfma_f32_16x16x32_bf16 v[48:51], v[172:175], v[180:183], v[48:51]
	v_mfma_f32_16x16x32_bf16 v[36:39], v[164:167], v[188:191], v[36:39]
	v_mfma_f32_16x16x32_bf16 v[32:35], v[172:175], v[188:191], v[32:35]
	v_mfma_f32_16x16x32_bf16 v[20:23], v[164:167], v[196:199], v[20:23]
	v_mfma_f32_16x16x32_bf16 v[16:19], v[172:175], v[196:199], v[16:19]
	v_mfma_f32_16x16x32_bf16 v[4:7], v[164:167], v[212:215], v[4:7]
	v_mfma_f32_16x16x32_bf16 v[0:3], v[172:175], v[212:215], v[0:3]
	v_mfma_f32_16x16x32_bf16 v[52:55], v[168:171], v[184:187], v[52:55]
	v_mfma_f32_16x16x32_bf16 v[48:51], v[176:179], v[184:187], v[48:51]
	v_mfma_f32_16x16x32_bf16 v[36:39], v[168:171], v[192:195], v[36:39]
	v_mfma_f32_16x16x32_bf16 v[32:35], v[176:179], v[192:195], v[32:35]
	v_mfma_f32_16x16x32_bf16 v[20:23], v[168:171], v[208:211], v[20:23]
	v_mfma_f32_16x16x32_bf16 v[16:19], v[176:179], v[208:211], v[16:19]
	v_mfma_f32_16x16x32_bf16 v[4:7], v[168:171], v[216:219], v[4:7]
	v_mfma_f32_16x16x32_bf16 v[0:3], v[176:179], v[216:219], v[0:3]
	s_setprio 0
	s_barrier
	s_add_i32 s69, s69, 2
	s_add_u32 s67, s67, 0x100
	s_addc_u32 s68, s68, 0
	s_cmp_gt_u32 s69, 13
	s_mov_b64 s[36:37], s[38:39]
	s_cbranch_scc0 .LBB0_2334
	s_and_b64 vcc, exec, s[14:15]
	s_cbranch_vccz .LBB0_2337
	s_barrier

; #define PG8_STAGE(bufoff, gbase, voff) do { _Pragma("unroll") for (int _i = 0; _i < 2; ++_i) \
;         __builtin_amdgcn_global_load_lds((const unsigned*)((const char*)(gbase) + (voff)[_i]), (PG8_LAS unsigned*)(lds + (bufoff) + ldsw + _i * 8192), 16, 0, 0); } while (0)
; #define PG8_LDA(dst, b, h) do { _Pragma("unroll") for (int m = 0; m < 4; ++m) _Pragma("unroll") for (int k = 0; k < 2; ++k) dst[m][k] = *(const PG8_LAS bf16x8*)(lds + PG8_SA(b, h) + aoff + m * 2048 + k * 1024); } while (0)
; #define PG8_LDB(dst, b, h) do { _Pragma("unroll") for (int n = 0; n < 2; ++n) _Pragma("unroll") for (int k = 0; k < 2; ++k) dst[n][k] = *(const PG8_LAS bf16x8*)(lds + PG8_SB(b, h) + boff + n * 2048 + k * 1024); } while (0)
; #define PG8_WAIT_V(n) asm volatile("s_waitcnt vmcnt(" #n ")" ::: "memory")
; #define PG8_WAIT_L(n) asm volatile("s_waitcnt lgkmcnt(" #n ")" ::: "memory")
; #define PG8_BAR __builtin_amdgcn_s_barrier()
; #define PG8_SCHED __builtin_amdgcn_sched_barrier(0)
; #define PG8_MMA2(ai) PG8_MMA(ai, 0, At, B0)
; #define PG8_MMA2(ai) PG8_MMA(ai, 1, At, B1)
; #define PG8_MMA2(ai) do { PG8_MMA(ai, 0, At, B0); PG8_MMA(ai, 1, At, B1); } while (0)
;     ...
;             PG8_LDB(B0, 0, 0); PG8_LDB(B1, 0, 1); PG8_SCHED; PG8_LDA(At, 0, 0); PG8_STAGE(PG8_SA(1, 1), a1 + hstep, voffA);
;             PG8_WAIT_V(8); PG8_WAIT_L(0); PG8_BAR; PG8_MMA2(0); PG8_BAR; PG8_SCHED;
;             PG8_LDA(At, 0, 1); PG8_STAGE(PG8_SB(0, 0), b2, voffB); PG8_STAGE(PG8_SB(0, 1), b2 + hstep, voffB); PG8_STAGE(PG8_SA(0, 0), a2, voffA);
;             PG8_WAIT_V(8); PG8_WAIT_L(0); PG8_BAR; PG8_MMA2(1); PG8_BAR; PG8_SCHED;
.LBB0_2461:
	s_cmp_eq_u32 s63, -2
	s_cbranch_scc1 .Ldf_skipA_10
	s_mov_b32 m0, s53
	s_nop 0
	global_load_lds_dwordx4 v[144:145], off
.Ldf_skipA_10:
	ds_read_b128 v[152:155], v149
	ds_read_b128 v[156:159], v149 offset:1024
	ds_read_b128 v[160:163], v149 offset:2048
	ds_read_b128 v[164:167], v149 offset:3072
	ds_read_b128 v[168:171], v150
	ds_read_b128 v[172:175], v150 offset:1024
	ds_read_b128 v[176:179], v150 offset:2048
	ds_read_b128 v[180:183], v150 offset:3072
	s_add_u32 s34, s36, 0xfffc0080
	s_addc_u32 s35, s37, -1
	s_cmp_eq_u32 s63, 12
	s_cselect_b32 s41, s19, s35
	s_cselect_b32 s40, s59, s34
	s_cselect_b32 s39, s17, s62
	s_cselect_b32 s38, s60, s61
	v_lshl_add_u64 v[144:145], s[36:37], 0, v[138:139]
	s_add_i32 m0, s27, 0xc000
	ds_read_b128 v[184:187], v151
	ds_read_b128 v[188:191], v151 offset:1024
	ds_read_b128 v[192:195], v151 offset:2048
	ds_read_b128 v[196:199], v151 offset:3072
	ds_read_b128 v[208:211], v151 offset:4096
	ds_read_b128 v[212:215], v151 offset:5120
	ds_read_b128 v[216:219], v151 offset:6144
	ds_read_b128 v[220:223], v151 offset:7168
	global_load_lds_dwordx4 v[144:145], off
	v_lshl_add_u64 v[144:145], s[36:37], 0, v[136:137]
	s_add_i32 m0, s27, 0xe000
	s_nop 0
	global_load_lds_dwordx4 v[144:145], off
	s_waitcnt vmcnt(8)
	s_waitcnt lgkmcnt(0)
	s_barrier
	s_setprio 1
	s_waitcnt lgkmcnt(0)
	v_mfma_f32_16x16x32_bf16 v[124:127], v[152:155], v[184:187], v[124:127]
	v_mfma_f32_16x16x32_bf16 v[120:123], v[160:163], v[184:187], v[120:123]
	v_mfma_f32_16x16x32_bf16 v[108:111], v[152:155], v[192:195], v[108:111]
	v_mfma_f32_16x16x32_bf16 v[104:107], v[160:163], v[192:195], v[104:107]
	v_mfma_f32_16x16x32_bf16 v[92:95], v[152:155], v[208:211], v[92:95]
	v_mfma_f32_16x16x32_bf16 v[88:91], v[160:163], v[208:211], v[88:91]
	v_mfma_f32_16x16x32_bf16 v[76:79], v[152:155], v[216:219], v[76:79]
	v_mfma_f32_16x16x32_bf16 v[72:75], v[160:163], v[216:219], v[72:75]
	v_mfma_f32_16x16x32_bf16 v[124:127], v[156:159], v[188:191], v[124:127]
	v_mfma_f32_16x16x32_bf16 v[120:123], v[164:167], v[188:191], v[120:123]
	v_mfma_f32_16x16x32_bf16 v[108:111], v[156:159], v[196:199], v[108:111]
	v_mfma_f32_16x16x32_bf16 v[104:107], v[164:167], v[196:199], v[104:107]
	v_mfma_f32_16x16x32_bf16 v[92:95], v[156:159], v[212:215], v[92:95]
	v_mfma_f32_16x16x32_bf16 v[88:91], v[164:167], v[212:215], v[88:91]
	v_mfma_f32_16x16x32_bf16 v[76:79], v[156:159], v[220:223], v[76:79]
	v_mfma_f32_16x16x32_bf16 v[72:75], v[164:167], v[220:223], v[72:75]
	s_setprio 0
	s_setprio 1
	v_mfma_f32_16x16x32_bf16 v[116:119], v[168:171], v[184:187], v[116:119]
	v_mfma_f32_16x16x32_bf16 v[112:115], v[176:179], v[184:187], v[112:115]
	v_mfma_f32_16x16x32_bf16 v[100:103], v[168:171], v[192:195], v[100:103]
	v_mfma_f32_16x16x32_bf16 v[96:99], v[176:179], v[192:195], v[96:99]
	v_mfma_f32_16x16x32_bf16 v[84:87], v[168:171], v[208:211], v[84:87]
	v_mfma_f32_16x16x32_bf16 v[80:83], v[176:179], v[208:211], v[80:83]
	v_mfma_f32_16x16x32_bf16 v[68:71], v[168:171], v[216:219], v[68:71]
	v_mfma_f32_16x16x32_bf16 v[64:67], v[176:179], v[216:219], v[64:67]
	v_mfma_f32_16x16x32_bf16 v[116:119], v[172:175], v[188:191], v[116:119]
	v_mfma_f32_16x16x32_bf16 v[112:115], v[180:183], v[188:191], v[112:115]
	v_mfma_f32_16x16x32_bf16 v[100:103], v[172:175], v[196:199], v[100:103]
	v_mfma_f32_16x16x32_bf16 v[96:99], v[180:183], v[196:199], v[96:99]
	v_mfma_f32_16x16x32_bf16 v[84:87], v[172:175], v[212:215], v[84:87]
	v_mfma_f32_16x16x32_bf16 v[80:83], v[180:183], v[212:215], v[80:83]
	v_mfma_f32_16x16x32_bf16 v[68:71], v[172:175], v[220:223], v[68:71]
	v_mfma_f32_16x16x32_bf16 v[64:67], v[180:183], v[220:223], v[64:67]
	s_setprio 0
	s_barrier
	s_add_i32 s34, s3, s45
	v_lshl_add_u64 v[144:145], s[38:39], 0, v[132:133]
	s_mov_b32 m0, s34
	ds_read_b128 v[184:187], v151 offset:16384
	ds_read_b128 v[188:191], v151 offset:17408
	ds_read_b128 v[192:195], v151 offset:18432
	ds_read_b128 v[196:199], v151 offset:19456
	ds_read_b128 v[208:211], v151 offset:20480
	ds_read_b128 v[212:215], v151 offset:21504
	ds_read_b128 v[216:219], v151 offset:22528
	ds_read_b128 v[220:223], v151 offset:23552
	global_load_lds_dwordx4 v[144:145], off
	s_add_i32 m0, s34, 0x2000
	s_add_u32 s34, s38, 0x40000
	v_lshl_add_u64 v[200:201], s[38:39], 0, v[128:129]
	s_addc_u32 s35, s39, 0
	s_add_i32 s64, s56, s45
	global_load_lds_dwordx4 v[200:201], off
	v_lshl_add_u64 v[224:225], s[34:35], 0, v[132:133]
	s_mov_b32 m0, s64
	v_lshl_add_u64 v[226:227], s[40:41], 0, v[130:131]
	global_load_lds_dwordx4 v[224:225], off
	v_lshl_add_u64 v[224:225], s[34:35], 0, v[128:129]
	s_add_i32 m0, s64, 0x2000
	s_nop 0
	global_load_lds_dwordx4 v[224:225], off
	v_lshl_add_u64 v[224:225], s[40:41], 0, v[134:135]
	s_mov_b32 m0, s27
	s_nop 0
	global_load_lds_dwordx4 v[224:225], off
	s_nop 0
	s_waitcnt vmcnt(7)
	s_waitcnt lgkmcnt(0)
	s_barrier
; #define PG8_STAGE(bufoff, gbase, voff) do { _Pragma("unroll") for (int _i = 0; _i < 2; ++_i) \
;         __builtin_amdgcn_global_load_lds((const unsigned*)((const char*)(gbase) + (voff)[_i]), (PG8_LAS unsigned*)(lds + (bufoff) + ldsw + _i * 8192), 16, 0, 0); } while (0)
; #define PG8_LDA(dst, b, h) do { _Pragma("unroll") for (int m = 0; m < 4; ++m) _Pragma("unroll") for (int k = 0; k < 2; ++k) dst[m][k] = *(const PG8_LAS bf16x8*)(lds + PG8_SA(b, h) + aoff + m * 2048 + k * 1024); } while (0)
; #define PG8_LDB(dst, b, h) do { _Pragma("unroll") for (int n = 0; n < 2; ++n) _Pragma("unroll") for (int k = 0; k < 2; ++k) dst[n][k] = *(const PG8_LAS bf16x8*)(lds + PG8_SB(b, h) + boff + n * 2048 + k * 1024); } while (0)
; #define PG8_WAIT_V(n) asm volatile("s_waitcnt vmcnt(" #n ")" ::: "memory")
; #define PG8_WAIT_L(n) asm volatile("s_waitcnt lgkmcnt(" #n ")" ::: "memory")
; #define PG8_BAR __builtin_amdgcn_s_barrier()
; #define PG8_SCHED __builtin_amdgcn_sched_barrier(0)
; #define PG8_MMA2(ai) PG8_MMA(ai, 0, At, B0)
; #define PG8_MMA2(ai) PG8_MMA(ai, 1, At, B1)
; #define PG8_MMA2(ai) do { PG8_MMA(ai, 0, At, B0); PG8_MMA(ai, 1, At, B1); } while (0)
;     ...
;             PG8_WAIT_V(8); PG8_WAIT_L(0); PG8_BAR; PG8_MMA2(1); PG8_BAR; PG8_SCHED;
;             PG8_LDB(B0, 1, 0); PG8_LDB(B1, 1, 1); PG8_SCHED; PG8_LDA(At, 1, 0); PG8_STAGE(PG8_SA(0, 1), a2 + hstep, voffA);
;             PG8_WAIT_V(8); PG8_WAIT_L(0); PG8_BAR; PG8_MMA2(0); PG8_BAR; PG8_SCHED;
	s_setprio 1
	s_waitcnt lgkmcnt(0)
	v_mfma_f32_16x16x32_bf16 v[60:63], v[152:155], v[184:187], v[60:63]
	v_mfma_f32_16x16x32_bf16 v[56:59], v[160:163], v[184:187], v[56:59]
	v_mfma_f32_16x16x32_bf16 v[44:47], v[152:155], v[192:195], v[44:47]
	v_mfma_f32_16x16x32_bf16 v[40:43], v[160:163], v[192:195], v[40:43]
	v_mfma_f32_16x16x32_bf16 v[28:31], v[152:155], v[208:211], v[28:31]
	v_mfma_f32_16x16x32_bf16 v[24:27], v[160:163], v[208:211], v[24:27]
	v_mfma_f32_16x16x32_bf16 v[12:15], v[152:155], v[216:219], v[12:15]
	v_mfma_f32_16x16x32_bf16 v[8:11], v[160:163], v[216:219], v[8:11]
	v_mfma_f32_16x16x32_bf16 v[60:63], v[156:159], v[188:191], v[60:63]
	v_mfma_f32_16x16x32_bf16 v[56:59], v[164:167], v[188:191], v[56:59]
	v_mfma_f32_16x16x32_bf16 v[44:47], v[156:159], v[196:199], v[44:47]
	v_mfma_f32_16x16x32_bf16 v[40:43], v[164:167], v[196:199], v[40:43]
	v_mfma_f32_16x16x32_bf16 v[28:31], v[156:159], v[212:215], v[28:31]
	v_mfma_f32_16x16x32_bf16 v[24:27], v[164:167], v[212:215], v[24:27]
	v_mfma_f32_16x16x32_bf16 v[12:15], v[156:159], v[220:223], v[12:15]
	v_mfma_f32_16x16x32_bf16 v[8:11], v[164:167], v[220:223], v[8:11]
	s_setprio 0
	s_setprio 1
	v_mfma_f32_16x16x32_bf16 v[52:55], v[168:171], v[184:187], v[52:55]
	v_mfma_f32_16x16x32_bf16 v[48:51], v[176:179], v[184:187], v[48:51]
	v_mfma_f32_16x16x32_bf16 v[36:39], v[168:171], v[192:195], v[36:39]
	v_mfma_f32_16x16x32_bf16 v[32:35], v[176:179], v[192:195], v[32:35]
	v_mfma_f32_16x16x32_bf16 v[20:23], v[168:171], v[208:211], v[20:23]
	v_mfma_f32_16x16x32_bf16 v[16:19], v[176:179], v[208:211], v[16:19]
	v_mfma_f32_16x16x32_bf16 v[4:7], v[168:171], v[216:219], v[4:7]
	v_mfma_f32_16x16x32_bf16 v[0:3], v[176:179], v[216:219], v[0:3]
	v_mfma_f32_16x16x32_bf16 v[52:55], v[172:175], v[188:191], v[52:55]
	v_mfma_f32_16x16x32_bf16 v[48:51], v[180:183], v[188:191], v[48:51]
	v_mfma_f32_16x16x32_bf16 v[36:39], v[172:175], v[196:199], v[36:39]
	v_mfma_f32_16x16x32_bf16 v[32:35], v[180:183], v[196:199], v[32:35]
	v_mfma_f32_16x16x32_bf16 v[20:23], v[172:175], v[212:215], v[20:23]
	v_mfma_f32_16x16x32_bf16 v[16:19], v[180:183], v[212:215], v[16:19]
	v_mfma_f32_16x16x32_bf16 v[4:7], v[172:175], v[220:223], v[4:7]
	v_mfma_f32_16x16x32_bf16 v[0:3], v[180:183], v[220:223], v[0:3]
	s_setprio 0
	s_barrier
	s_add_i32 s64, 0, 0x18000
	s_add_i32 s65, 0, 0x1c000
	v_add_u32_e32 v164, s64, v147
	v_add_u32_e32 v180, s65, v147
	ds_read_b128 v[152:155], v164
	ds_read_b128 v[156:159], v164 offset:1024
	ds_read_b128 v[160:163], v164 offset:2048
	ds_read_b128 v[164:167], v164 offset:3072
	ds_read_b128 v[168:171], v180
	ds_read_b128 v[172:175], v180 offset:1024
	ds_read_b128 v[176:179], v180 offset:2048
	ds_read_b128 v[180:183], v180 offset:3072
	s_add_u32 s34, s40, 0x40000
	s_addc_u32 s35, s41, 0
	s_mov_b32 m0, s48
	s_nop 0
	global_load_lds_dwordx4 v[226:227], off
	s_mov_b32 m0, s49
	v_lshl_add_u64 v[228:229], s[34:35], 0, v[134:135]
	ds_read_b128 v[184:187], v151 offset:32768
	ds_read_b128 v[188:191], v151 offset:33792
	ds_read_b128 v[192:195], v151 offset:34816
	ds_read_b128 v[196:199], v151 offset:35840
	ds_read_b128 v[208:211], v151 offset:36864
	ds_read_b128 v[212:215], v151 offset:37888
	ds_read_b128 v[216:219], v151 offset:38912
	ds_read_b128 v[220:223], v151 offset:39936
	global_load_lds_dwordx4 v[228:229], off
	v_lshl_add_u64 v[228:229], s[34:35], 0, v[130:131]
	s_mov_b32 m0, s50
	s_nop 0
	global_load_lds_dwordx4 v[228:229], off
	s_waitcnt vmcnt(8)
	s_waitcnt lgkmcnt(0)
	s_barrier
	s_setprio 1
	s_waitcnt lgkmcnt(0)
	v_mfma_f32_16x16x32_bf16 v[124:127], v[152:155], v[184:187], v[124:127]
	v_mfma_f32_16x16x32_bf16 v[120:123], v[160:163], v[184:187], v[120:123]
	v_mfma_f32_16x16x32_bf16 v[108:111], v[152:155], v[192:195], v[108:111]
	v_mfma_f32_16x16x32_bf16 v[104:107], v[160:163], v[192:195], v[104:107]
	v_mfma_f32_16x16x32_bf16 v[92:95], v[152:155], v[208:211], v[92:95]
	v_mfma_f32_16x16x32_bf16 v[88:91], v[160:163], v[208:211], v[88:91]
	v_mfma_f32_16x16x32_bf16 v[76:79], v[152:155], v[216:219], v[76:79]
	v_mfma_f32_16x16x32_bf16 v[72:75], v[160:163], v[216:219], v[72:75]
	v_mfma_f32_16x16x32_bf16 v[124:127], v[156:159], v[188:191], v[124:127]
	v_mfma_f32_16x16x32_bf16 v[120:123], v[164:167], v[188:191], v[120:123]
	v_mfma_f32_16x16x32_bf16 v[108:111], v[156:159], v[196:199], v[108:111]
	v_mfma_f32_16x16x32_bf16 v[104:107], v[164:167], v[196:199], v[104:107]
	v_mfma_f32_16x16x32_bf16 v[92:95], v[156:159], v[212:215], v[92:95]
	v_mfma_f32_16x16x32_bf16 v[88:91], v[164:167], v[212:215], v[88:91]
	v_mfma_f32_16x16x32_bf16 v[76:79], v[156:159], v[220:223], v[76:79]
	v_mfma_f32_16x16x32_bf16 v[72:75], v[164:167], v[220:223], v[72:75]
	s_setprio 0
	s_setprio 1
	v_mfma_f32_16x16x32_bf16 v[116:119], v[168:171], v[184:187], v[116:119]
	v_mfma_f32_16x16x32_bf16 v[112:115], v[176:179], v[184:187], v[112:115]
	v_mfma_f32_16x16x32_bf16 v[100:103], v[168:171], v[192:195], v[100:103]
	v_mfma_f32_16x16x32_bf16 v[96:99], v[176:179], v[192:195], v[96:99]
	v_mfma_f32_16x16x32_bf16 v[84:87], v[168:171], v[208:211], v[84:87]
	v_mfma_f32_16x16x32_bf16 v[80:83], v[176:179], v[208:211], v[80:83]
	v_mfma_f32_16x16x32_bf16 v[68:71], v[168:171], v[216:219], v[68:71]
	v_mfma_f32_16x16x32_bf16 v[64:67], v[176:179], v[216:219], v[64:67]
	v_mfma_f32_16x16x32_bf16 v[116:119], v[172:175], v[188:191], v[116:119]
	v_mfma_f32_16x16x32_bf16 v[112:115], v[180:183], v[188:191], v[112:115]
	v_mfma_f32_16x16x32_bf16 v[100:103], v[172:175], v[196:199], v[100:103]
	v_mfma_f32_16x16x32_bf16 v[96:99], v[180:183], v[196:199], v[96:99]
	v_mfma_f32_16x16x32_bf16 v[84:87], v[172:175], v[212:215], v[84:87]
	v_mfma_f32_16x16x32_bf16 v[80:83], v[180:183], v[212:215], v[80:83]
	v_mfma_f32_16x16x32_bf16 v[68:71], v[172:175], v[220:223], v[68:71]
	v_mfma_f32_16x16x32_bf16 v[64:67], v[180:183], v[220:223], v[64:67]
	s_setprio 0
	s_barrier
; #define PG8_STAGE(bufoff, gbase, voff) do { _Pragma("unroll") for (int _i = 0; _i < 2; ++_i) \
;         __builtin_amdgcn_global_load_lds((const unsigned*)((const char*)(gbase) + (voff)[_i]), (PG8_LAS unsigned*)(lds + (bufoff) + ldsw + _i * 8192), 16, 0, 0); } while (0)
; #define PG8_LDA(dst, b, h) do { _Pragma("unroll") for (int m = 0; m < 4; ++m) _Pragma("unroll") for (int k = 0; k < 2; ++k) dst[m][k] = *(const PG8_LAS bf16x8*)(lds + PG8_SA(b, h) + aoff + m * 2048 + k * 1024); } while (0)
; #define PG8_WAIT_V(n) asm volatile("s_waitcnt vmcnt(" #n ")" ::: "memory")
; #define PG8_WAIT_L(n) asm volatile("s_waitcnt lgkmcnt(" #n ")" ::: "memory")
; #define PG8_BAR __builtin_amdgcn_s_barrier()
; #define PG8_SCHED __builtin_amdgcn_sched_barrier(0)
; #define PG8_MMA2(ai) PG8_MMA(ai, 0, At, B0)
; #define PG8_MMA2(ai) PG8_MMA(ai, 1, At, B1)
; #define PG8_MMA2(ai) do { PG8_MMA(ai, 0, At, B0); PG8_MMA(ai, 1, At, B1); } while (0)
;     ...
;             PG8_LDA(At, 1, 1); PG8_STAGE(PG8_SB(1, 0), b3, voffB); PG8_STAGE(PG8_SB(1, 1), b3 + hstep, voffB); PG8_STAGE(PG8_SA(1, 0), a3, voffA);
;             PG8_WAIT_V(8); PG8_WAIT_L(0); PG8_BAR; PG8_MMA2(1); PG8_BAR; PG8_SCHED;
	s_add_i32 s34, s64, s45
	v_lshl_add_u64 v[144:145], v[144:145], 0, s[12:13]
	s_mov_b32 m0, s34
	ds_read_b128 v[184:187], v151 offset:49152
	ds_read_b128 v[188:191], v151 offset:50176
	ds_read_b128 v[192:195], v151 offset:51200
	ds_read_b128 v[196:199], v151 offset:52224
	ds_read_b128 v[208:211], v151 offset:53248
	ds_read_b128 v[212:215], v151 offset:54272
	ds_read_b128 v[216:219], v151 offset:55296
	ds_read_b128 v[220:223], v151 offset:56320
	global_load_lds_dwordx4 v[144:145], off
	s_add_i32 m0, s34, 0x2000
	s_add_u32 s34, s38, 0x40080
	v_lshl_add_u64 v[144:145], v[200:201], 0, s[12:13]
	s_addc_u32 s35, s39, 0
	s_add_i32 s38, s65, s45
	global_load_lds_dwordx4 v[144:145], off
	v_lshl_add_u64 v[144:145], s[34:35], 0, v[132:133]
	s_mov_b32 m0, s38
	s_nop 0
	global_load_lds_dwordx4 v[144:145], off
	v_lshl_add_u64 v[144:145], s[34:35], 0, v[128:129]
	s_add_i32 m0, s38, 0x2000
	s_nop 0
	global_load_lds_dwordx4 v[144:145], off
	v_lshl_add_u64 v[144:145], v[224:225], 0, s[12:13]
	s_mov_b32 m0, s52
	s_nop 0
	global_load_lds_dwordx4 v[144:145], off
	v_lshl_add_u64 v[144:145], v[226:227], 0, s[12:13]
	s_nop 0
	s_cmp_lg_u32 s63, 12
	s_cbranch_scc1 .Ldf_skipD_10
	s_mov_b32 m0, s53
	s_nop 0
	global_load_lds_dwordx4 v[144:145], off
.Ldf_skipD_10:
	s_waitcnt vmcnt(7)
	s_waitcnt lgkmcnt(0)
	s_barrier
	s_setprio 1
	s_waitcnt lgkmcnt(0)
	v_mfma_f32_16x16x32_bf16 v[60:63], v[152:155], v[184:187], v[60:63]
	v_mfma_f32_16x16x32_bf16 v[56:59], v[160:163], v[184:187], v[56:59]
	v_mfma_f32_16x16x32_bf16 v[44:47], v[152:155], v[192:195], v[44:47]
	v_mfma_f32_16x16x32_bf16 v[40:43], v[160:163], v[192:195], v[40:43]
	v_mfma_f32_16x16x32_bf16 v[28:31], v[152:155], v[208:211], v[28:31]
	v_mfma_f32_16x16x32_bf16 v[24:27], v[160:163], v[208:211], v[24:27]
	v_mfma_f32_16x16x32_bf16 v[12:15], v[152:155], v[216:219], v[12:15]
	v_mfma_f32_16x16x32_bf16 v[8:11], v[160:163], v[216:219], v[8:11]
	v_mfma_f32_16x16x32_bf16 v[60:63], v[156:159], v[188:191], v[60:63]
	v_mfma_f32_16x16x32_bf16 v[56:59], v[164:167], v[188:191], v[56:59]
	v_mfma_f32_16x16x32_bf16 v[44:47], v[156:159], v[196:199], v[44:47]
	v_mfma_f32_16x16x32_bf16 v[40:43], v[164:167], v[196:199], v[40:43]
	v_mfma_f32_16x16x32_bf16 v[28:31], v[156:159], v[212:215], v[28:31]
	v_mfma_f32_16x16x32_bf16 v[24:27], v[164:167], v[212:215], v[24:27]
	v_mfma_f32_16x16x32_bf16 v[12:15], v[156:159], v[220:223], v[12:15]
	v_mfma_f32_16x16x32_bf16 v[8:11], v[164:167], v[220:223], v[8:11]
	s_setprio 0
	s_setprio 1
	v_mfma_f32_16x16x32_bf16 v[52:55], v[168:171], v[184:187], v[52:55]
	v_mfma_f32_16x16x32_bf16 v[48:51], v[176:179], v[184:187], v[48:51]
	v_mfma_f32_16x16x32_bf16 v[36:39], v[168:171], v[192:195], v[36:39]
	v_mfma_f32_16x16x32_bf16 v[32:35], v[176:179], v[192:195], v[32:35]
	v_mfma_f32_16x16x32_bf16 v[20:23], v[168:171], v[208:211], v[20:23]
	v_mfma_f32_16x16x32_bf16 v[16:19], v[176:179], v[208:211], v[16:19]
	v_mfma_f32_16x16x32_bf16 v[4:7], v[168:171], v[216:219], v[4:7]
	v_mfma_f32_16x16x32_bf16 v[0:3], v[176:179], v[216:219], v[0:3]
	v_mfma_f32_16x16x32_bf16 v[52:55], v[172:175], v[188:191], v[52:55]
	v_mfma_f32_16x16x32_bf16 v[48:51], v[180:183], v[188:191], v[48:51]
	v_mfma_f32_16x16x32_bf16 v[36:39], v[172:175], v[196:199], v[36:39]
	v_mfma_f32_16x16x32_bf16 v[32:35], v[180:183], v[196:199], v[32:35]
	v_mfma_f32_16x16x32_bf16 v[20:23], v[172:175], v[212:215], v[20:23]
	v_mfma_f32_16x16x32_bf16 v[16:19], v[180:183], v[212:215], v[16:19]
	v_mfma_f32_16x16x32_bf16 v[4:7], v[172:175], v[220:223], v[4:7]
	v_mfma_f32_16x16x32_bf16 v[0:3], v[180:183], v[220:223], v[0:3]
	s_setprio 0
	s_barrier
	s_add_i32 s63, s63, 2
	s_add_u32 s61, s61, 0x100
	s_addc_u32 s62, s62, 0
	s_add_u32 s36, s36, 0x100
	s_addc_u32 s37, s37, 0
	s_cmp_gt_u32 s63, 13
	s_cbranch_scc0 .LBB0_2461
	s_and_b64 vcc, exec, s[14:15]
	s_cbranch_vccz .LBB0_2464
	s_barrier

; #define PG8_STAGE(bufoff, gbase, voff) do { _Pragma("unroll") for (int _i = 0; _i < 2; ++_i) \
;         __builtin_amdgcn_global_load_lds((const unsigned*)((const char*)(gbase) + (voff)[_i]), (PG8_LAS unsigned*)(lds + (bufoff) + ldsw + _i * 8192), 16, 0, 0); } while (0)
; #define PG8_LDA(dst, b, h) do { _Pragma("unroll") for (int m = 0; m < 4; ++m) _Pragma("unroll") for (int k = 0; k < 2; ++k) dst[m][k] = *(const PG8_LAS bf16x8*)(lds + PG8_SA(b, h) + aoff + m * 2048 + k * 1024); } while (0)
; #define PG8_LDB(dst, b, h) do { _Pragma("unroll") for (int n = 0; n < 2; ++n) _Pragma("unroll") for (int k = 0; k < 2; ++k) dst[n][k] = *(const PG8_LAS bf16x8*)(lds + PG8_SB(b, h) + boff + n * 2048 + k * 1024); } while (0)
; #define PG8_WAIT_V(n) asm volatile("s_waitcnt vmcnt(" #n ")" ::: "memory")
; #define PG8_WAIT_L(n) asm volatile("s_waitcnt lgkmcnt(" #n ")" ::: "memory")
; #define PG8_BAR __builtin_amdgcn_s_barrier()
; #define PG8_SCHED __builtin_amdgcn_sched_barrier(0)
; #define PG8_MMA2(ai) PG8_MMA(ai, 0, At, B0)
; #define PG8_MMA2(ai) PG8_MMA(ai, 1, At, B1)
; #define PG8_MMA2(ai) do { PG8_MMA(ai, 0, At, B0); PG8_MMA(ai, 1, At, B1); } while (0)
;     ...
;             PG8_LDB(B0, 0, 0); PG8_LDB(B1, 0, 1); PG8_SCHED; PG8_LDA(At, 0, 0); PG8_STAGE(PG8_SA(1, 1), a1 + hstep, voffA);
;             PG8_WAIT_V(8); PG8_WAIT_L(0); PG8_BAR; PG8_MMA2(0); PG8_BAR; PG8_SCHED;
;             PG8_LDA(At, 0, 1); PG8_STAGE(PG8_SB(0, 0), b2, voffB); PG8_STAGE(PG8_SB(0, 1), b2 + hstep, voffB); PG8_STAGE(PG8_SA(0, 0), a2, voffA);
;             PG8_WAIT_V(8); PG8_WAIT_L(0); PG8_BAR; PG8_MMA2(1); PG8_BAR; PG8_SCHED;
.LBB0_2541:
	s_cmp_eq_u32 s61, -2
	s_cbranch_scc1 .Ldf_skipA_11
	s_mov_b32 m0, s49
	s_nop 0
	global_load_lds_dwordx4 v[156:157], off
.Ldf_skipA_11:
	ds_read_b128 v[140:143], v161
	ds_read_b128 v[144:147], v161 offset:1024
	ds_read_b128 v[148:151], v161 offset:2048
	ds_read_b128 v[152:155], v161 offset:3072
	ds_read_b128 v[164:167], v162
	ds_read_b128 v[168:171], v162 offset:1024
	ds_read_b128 v[172:175], v162 offset:2048
	ds_read_b128 v[176:179], v162 offset:3072
	s_add_u32 s20, s18, 0x100
	s_addc_u32 s21, s19, 0
	s_cmp_eq_u32 s61, 40
	s_cselect_b32 s27, s7, s21
	s_cselect_b32 s26, s6, s20
	s_cselect_b32 s23, s17, s60
	s_cselect_b32 s22, s16, s59
	v_lshl_add_u64 v[156:157], s[18:19], 0, v[134:135]
	s_add_i32 m0, s39, 0xc000
	ds_read_b128 v[180:183], v163
	ds_read_b128 v[184:187], v163 offset:1024
	ds_read_b128 v[188:191], v163 offset:2048
	ds_read_b128 v[192:195], v163 offset:3072
	ds_read_b128 v[196:199], v163 offset:4096
	ds_read_b128 v[208:211], v163 offset:5120
	ds_read_b128 v[212:215], v163 offset:6144
	ds_read_b128 v[216:219], v163 offset:7168
	global_load_lds_dwordx4 v[156:157], off
	v_lshl_add_u64 v[156:157], s[18:19], 0, v[132:133]
	s_add_i32 m0, s39, 0xe000
	s_nop 0
	global_load_lds_dwordx4 v[156:157], off
	s_waitcnt vmcnt(8)
	s_waitcnt lgkmcnt(0)
	s_barrier
	s_setprio 1
	s_waitcnt lgkmcnt(0)
	v_mfma_f32_16x16x32_bf16 v[124:127], v[140:143], v[180:183], v[124:127]
	v_mfma_f32_16x16x32_bf16 v[120:123], v[148:151], v[180:183], v[120:123]
	v_mfma_f32_16x16x32_bf16 v[108:111], v[140:143], v[188:191], v[108:111]
	v_mfma_f32_16x16x32_bf16 v[104:107], v[148:151], v[188:191], v[104:107]
	v_mfma_f32_16x16x32_bf16 v[92:95], v[140:143], v[196:199], v[92:95]
	v_mfma_f32_16x16x32_bf16 v[88:91], v[148:151], v[196:199], v[88:91]
	v_mfma_f32_16x16x32_bf16 v[76:79], v[140:143], v[212:215], v[76:79]
	v_mfma_f32_16x16x32_bf16 v[72:75], v[148:151], v[212:215], v[72:75]
	v_mfma_f32_16x16x32_bf16 v[124:127], v[144:147], v[184:187], v[124:127]
	v_mfma_f32_16x16x32_bf16 v[120:123], v[152:155], v[184:187], v[120:123]
	v_mfma_f32_16x16x32_bf16 v[108:111], v[144:147], v[192:195], v[108:111]
	v_mfma_f32_16x16x32_bf16 v[104:107], v[152:155], v[192:195], v[104:107]
	v_mfma_f32_16x16x32_bf16 v[92:95], v[144:147], v[208:211], v[92:95]
	v_mfma_f32_16x16x32_bf16 v[88:91], v[152:155], v[208:211], v[88:91]
	v_mfma_f32_16x16x32_bf16 v[76:79], v[144:147], v[216:219], v[76:79]
	v_mfma_f32_16x16x32_bf16 v[72:75], v[152:155], v[216:219], v[72:75]
	s_setprio 0
	s_setprio 1
	v_mfma_f32_16x16x32_bf16 v[116:119], v[164:167], v[180:183], v[116:119]
	v_mfma_f32_16x16x32_bf16 v[112:115], v[172:175], v[180:183], v[112:115]
	v_mfma_f32_16x16x32_bf16 v[100:103], v[164:167], v[188:191], v[100:103]
	v_mfma_f32_16x16x32_bf16 v[96:99], v[172:175], v[188:191], v[96:99]
	v_mfma_f32_16x16x32_bf16 v[84:87], v[164:167], v[196:199], v[84:87]
	v_mfma_f32_16x16x32_bf16 v[80:83], v[172:175], v[196:199], v[80:83]
	v_mfma_f32_16x16x32_bf16 v[68:71], v[164:167], v[212:215], v[68:71]
	v_mfma_f32_16x16x32_bf16 v[64:67], v[172:175], v[212:215], v[64:67]
	v_mfma_f32_16x16x32_bf16 v[116:119], v[168:171], v[184:187], v[116:119]
	v_mfma_f32_16x16x32_bf16 v[112:115], v[176:179], v[184:187], v[112:115]
	v_mfma_f32_16x16x32_bf16 v[100:103], v[168:171], v[192:195], v[100:103]
	v_mfma_f32_16x16x32_bf16 v[96:99], v[176:179], v[192:195], v[96:99]
	v_mfma_f32_16x16x32_bf16 v[84:87], v[168:171], v[208:211], v[84:87]
	v_mfma_f32_16x16x32_bf16 v[80:83], v[176:179], v[208:211], v[80:83]
	v_mfma_f32_16x16x32_bf16 v[68:71], v[168:171], v[216:219], v[68:71]
	v_mfma_f32_16x16x32_bf16 v[64:67], v[176:179], v[216:219], v[64:67]
	s_setprio 0
	s_barrier
	s_add_i32 s18, s3, s38
	v_lshl_add_u64 v[156:157], s[22:23], 0, v[128:129]
	s_mov_b32 m0, s18
	ds_read_b128 v[180:183], v163 offset:16384
	ds_read_b128 v[184:187], v163 offset:17408
	ds_read_b128 v[188:191], v163 offset:18432
	ds_read_b128 v[192:195], v163 offset:19456
	ds_read_b128 v[196:199], v163 offset:20480
	ds_read_b128 v[208:211], v163 offset:21504
	ds_read_b128 v[212:215], v163 offset:22528
	ds_read_b128 v[216:219], v163 offset:23552
	global_load_lds_dwordx4 v[156:157], off
	s_add_i32 m0, s18, 0x2000
	s_add_u32 s18, s22, 0xb0000
	v_lshl_add_u64 v[200:201], s[22:23], 0, v[130:131]
	s_addc_u32 s19, s23, 0
	s_add_i32 s62, s53, s38
	global_load_lds_dwordx4 v[200:201], off
	v_lshl_add_u64 v[220:221], s[18:19], 0, v[128:129]
	s_mov_b32 m0, s62
	v_lshl_add_u64 v[222:223], s[26:27], 0, v[130:131]
	global_load_lds_dwordx4 v[220:221], off
	v_lshl_add_u64 v[220:221], s[18:19], 0, v[130:131]
	s_add_i32 m0, s62, 0x2000
	s_nop 0
	global_load_lds_dwordx4 v[220:221], off
	v_lshl_add_u64 v[220:221], s[26:27], 0, v[128:129]
	s_mov_b32 m0, s39
	s_nop 0
	global_load_lds_dwordx4 v[220:221], off
	s_nop 0
	s_waitcnt vmcnt(7)
	s_waitcnt lgkmcnt(0)
	s_barrier
; #define PG8_STAGE(bufoff, gbase, voff) do { _Pragma("unroll") for (int _i = 0; _i < 2; ++_i) \
;         __builtin_amdgcn_global_load_lds((const unsigned*)((const char*)(gbase) + (voff)[_i]), (PG8_LAS unsigned*)(lds + (bufoff) + ldsw + _i * 8192), 16, 0, 0); } while (0)
; #define PG8_LDA(dst, b, h) do { _Pragma("unroll") for (int m = 0; m < 4; ++m) _Pragma("unroll") for (int k = 0; k < 2; ++k) dst[m][k] = *(const PG8_LAS bf16x8*)(lds + PG8_SA(b, h) + aoff + m * 2048 + k * 1024); } while (0)
; #define PG8_LDB(dst, b, h) do { _Pragma("unroll") for (int n = 0; n < 2; ++n) _Pragma("unroll") for (int k = 0; k < 2; ++k) dst[n][k] = *(const PG8_LAS bf16x8*)(lds + PG8_SB(b, h) + boff + n * 2048 + k * 1024); } while (0)
; #define PG8_WAIT_V(n) asm volatile("s_waitcnt vmcnt(" #n ")" ::: "memory")
; #define PG8_WAIT_L(n) asm volatile("s_waitcnt lgkmcnt(" #n ")" ::: "memory")
; #define PG8_BAR __builtin_amdgcn_s_barrier()
; #define PG8_SCHED __builtin_amdgcn_sched_barrier(0)
; #define PG8_MMA2(ai) PG8_MMA(ai, 0, At, B0)
; #define PG8_MMA2(ai) PG8_MMA(ai, 1, At, B1)
; #define PG8_MMA2(ai) do { PG8_MMA(ai, 0, At, B0); PG8_MMA(ai, 1, At, B1); } while (0)
;     ...
;             PG8_WAIT_V(8); PG8_WAIT_L(0); PG8_BAR; PG8_MMA2(1); PG8_BAR; PG8_SCHED;
;             PG8_LDB(B0, 1, 0); PG8_LDB(B1, 1, 1); PG8_SCHED; PG8_LDA(At, 1, 0); PG8_STAGE(PG8_SA(0, 1), a2 + hstep, voffA);
;             PG8_WAIT_V(8); PG8_WAIT_L(0); PG8_BAR; PG8_MMA2(0); PG8_BAR; PG8_SCHED;
	s_setprio 1
	s_waitcnt lgkmcnt(0)
	v_mfma_f32_16x16x32_bf16 v[60:63], v[140:143], v[180:183], v[60:63]
	v_mfma_f32_16x16x32_bf16 v[56:59], v[148:151], v[180:183], v[56:59]
	v_mfma_f32_16x16x32_bf16 v[44:47], v[140:143], v[188:191], v[44:47]
	v_mfma_f32_16x16x32_bf16 v[40:43], v[148:151], v[188:191], v[40:43]
	v_mfma_f32_16x16x32_bf16 v[28:31], v[140:143], v[196:199], v[28:31]
	v_mfma_f32_16x16x32_bf16 v[24:27], v[148:151], v[196:199], v[24:27]
	v_mfma_f32_16x16x32_bf16 v[12:15], v[140:143], v[212:215], v[12:15]
	v_mfma_f32_16x16x32_bf16 v[8:11], v[148:151], v[212:215], v[8:11]
	v_mfma_f32_16x16x32_bf16 v[60:63], v[144:147], v[184:187], v[60:63]
	v_mfma_f32_16x16x32_bf16 v[56:59], v[152:155], v[184:187], v[56:59]
	v_mfma_f32_16x16x32_bf16 v[44:47], v[144:147], v[192:195], v[44:47]
	v_mfma_f32_16x16x32_bf16 v[40:43], v[152:155], v[192:195], v[40:43]
	v_mfma_f32_16x16x32_bf16 v[28:31], v[144:147], v[208:211], v[28:31]
	v_mfma_f32_16x16x32_bf16 v[24:27], v[152:155], v[208:211], v[24:27]
	v_mfma_f32_16x16x32_bf16 v[12:15], v[144:147], v[216:219], v[12:15]
	v_mfma_f32_16x16x32_bf16 v[8:11], v[152:155], v[216:219], v[8:11]
	s_setprio 0
	s_setprio 1
	v_mfma_f32_16x16x32_bf16 v[52:55], v[164:167], v[180:183], v[52:55]
	v_mfma_f32_16x16x32_bf16 v[48:51], v[172:175], v[180:183], v[48:51]
	v_mfma_f32_16x16x32_bf16 v[36:39], v[164:167], v[188:191], v[36:39]
	v_mfma_f32_16x16x32_bf16 v[32:35], v[172:175], v[188:191], v[32:35]
	v_mfma_f32_16x16x32_bf16 v[20:23], v[164:167], v[196:199], v[20:23]
	v_mfma_f32_16x16x32_bf16 v[16:19], v[172:175], v[196:199], v[16:19]
	v_mfma_f32_16x16x32_bf16 v[4:7], v[164:167], v[212:215], v[4:7]
	v_mfma_f32_16x16x32_bf16 v[0:3], v[172:175], v[212:215], v[0:3]
	v_mfma_f32_16x16x32_bf16 v[52:55], v[168:171], v[184:187], v[52:55]
	v_mfma_f32_16x16x32_bf16 v[48:51], v[176:179], v[184:187], v[48:51]
	v_mfma_f32_16x16x32_bf16 v[36:39], v[168:171], v[192:195], v[36:39]
	v_mfma_f32_16x16x32_bf16 v[32:35], v[176:179], v[192:195], v[32:35]
	v_mfma_f32_16x16x32_bf16 v[20:23], v[168:171], v[208:211], v[20:23]
	v_mfma_f32_16x16x32_bf16 v[16:19], v[176:179], v[208:211], v[16:19]
	v_mfma_f32_16x16x32_bf16 v[4:7], v[168:171], v[216:219], v[4:7]
	v_mfma_f32_16x16x32_bf16 v[0:3], v[176:179], v[216:219], v[0:3]
	s_setprio 0
	s_barrier
	s_add_i32 s62, 0, 0x18000
	s_add_i32 s63, 0, 0x1c000
	v_add_u32_e32 v152, s62, v159
	v_add_u32_e32 v176, s63, v159
	ds_read_b128 v[140:143], v152
	ds_read_b128 v[144:147], v152 offset:1024
	ds_read_b128 v[148:151], v152 offset:2048
	ds_read_b128 v[152:155], v152 offset:3072
	ds_read_b128 v[164:167], v176
	ds_read_b128 v[168:171], v176 offset:1024
	ds_read_b128 v[172:175], v176 offset:2048
	ds_read_b128 v[176:179], v176 offset:3072
	s_add_u32 s18, s26, 0xb0000
	s_addc_u32 s19, s27, 0
	s_mov_b32 m0, s40
	s_nop 0
	global_load_lds_dwordx4 v[222:223], off
	s_mov_b32 m0, s41
	v_lshl_add_u64 v[224:225], s[18:19], 0, v[128:129]
	ds_read_b128 v[180:183], v163 offset:32768
	ds_read_b128 v[184:187], v163 offset:33792
	ds_read_b128 v[188:191], v163 offset:34816
	ds_read_b128 v[192:195], v163 offset:35840
	ds_read_b128 v[196:199], v163 offset:36864
	ds_read_b128 v[208:211], v163 offset:37888
	ds_read_b128 v[212:215], v163 offset:38912
	ds_read_b128 v[216:219], v163 offset:39936
	global_load_lds_dwordx4 v[224:225], off
	v_lshl_add_u64 v[224:225], s[18:19], 0, v[130:131]
	s_mov_b32 m0, s42
	s_nop 0
	global_load_lds_dwordx4 v[224:225], off
	s_waitcnt vmcnt(8)
	s_waitcnt lgkmcnt(0)
	s_barrier
	s_setprio 1
	s_waitcnt lgkmcnt(0)
	v_mfma_f32_16x16x32_bf16 v[124:127], v[140:143], v[180:183], v[124:127]
	v_mfma_f32_16x16x32_bf16 v[120:123], v[148:151], v[180:183], v[120:123]
	v_mfma_f32_16x16x32_bf16 v[108:111], v[140:143], v[188:191], v[108:111]
	v_mfma_f32_16x16x32_bf16 v[104:107], v[148:151], v[188:191], v[104:107]
	v_mfma_f32_16x16x32_bf16 v[92:95], v[140:143], v[196:199], v[92:95]
	v_mfma_f32_16x16x32_bf16 v[88:91], v[148:151], v[196:199], v[88:91]
	v_mfma_f32_16x16x32_bf16 v[76:79], v[140:143], v[212:215], v[76:79]
	v_mfma_f32_16x16x32_bf16 v[72:75], v[148:151], v[212:215], v[72:75]
	v_mfma_f32_16x16x32_bf16 v[124:127], v[144:147], v[184:187], v[124:127]
	v_mfma_f32_16x16x32_bf16 v[120:123], v[152:155], v[184:187], v[120:123]
	v_mfma_f32_16x16x32_bf16 v[108:111], v[144:147], v[192:195], v[108:111]
	v_mfma_f32_16x16x32_bf16 v[104:107], v[152:155], v[192:195], v[104:107]
	v_mfma_f32_16x16x32_bf16 v[92:95], v[144:147], v[208:211], v[92:95]
	v_mfma_f32_16x16x32_bf16 v[88:91], v[152:155], v[208:211], v[88:91]
	v_mfma_f32_16x16x32_bf16 v[76:79], v[144:147], v[216:219], v[76:79]
	v_mfma_f32_16x16x32_bf16 v[72:75], v[152:155], v[216:219], v[72:75]
	s_setprio 0
	s_setprio 1
	v_mfma_f32_16x16x32_bf16 v[116:119], v[164:167], v[180:183], v[116:119]
	v_mfma_f32_16x16x32_bf16 v[112:115], v[172:175], v[180:183], v[112:115]
	v_mfma_f32_16x16x32_bf16 v[100:103], v[164:167], v[188:191], v[100:103]
	v_mfma_f32_16x16x32_bf16 v[96:99], v[172:175], v[188:191], v[96:99]
	v_mfma_f32_16x16x32_bf16 v[84:87], v[164:167], v[196:199], v[84:87]
	v_mfma_f32_16x16x32_bf16 v[80:83], v[172:175], v[196:199], v[80:83]
	v_mfma_f32_16x16x32_bf16 v[68:71], v[164:167], v[212:215], v[68:71]
	v_mfma_f32_16x16x32_bf16 v[64:67], v[172:175], v[212:215], v[64:67]
	v_mfma_f32_16x16x32_bf16 v[116:119], v[168:171], v[184:187], v[116:119]
	v_mfma_f32_16x16x32_bf16 v[112:115], v[176:179], v[184:187], v[112:115]
	v_mfma_f32_16x16x32_bf16 v[100:103], v[168:171], v[192:195], v[100:103]
	v_mfma_f32_16x16x32_bf16 v[96:99], v[176:179], v[192:195], v[96:99]
	v_mfma_f32_16x16x32_bf16 v[84:87], v[168:171], v[208:211], v[84:87]
	v_mfma_f32_16x16x32_bf16 v[80:83], v[176:179], v[208:211], v[80:83]
	v_mfma_f32_16x16x32_bf16 v[68:71], v[168:171], v[216:219], v[68:71]
	v_mfma_f32_16x16x32_bf16 v[64:67], v[176:179], v[216:219], v[64:67]
	s_setprio 0
	s_barrier
; #define PG8_STAGE(bufoff, gbase, voff) do { _Pragma("unroll") for (int _i = 0; _i < 2; ++_i) \
;         __builtin_amdgcn_global_load_lds((const unsigned*)((const char*)(gbase) + (voff)[_i]), (PG8_LAS unsigned*)(lds + (bufoff) + ldsw + _i * 8192), 16, 0, 0); } while (0)
; #define PG8_LDA(dst, b, h) do { _Pragma("unroll") for (int m = 0; m < 4; ++m) _Pragma("unroll") for (int k = 0; k < 2; ++k) dst[m][k] = *(const PG8_LAS bf16x8*)(lds + PG8_SA(b, h) + aoff + m * 2048 + k * 1024); } while (0)
; #define PG8_WAIT_V(n) asm volatile("s_waitcnt vmcnt(" #n ")" ::: "memory")
; #define PG8_WAIT_L(n) asm volatile("s_waitcnt lgkmcnt(" #n ")" ::: "memory")
; #define PG8_BAR __builtin_amdgcn_s_barrier()
; #define PG8_SCHED __builtin_amdgcn_sched_barrier(0)
; #define PG8_MMA2(ai) PG8_MMA(ai, 0, At, B0)
; #define PG8_MMA2(ai) PG8_MMA(ai, 1, At, B1)
; #define PG8_MMA2(ai) do { PG8_MMA(ai, 0, At, B0); PG8_MMA(ai, 1, At, B1); } while (0)
;     ...
;             PG8_LDA(At, 1, 1); PG8_STAGE(PG8_SB(1, 0), b3, voffB); PG8_STAGE(PG8_SB(1, 1), b3 + hstep, voffB); PG8_STAGE(PG8_SA(1, 0), a3, voffA);
;             PG8_WAIT_V(8); PG8_WAIT_L(0); PG8_BAR; PG8_MMA2(1); PG8_BAR; PG8_SCHED;
	s_add_i32 s18, s62, s38
	v_lshl_add_u64 v[156:157], v[156:157], 0, s[12:13]
	s_mov_b32 m0, s18
	ds_read_b128 v[180:183], v163 offset:49152
	ds_read_b128 v[184:187], v163 offset:50176
	ds_read_b128 v[188:191], v163 offset:51200
	ds_read_b128 v[192:195], v163 offset:52224
	ds_read_b128 v[196:199], v163 offset:53248
	ds_read_b128 v[208:211], v163 offset:54272
	ds_read_b128 v[212:215], v163 offset:55296
	ds_read_b128 v[216:219], v163 offset:56320
	global_load_lds_dwordx4 v[156:157], off
	s_add_i32 m0, s18, 0x2000
	s_add_u32 s18, s22, 0xb0080
	v_lshl_add_u64 v[156:157], v[200:201], 0, s[12:13]
	s_addc_u32 s19, s23, 0
	s_add_i32 s22, s63, s38
	global_load_lds_dwordx4 v[156:157], off
	v_lshl_add_u64 v[156:157], s[18:19], 0, v[128:129]
	s_mov_b32 m0, s22
	s_nop 0
	global_load_lds_dwordx4 v[156:157], off
	v_lshl_add_u64 v[156:157], s[18:19], 0, v[130:131]
	s_add_i32 m0, s22, 0x2000
	s_nop 0
	global_load_lds_dwordx4 v[156:157], off
	v_lshl_add_u64 v[156:157], v[220:221], 0, s[12:13]
	s_mov_b32 m0, s48
	s_nop 0
	global_load_lds_dwordx4 v[156:157], off
	v_lshl_add_u64 v[156:157], v[222:223], 0, s[12:13]
	s_nop 0
	s_cmp_lg_u32 s61, 40
	s_cbranch_scc1 .Ldf_skipD_11
	s_mov_b32 m0, s49
	s_nop 0
	global_load_lds_dwordx4 v[156:157], off
.Ldf_skipD_11:
	s_waitcnt vmcnt(7)
	s_waitcnt lgkmcnt(0)
	s_barrier
	s_setprio 1
	s_waitcnt lgkmcnt(0)
	v_mfma_f32_16x16x32_bf16 v[60:63], v[140:143], v[180:183], v[60:63]
	v_mfma_f32_16x16x32_bf16 v[56:59], v[148:151], v[180:183], v[56:59]
	v_mfma_f32_16x16x32_bf16 v[44:47], v[140:143], v[188:191], v[44:47]
	v_mfma_f32_16x16x32_bf16 v[40:43], v[148:151], v[188:191], v[40:43]
	v_mfma_f32_16x16x32_bf16 v[28:31], v[140:143], v[196:199], v[28:31]
	v_mfma_f32_16x16x32_bf16 v[24:27], v[148:151], v[196:199], v[24:27]
	v_mfma_f32_16x16x32_bf16 v[12:15], v[140:143], v[212:215], v[12:15]
	v_mfma_f32_16x16x32_bf16 v[8:11], v[148:151], v[212:215], v[8:11]
	v_mfma_f32_16x16x32_bf16 v[60:63], v[144:147], v[184:187], v[60:63]
	v_mfma_f32_16x16x32_bf16 v[56:59], v[152:155], v[184:187], v[56:59]
	v_mfma_f32_16x16x32_bf16 v[44:47], v[144:147], v[192:195], v[44:47]
	v_mfma_f32_16x16x32_bf16 v[40:43], v[152:155], v[192:195], v[40:43]
	v_mfma_f32_16x16x32_bf16 v[28:31], v[144:147], v[208:211], v[28:31]
	v_mfma_f32_16x16x32_bf16 v[24:27], v[152:155], v[208:211], v[24:27]
	v_mfma_f32_16x16x32_bf16 v[12:15], v[144:147], v[216:219], v[12:15]
	v_mfma_f32_16x16x32_bf16 v[8:11], v[152:155], v[216:219], v[8:11]
	s_setprio 0
	s_setprio 1
	v_mfma_f32_16x16x32_bf16 v[52:55], v[164:167], v[180:183], v[52:55]
	v_mfma_f32_16x16x32_bf16 v[48:51], v[172:175], v[180:183], v[48:51]
	v_mfma_f32_16x16x32_bf16 v[36:39], v[164:167], v[188:191], v[36:39]
	v_mfma_f32_16x16x32_bf16 v[32:35], v[172:175], v[188:191], v[32:35]
	v_mfma_f32_16x16x32_bf16 v[20:23], v[164:167], v[196:199], v[20:23]
	v_mfma_f32_16x16x32_bf16 v[16:19], v[172:175], v[196:199], v[16:19]
	v_mfma_f32_16x16x32_bf16 v[4:7], v[164:167], v[212:215], v[4:7]
	v_mfma_f32_16x16x32_bf16 v[0:3], v[172:175], v[212:215], v[0:3]
	v_mfma_f32_16x16x32_bf16 v[52:55], v[168:171], v[184:187], v[52:55]
	v_mfma_f32_16x16x32_bf16 v[48:51], v[176:179], v[184:187], v[48:51]
	v_mfma_f32_16x16x32_bf16 v[36:39], v[168:171], v[192:195], v[36:39]
	v_mfma_f32_16x16x32_bf16 v[32:35], v[176:179], v[192:195], v[32:35]
	v_mfma_f32_16x16x32_bf16 v[20:23], v[168:171], v[208:211], v[20:23]
	v_mfma_f32_16x16x32_bf16 v[16:19], v[176:179], v[208:211], v[16:19]
	v_mfma_f32_16x16x32_bf16 v[4:7], v[168:171], v[216:219], v[4:7]
	v_mfma_f32_16x16x32_bf16 v[0:3], v[176:179], v[216:219], v[0:3]
	s_setprio 0
	s_barrier
	s_add_i32 s61, s61, 2
	s_add_u32 s59, s59, 0x100
	s_addc_u32 s60, s60, 0
	s_cmp_gt_u32 s61, 41
	s_mov_b64 s[18:19], s[20:21]
	s_cbranch_scc0 .LBB0_2541
	s_and_b64 vcc, exec, s[14:15]
	s_cbranch_vccz .LBB0_2544
	s_barrier
